# plus GEMM K-loops: look-ahead LDS-DMA loads of a workgroup's final K-iteration (no consumer) read one 16-byte address per instruction instead of 1 KiB (offsets masked to zero, EXEC full, vmcnt account
# speedup vs baseline: 1.0055x; 1.0038x over previous
; #define PG8_STAGE(bufoff, gbase, voff) do { _Pragma("unroll") for (int _i = 0; _i < 2; ++_i) \
;         __builtin_amdgcn_global_load_lds((const unsigned*)((const char*)(gbase) + (voff)[_i]), (PG8_LAS unsigned*)(lds + (bufoff) + ldsw + _i * 8192), 16, 0, 0); } while (0)
; #define PG8_LDA(dst, b, h) do { _Pragma("unroll") for (int m = 0; m < 4; ++m) _Pragma("unroll") for (int k = 0; k < 2; ++k) dst[m][k] = *(const PG8_LAS bf16x8*)(lds + PG8_SA(b, h) + aoff + m * 2048 + k * 1024); } while (0)
; template <class Epi, class Sched, bool ALIGN_EPI = false, bool SP2 = false>
; __device__ __forceinline__ void gemm_phase(PG8_LAS unsigned char* lds, const Gemm g, const Sched& S, const Epi& E) {
;     ...
;         const bool has_next = S.next(ui + 1, nxt);
;         const char* nA = has_next ? (const char*)g.A + (size_t)nxt.pm * tstep : cA; const char* nB = has_next ? (const char*)g.Bt + (size_t)nxt.pn * tstep : cB;
;         for (int t = 0; t < nt; t += 2) {
;             const bool last = (t == nt - 2);
;             const char* a1 = cA + (size_t)(t + 1) * kstep;
;             const char* a2 = last ? nA : cA + (size_t)(t + 2) * kstep; const char* b2 = last ? nB : cB + (size_t)(t + 2) * kstep;
;             const char* a3 = a2 + kstep; const char* b3 = b2 + kstep;
;             if (last && has_next) S.a_ready(nxt);
;             if constexpr (SP2) {
;             PG8_LDB(B0, 0, 0); PG8_LDB(B1, 0, 1); PG8_SCHED; PG8_LDA(At, 0, 0); PG8_STAGE(PG8_SA(1, 1), a1 + hstep, voffA);
;             PG8_WAIT_V(8); PG8_WAIT_L(0); PG8_BAR; PG8_MMA(0, 0, At, B0); PG8_MMA(0, 1, At, B1); PG8_BAR; PG8_SCHED;
;             PG8_LDA(At, 0, 1); PG8_STAGE(PG8_SB(0, 0), b2, voffB); PG8_STAGE(PG8_SB(0, 1), b2 + hstep, voffB); PG8_STAGE(PG8_SA(0, 0), a2, voffA);
;             PG8_WAIT_V(8); PG8_WAIT_L(0); PG8_BAR; PG8_MMA(1, 0, At, B0); PG8_MMA(1, 1, At, B1); PG8_BAR; PG8_SCHED;
;             PG8_LDB(B0, 1, 0); PG8_LDB(B1, 1, 1); PG8_SCHED; PG8_LDA(At, 1, 0); PG8_STAGE(PG8_SA(0, 1), a2 + hstep, voffA);
;             PG8_WAIT_V(8); PG8_WAIT_L(0); PG8_BAR; PG8_MMA(0, 0, At, B0); PG8_MMA(0, 1, At, B1); PG8_BAR; PG8_SCHED;
;             PG8_LDA(At, 1, 1); PG8_STAGE(PG8_SB(1, 0), b3, voffB); PG8_STAGE(PG8_SB(1, 1), b3 + hstep, voffB); PG8_STAGE(PG8_SA(1, 0), a3, voffA);
;             PG8_WAIT_V(8); PG8_WAIT_L(0); PG8_BAR; PG8_MMA(1, 0, At, B0); PG8_MMA(1, 1, At, B1); PG8_BAR; PG8_SCHED;
.LBB0_38:
	s_add_i32 s19, s18, 2
	s_add_u32 s20, s38, 0x80
	s_addc_u32 s23, s39, 0
	s_add_i32 s25, s33, 0x100
	s_cmp_eq_u32 s97, s18
	s_cselect_b32 s51, s43, s23
	s_cselect_b32 s50, s42, s20
	v_add_u32_e32 v2, s25, v142
	s_cselect_b32 s27, s61, s15
	s_cselect_b32 s26, s60, s12
	s_cselect_b64 s[98:99], s[40:41], 0
	s_cmp_lg_u64 s[98:99], 0
	s_cselect_b32 s98, 0, -1
	v_and_b32_e32 v246, s98, v134
	v_and_b32_e32 v247, s98, v135
	v_and_b32_e32 v248, s98, v0
	v_and_b32_e32 v249, s98, v1
	v_and_b32_e32 v250, s98, v136
	v_and_b32_e32 v251, s98, v137
	v_and_b32_e32 v252, s98, v132
	v_and_b32_e32 v253, s98, v133
	s_add_i32 s18, s21, 0x100
	ds_read_b128 v[144:147], v2
	ds_read_b128 v[148:151], v2 offset:1024
	ds_read_b128 v[152:155], v2 offset:2048
	ds_read_b128 v[156:159], v2 offset:3072
	v_add_u32_e32 v2, s18, v142
	ds_read_b128 v[160:163], v2
	ds_read_b128 v[164:167], v2 offset:1024
	ds_read_b128 v[168:171], v2 offset:2048
	ds_read_b128 v[172:175], v2 offset:3072
	v_lshl_add_u64 v[210:211], s[38:39], 0, v[140:141]
	s_add_i32 m0, s70, 0xc000
	ds_read_b128 v[176:179], v143
	ds_read_b128 v[180:183], v143 offset:1024
	ds_read_b128 v[194:197], v143 offset:2048
	ds_read_b128 v[198:201], v143 offset:3072
	ds_read_b128 v[202:205], v143 offset:4096
	ds_read_b128 v[206:209], v143 offset:5120
	ds_read_b128 v[220:223], v143 offset:6144
	ds_read_b128 v[224:227], v143 offset:7168
	global_load_lds_dwordx4 v[210:211], off
	v_lshl_add_u64 v[210:211], s[38:39], 0, v[138:139]
	s_add_i32 m0, s70, 0xe000
	s_nop 0
	global_load_lds_dwordx4 v[210:211], off
	s_waitcnt vmcnt(8)
	s_waitcnt lgkmcnt(0)
	s_barrier
	s_setprio 1
	s_waitcnt lgkmcnt(0)
	v_mfma_f32_16x16x32_bf16 v[128:131], v[144:147], v[176:179], v[128:131]
	v_mfma_f32_16x16x32_bf16 v[120:123], v[152:155], v[176:179], v[120:123]
	v_mfma_f32_16x16x32_bf16 v[112:115], v[144:147], v[194:197], v[112:115]
	v_mfma_f32_16x16x32_bf16 v[104:107], v[152:155], v[194:197], v[104:107]
	v_mfma_f32_16x16x32_bf16 v[96:99], v[144:147], v[202:205], v[96:99]
	v_mfma_f32_16x16x32_bf16 v[88:91], v[152:155], v[202:205], v[88:91]
	v_mfma_f32_16x16x32_bf16 v[80:83], v[144:147], v[220:223], v[80:83]
	v_mfma_f32_16x16x32_bf16 v[72:75], v[152:155], v[220:223], v[72:75]
	v_mfma_f32_16x16x32_bf16 v[128:131], v[148:151], v[180:183], v[128:131]
	v_mfma_f32_16x16x32_bf16 v[120:123], v[156:159], v[180:183], v[120:123]
	v_mfma_f32_16x16x32_bf16 v[112:115], v[148:151], v[198:201], v[112:115]
	v_mfma_f32_16x16x32_bf16 v[104:107], v[156:159], v[198:201], v[104:107]
	v_mfma_f32_16x16x32_bf16 v[96:99], v[148:151], v[206:209], v[96:99]
	v_mfma_f32_16x16x32_bf16 v[88:91], v[156:159], v[206:209], v[88:91]
	v_mfma_f32_16x16x32_bf16 v[80:83], v[148:151], v[224:227], v[80:83]
	v_mfma_f32_16x16x32_bf16 v[72:75], v[156:159], v[224:227], v[72:75]
	s_setprio 0
	s_setprio 1
	v_mfma_f32_16x16x32_bf16 v[124:127], v[160:163], v[176:179], v[124:127]
	v_mfma_f32_16x16x32_bf16 v[116:119], v[168:171], v[176:179], v[116:119]
	v_mfma_f32_16x16x32_bf16 v[108:111], v[160:163], v[194:197], v[108:111]
	v_mfma_f32_16x16x32_bf16 v[100:103], v[168:171], v[194:197], v[100:103]
	v_mfma_f32_16x16x32_bf16 v[92:95], v[160:163], v[202:205], v[92:95]
	v_mfma_f32_16x16x32_bf16 v[84:87], v[168:171], v[202:205], v[84:87]
	v_mfma_f32_16x16x32_bf16 v[76:79], v[160:163], v[220:223], v[76:79]
	v_mfma_f32_16x16x32_bf16 v[68:71], v[168:171], v[220:223], v[68:71]
	v_mfma_f32_16x16x32_bf16 v[124:127], v[164:167], v[180:183], v[124:127]
	v_mfma_f32_16x16x32_bf16 v[116:119], v[172:175], v[180:183], v[116:119]
	v_mfma_f32_16x16x32_bf16 v[108:111], v[164:167], v[198:201], v[108:111]
	v_mfma_f32_16x16x32_bf16 v[100:103], v[172:175], v[198:201], v[100:103]
	v_mfma_f32_16x16x32_bf16 v[92:95], v[164:167], v[206:209], v[92:95]
	v_mfma_f32_16x16x32_bf16 v[84:87], v[172:175], v[206:209], v[84:87]
	v_mfma_f32_16x16x32_bf16 v[76:79], v[164:167], v[224:227], v[76:79]
	v_mfma_f32_16x16x32_bf16 v[68:71], v[172:175], v[224:227], v[68:71]
	s_setprio 0
	s_barrier
	s_add_i32 s20, s25, s67
	v_lshl_add_u64 v[210:211], s[26:27], 0, v[246:247]
	s_mov_b32 m0, s20
	ds_read_b128 v[176:179], v143 offset:16384
	ds_read_b128 v[180:183], v143 offset:17408
	ds_read_b128 v[194:197], v143 offset:18432
	ds_read_b128 v[198:201], v143 offset:19456
	ds_read_b128 v[202:205], v143 offset:20480
	ds_read_b128 v[206:209], v143 offset:21504
	ds_read_b128 v[220:223], v143 offset:22528
	ds_read_b128 v[224:227], v143 offset:23552
	global_load_lds_dwordx4 v[210:211], off
	s_add_i32 m0, s20, 0x2000
	v_lshl_add_u64 v[228:229], s[26:27], 0, v[248:249]
	s_add_u32 s26, s26, s44
	s_addc_u32 s27, s27, s45
	s_add_i32 s18, s18, s67
	global_load_lds_dwordx4 v[228:229], off
	v_lshl_add_u64 v[230:231], s[26:27], 0, v[246:247]
	s_mov_b32 m0, s18
	v_lshl_add_u64 v[232:233], s[26:27], 0, v[248:249]
	global_load_lds_dwordx4 v[230:231], off
	s_add_i32 m0, s18, 0x2000
	v_lshl_add_u64 v[234:235], s[50:51], 0, v[250:251]
	global_load_lds_dwordx4 v[232:233], off
	s_mov_b32 m0, s70
	v_lshl_add_u64 v[236:237], s[50:51], 0, v[252:253]
	global_load_lds_dwordx4 v[234:235], off
	s_mov_b32 m0, s71
	s_nop 0
	global_load_lds_dwordx4 v[236:237], off
	s_waitcnt vmcnt(8)
	s_waitcnt lgkmcnt(0)
	s_barrier
; #define PG8_STAGE(bufoff, gbase, voff) do { _Pragma("unroll") for (int _i = 0; _i < 2; ++_i) \
;         __builtin_amdgcn_global_load_lds((const unsigned*)((const char*)(gbase) + (voff)[_i]), (PG8_LAS unsigned*)(lds + (bufoff) + ldsw + _i * 8192), 16, 0, 0); } while (0)
; #define PG8_LDA(dst, b, h) do { _Pragma("unroll") for (int m = 0; m < 4; ++m) _Pragma("unroll") for (int k = 0; k < 2; ++k) dst[m][k] = *(const PG8_LAS bf16x8*)(lds + PG8_SA(b, h) + aoff + m * 2048 + k * 1024); } while (0)
; #define PG8_LDB(dst, b, h) do { _Pragma("unroll") for (int n = 0; n < 2; ++n) _Pragma("unroll") for (int k = 0; k < 2; ++k) dst[n][k] = *(const PG8_LAS bf16x8*)(lds + PG8_SB(b, h) + boff + n * 2048 + k * 1024); } while (0)
; #define PG8_MMA(ai, bj, At, Bt) do { __builtin_amdgcn_s_setprio(1); _Pragma("unroll") for (int m = 0; m < 4; ++m) _Pragma("unroll") for (int n = 0; n < 2; ++n) _Pragma("unroll") for (int k = 0; k < 2; ++k) \
;         acc[ai][bj][m][n] = __builtin_amdgcn_mfma_f32_16x16x32_bf16(Bt[n][k], At[m][k], acc[ai][bj][m][n], 0, 0, 0); __builtin_amdgcn_s_setprio(0); } while (0)
; #define PG8_WAIT_V(n) asm volatile("s_waitcnt vmcnt(" #n ")" ::: "memory")
; #define PG8_WAIT_L(n) asm volatile("s_waitcnt lgkmcnt(" #n ")" ::: "memory")
; #define PG8_BAR __builtin_amdgcn_s_barrier()
; #define PG8_SCHED __builtin_amdgcn_sched_barrier(0)
; template <class Epi, class Sched, bool ALIGN_EPI = false, bool SP2 = false>
; __device__ __forceinline__ void gemm_phase(PG8_LAS unsigned char* lds, const Gemm g, const Sched& S, const Epi& E) {
;     ...
;             PG8_WAIT_V(8); PG8_WAIT_L(0); PG8_BAR; PG8_MMA(1, 0, At, B0); PG8_MMA(1, 1, At, B1); PG8_BAR; PG8_SCHED;
;             PG8_LDB(B0, 1, 0); PG8_LDB(B1, 1, 1); PG8_SCHED; PG8_LDA(At, 1, 0); PG8_STAGE(PG8_SA(0, 1), a2 + hstep, voffA);
;             PG8_WAIT_V(8); PG8_WAIT_L(0); PG8_BAR; PG8_MMA(0, 0, At, B0); PG8_MMA(0, 1, At, B1); PG8_BAR; PG8_SCHED;
;             PG8_LDA(At, 1, 1); PG8_STAGE(PG8_SB(1, 0), b3, voffB); PG8_STAGE(PG8_SB(1, 1), b3 + hstep, voffB); PG8_STAGE(PG8_SA(1, 0), a3, voffA);
;             PG8_WAIT_V(8); PG8_WAIT_L(0); PG8_BAR; PG8_MMA(1, 0, At, B0); PG8_MMA(1, 1, At, B1); PG8_BAR; PG8_SCHED;
	s_setprio 1
	s_waitcnt lgkmcnt(0)
	v_mfma_f32_16x16x32_bf16 v[64:67], v[144:147], v[176:179], v[64:67]
	v_mfma_f32_16x16x32_bf16 v[56:59], v[152:155], v[176:179], v[56:59]
	v_mfma_f32_16x16x32_bf16 v[48:51], v[144:147], v[194:197], v[48:51]
	v_mfma_f32_16x16x32_bf16 v[40:43], v[152:155], v[194:197], v[40:43]
	v_mfma_f32_16x16x32_bf16 v[32:35], v[144:147], v[202:205], v[32:35]
	v_mfma_f32_16x16x32_bf16 v[24:27], v[152:155], v[202:205], v[24:27]
	v_mfma_f32_16x16x32_bf16 v[16:19], v[144:147], v[220:223], v[16:19]
	v_mfma_f32_16x16x32_bf16 v[8:11], v[152:155], v[220:223], v[8:11]
	v_mfma_f32_16x16x32_bf16 v[64:67], v[148:151], v[180:183], v[64:67]
	v_mfma_f32_16x16x32_bf16 v[56:59], v[156:159], v[180:183], v[56:59]
	v_mfma_f32_16x16x32_bf16 v[48:51], v[148:151], v[198:201], v[48:51]
	v_mfma_f32_16x16x32_bf16 v[40:43], v[156:159], v[198:201], v[40:43]
	v_mfma_f32_16x16x32_bf16 v[32:35], v[148:151], v[206:209], v[32:35]
	v_mfma_f32_16x16x32_bf16 v[24:27], v[156:159], v[206:209], v[24:27]
	v_mfma_f32_16x16x32_bf16 v[16:19], v[148:151], v[224:227], v[16:19]
	v_mfma_f32_16x16x32_bf16 v[8:11], v[156:159], v[224:227], v[8:11]
	s_setprio 0
	s_setprio 1
	v_mfma_f32_16x16x32_bf16 v[60:63], v[160:163], v[176:179], v[60:63]
	v_mfma_f32_16x16x32_bf16 v[52:55], v[168:171], v[176:179], v[52:55]
	v_mfma_f32_16x16x32_bf16 v[44:47], v[160:163], v[194:197], v[44:47]
	v_mfma_f32_16x16x32_bf16 v[36:39], v[168:171], v[194:197], v[36:39]
	v_mfma_f32_16x16x32_bf16 v[28:31], v[160:163], v[202:205], v[28:31]
	v_mfma_f32_16x16x32_bf16 v[20:23], v[168:171], v[202:205], v[20:23]
	v_mfma_f32_16x16x32_bf16 v[12:15], v[160:163], v[220:223], v[12:15]
	v_mfma_f32_16x16x32_bf16 v[4:7], v[168:171], v[220:223], v[4:7]
	v_mfma_f32_16x16x32_bf16 v[60:63], v[164:167], v[180:183], v[60:63]
	v_mfma_f32_16x16x32_bf16 v[52:55], v[172:175], v[180:183], v[52:55]
	v_mfma_f32_16x16x32_bf16 v[44:47], v[164:167], v[198:201], v[44:47]
	v_mfma_f32_16x16x32_bf16 v[36:39], v[172:175], v[198:201], v[36:39]
	v_mfma_f32_16x16x32_bf16 v[28:31], v[164:167], v[206:209], v[28:31]
	v_mfma_f32_16x16x32_bf16 v[20:23], v[172:175], v[206:209], v[20:23]
	v_mfma_f32_16x16x32_bf16 v[12:15], v[164:167], v[224:227], v[12:15]
	v_mfma_f32_16x16x32_bf16 v[4:7], v[172:175], v[224:227], v[4:7]
	s_setprio 0
	s_barrier
	s_add_i32 s18, s82, 0x100
	v_add_u32_e32 v2, s18, v142
	s_add_i32 s20, s78, 0x100
	ds_read_b128 v[144:147], v2
	ds_read_b128 v[148:151], v2 offset:1024
	ds_read_b128 v[152:155], v2 offset:2048
	ds_read_b128 v[156:159], v2 offset:3072
	v_add_u32_e32 v2, s20, v142
	ds_read_b128 v[160:163], v2
	ds_read_b128 v[164:167], v2 offset:1024
	ds_read_b128 v[168:171], v2 offset:2048
	ds_read_b128 v[172:175], v2 offset:3072
	s_add_u32 s26, s50, s44
	s_addc_u32 s27, s51, s45
	s_mov_b32 m0, s80
	v_lshl_add_u64 v[238:239], s[26:27], 0, v[250:251]
	ds_read_b128 v[176:179], v143 offset:32768
	ds_read_b128 v[180:183], v143 offset:33792
	ds_read_b128 v[194:197], v143 offset:34816
	ds_read_b128 v[198:201], v143 offset:35840
	ds_read_b128 v[202:205], v143 offset:36864
	ds_read_b128 v[206:209], v143 offset:37888
	ds_read_b128 v[220:223], v143 offset:38912
	ds_read_b128 v[224:227], v143 offset:39936
	global_load_lds_dwordx4 v[238:239], off
	v_lshl_add_u64 v[238:239], s[26:27], 0, v[252:253]
	s_mov_b32 m0, s81
	s_nop 0
	global_load_lds_dwordx4 v[238:239], off
	s_waitcnt vmcnt(8)
	s_waitcnt lgkmcnt(0)
	s_barrier
	s_setprio 1
	s_waitcnt lgkmcnt(0)
	v_mfma_f32_16x16x32_bf16 v[128:131], v[144:147], v[176:179], v[128:131]
	v_mfma_f32_16x16x32_bf16 v[120:123], v[152:155], v[176:179], v[120:123]
	v_mfma_f32_16x16x32_bf16 v[112:115], v[144:147], v[194:197], v[112:115]
	v_mfma_f32_16x16x32_bf16 v[104:107], v[152:155], v[194:197], v[104:107]
	v_mfma_f32_16x16x32_bf16 v[96:99], v[144:147], v[202:205], v[96:99]
	v_mfma_f32_16x16x32_bf16 v[88:91], v[152:155], v[202:205], v[88:91]
	v_mfma_f32_16x16x32_bf16 v[80:83], v[144:147], v[220:223], v[80:83]
	v_mfma_f32_16x16x32_bf16 v[72:75], v[152:155], v[220:223], v[72:75]
	v_mfma_f32_16x16x32_bf16 v[128:131], v[148:151], v[180:183], v[128:131]
	v_mfma_f32_16x16x32_bf16 v[120:123], v[156:159], v[180:183], v[120:123]
	v_mfma_f32_16x16x32_bf16 v[112:115], v[148:151], v[198:201], v[112:115]
	v_mfma_f32_16x16x32_bf16 v[104:107], v[156:159], v[198:201], v[104:107]
	v_mfma_f32_16x16x32_bf16 v[96:99], v[148:151], v[206:209], v[96:99]
	v_mfma_f32_16x16x32_bf16 v[88:91], v[156:159], v[206:209], v[88:91]
	v_mfma_f32_16x16x32_bf16 v[80:83], v[148:151], v[224:227], v[80:83]
	v_mfma_f32_16x16x32_bf16 v[72:75], v[156:159], v[224:227], v[72:75]
	s_setprio 0
	s_setprio 1
	v_mfma_f32_16x16x32_bf16 v[124:127], v[160:163], v[176:179], v[124:127]
	v_mfma_f32_16x16x32_bf16 v[116:119], v[168:171], v[176:179], v[116:119]
	v_mfma_f32_16x16x32_bf16 v[108:111], v[160:163], v[194:197], v[108:111]
	v_mfma_f32_16x16x32_bf16 v[100:103], v[168:171], v[194:197], v[100:103]
	v_mfma_f32_16x16x32_bf16 v[92:95], v[160:163], v[202:205], v[92:95]
	v_mfma_f32_16x16x32_bf16 v[84:87], v[168:171], v[202:205], v[84:87]
	v_mfma_f32_16x16x32_bf16 v[76:79], v[160:163], v[220:223], v[76:79]
	v_mfma_f32_16x16x32_bf16 v[68:71], v[168:171], v[220:223], v[68:71]
	v_mfma_f32_16x16x32_bf16 v[124:127], v[164:167], v[180:183], v[124:127]
	v_mfma_f32_16x16x32_bf16 v[116:119], v[172:175], v[180:183], v[116:119]
	v_mfma_f32_16x16x32_bf16 v[108:111], v[164:167], v[198:201], v[108:111]
	v_mfma_f32_16x16x32_bf16 v[100:103], v[172:175], v[198:201], v[100:103]
	v_mfma_f32_16x16x32_bf16 v[92:95], v[164:167], v[206:209], v[92:95]
	v_mfma_f32_16x16x32_bf16 v[84:87], v[172:175], v[206:209], v[84:87]
	v_mfma_f32_16x16x32_bf16 v[76:79], v[164:167], v[224:227], v[76:79]
	v_mfma_f32_16x16x32_bf16 v[68:71], v[172:175], v[224:227], v[68:71]
	s_setprio 0
	s_barrier
; #define PG8_STAGE(bufoff, gbase, voff) do { _Pragma("unroll") for (int _i = 0; _i < 2; ++_i) \
;         __builtin_amdgcn_global_load_lds((const unsigned*)((const char*)(gbase) + (voff)[_i]), (PG8_LAS unsigned*)(lds + (bufoff) + ldsw + _i * 8192), 16, 0, 0); } while (0)
; #define PG8_LDA(dst, b, h) do { _Pragma("unroll") for (int m = 0; m < 4; ++m) _Pragma("unroll") for (int k = 0; k < 2; ++k) dst[m][k] = *(const PG8_LAS bf16x8*)(lds + PG8_SA(b, h) + aoff + m * 2048 + k * 1024); } while (0)
; #define PG8_MMA(ai, bj, At, Bt) do { __builtin_amdgcn_s_setprio(1); _Pragma("unroll") for (int m = 0; m < 4; ++m) _Pragma("unroll") for (int n = 0; n < 2; ++n) _Pragma("unroll") for (int k = 0; k < 2; ++k) \
;         acc[ai][bj][m][n] = __builtin_amdgcn_mfma_f32_16x16x32_bf16(Bt[n][k], At[m][k], acc[ai][bj][m][n], 0, 0, 0); __builtin_amdgcn_s_setprio(0); } while (0)
; #define PG8_WAIT_V(n) asm volatile("s_waitcnt vmcnt(" #n ")" ::: "memory")
; #define PG8_WAIT_L(n) asm volatile("s_waitcnt lgkmcnt(" #n ")" ::: "memory")
; #define PG8_BAR __builtin_amdgcn_s_barrier()
; #define PG8_SCHED __builtin_amdgcn_sched_barrier(0)
; template <class Epi, class Sched, bool ALIGN_EPI = false, bool SP2 = false>
; __device__ __forceinline__ void gemm_phase(PG8_LAS unsigned char* lds, const Gemm g, const Sched& S, const Epi& E) {
;     ...
;             PG8_LDA(At, 1, 1); PG8_STAGE(PG8_SB(1, 0), b3, voffB); PG8_STAGE(PG8_SB(1, 1), b3 + hstep, voffB); PG8_STAGE(PG8_SA(1, 0), a3, voffA);
;             PG8_WAIT_V(8); PG8_WAIT_L(0); PG8_BAR; PG8_MMA(1, 0, At, B0); PG8_MMA(1, 1, At, B1); PG8_BAR; PG8_SCHED;
	s_add_i32 s18, s18, s67
	v_lshl_add_u64 v[210:211], v[210:211], 0, s[8:9]
	s_mov_b32 m0, s18
	ds_read_b128 v[176:179], v143 offset:49152
	ds_read_b128 v[180:183], v143 offset:50176
	ds_read_b128 v[194:197], v143 offset:51200
	ds_read_b128 v[198:201], v143 offset:52224
	ds_read_b128 v[202:205], v143 offset:53248
	ds_read_b128 v[206:209], v143 offset:54272
	ds_read_b128 v[220:223], v143 offset:55296
	ds_read_b128 v[224:227], v143 offset:56320
	global_load_lds_dwordx4 v[210:211], off
	v_lshl_add_u64 v[210:211], v[228:229], 0, s[8:9]
	s_add_i32 m0, s18, 0x2000
	s_add_i32 s18, s20, s67
	global_load_lds_dwordx4 v[210:211], off
	v_lshl_add_u64 v[210:211], v[230:231], 0, s[8:9]
	s_mov_b32 m0, s18
	s_nop 0
	global_load_lds_dwordx4 v[210:211], off
	v_lshl_add_u64 v[210:211], v[232:233], 0, s[8:9]
	s_add_i32 m0, s18, 0x2000
	s_nop 0
	global_load_lds_dwordx4 v[210:211], off
	v_lshl_add_u64 v[210:211], v[234:235], 0, s[8:9]
	s_mov_b32 m0, s87
	s_nop 0
	global_load_lds_dwordx4 v[210:211], off
	v_lshl_add_u64 v[210:211], v[236:237], 0, s[8:9]
	s_mov_b32 m0, s92
	s_nop 0
	global_load_lds_dwordx4 v[210:211], off
	s_waitcnt vmcnt(8)
	s_waitcnt lgkmcnt(0)
	s_barrier
	s_setprio 1
	s_waitcnt lgkmcnt(0)
	v_mfma_f32_16x16x32_bf16 v[64:67], v[144:147], v[176:179], v[64:67]
	v_mfma_f32_16x16x32_bf16 v[56:59], v[152:155], v[176:179], v[56:59]
	v_mfma_f32_16x16x32_bf16 v[48:51], v[144:147], v[194:197], v[48:51]
	v_mfma_f32_16x16x32_bf16 v[40:43], v[152:155], v[194:197], v[40:43]
	v_mfma_f32_16x16x32_bf16 v[32:35], v[144:147], v[202:205], v[32:35]
	v_mfma_f32_16x16x32_bf16 v[24:27], v[152:155], v[202:205], v[24:27]
	v_mfma_f32_16x16x32_bf16 v[16:19], v[144:147], v[220:223], v[16:19]
	v_mfma_f32_16x16x32_bf16 v[8:11], v[152:155], v[220:223], v[8:11]
	v_mfma_f32_16x16x32_bf16 v[64:67], v[148:151], v[180:183], v[64:67]
	v_mfma_f32_16x16x32_bf16 v[56:59], v[156:159], v[180:183], v[56:59]
	v_mfma_f32_16x16x32_bf16 v[48:51], v[148:151], v[198:201], v[48:51]
	v_mfma_f32_16x16x32_bf16 v[40:43], v[156:159], v[198:201], v[40:43]
	v_mfma_f32_16x16x32_bf16 v[32:35], v[148:151], v[206:209], v[32:35]
	v_mfma_f32_16x16x32_bf16 v[24:27], v[156:159], v[206:209], v[24:27]
	v_mfma_f32_16x16x32_bf16 v[16:19], v[148:151], v[224:227], v[16:19]
	v_mfma_f32_16x16x32_bf16 v[8:11], v[156:159], v[224:227], v[8:11]
	s_setprio 0
	s_setprio 1
	v_mfma_f32_16x16x32_bf16 v[60:63], v[160:163], v[176:179], v[60:63]
	v_mfma_f32_16x16x32_bf16 v[52:55], v[168:171], v[176:179], v[52:55]
	v_mfma_f32_16x16x32_bf16 v[44:47], v[160:163], v[194:197], v[44:47]
	v_mfma_f32_16x16x32_bf16 v[36:39], v[168:171], v[194:197], v[36:39]
	v_mfma_f32_16x16x32_bf16 v[28:31], v[160:163], v[202:205], v[28:31]
	v_mfma_f32_16x16x32_bf16 v[20:23], v[168:171], v[202:205], v[20:23]
	v_mfma_f32_16x16x32_bf16 v[12:15], v[160:163], v[220:223], v[12:15]
	v_mfma_f32_16x16x32_bf16 v[4:7], v[168:171], v[220:223], v[4:7]
	v_mfma_f32_16x16x32_bf16 v[60:63], v[164:167], v[180:183], v[60:63]
	v_mfma_f32_16x16x32_bf16 v[52:55], v[172:175], v[180:183], v[52:55]
	v_mfma_f32_16x16x32_bf16 v[44:47], v[164:167], v[198:201], v[44:47]
	v_mfma_f32_16x16x32_bf16 v[36:39], v[172:175], v[198:201], v[36:39]
	v_mfma_f32_16x16x32_bf16 v[28:31], v[164:167], v[206:209], v[28:31]
	v_mfma_f32_16x16x32_bf16 v[20:23], v[172:175], v[206:209], v[20:23]
	v_mfma_f32_16x16x32_bf16 v[12:15], v[164:167], v[224:227], v[12:15]
	v_mfma_f32_16x16x32_bf16 v[4:7], v[172:175], v[224:227], v[4:7]
	s_setprio 0
	s_barrier
	s_add_u32 s12, s12, 0x100
	s_addc_u32 s15, s15, 0
	s_add_u32 s38, s38, 0x100
	s_addc_u32 s39, s39, 0
	s_cmp_ge_i32 s19, s93
	s_mov_b32 s18, s19
	s_cbranch_scc0 .LBB0_38

; #define PG8_STAGE(bufoff, gbase, voff) do { _Pragma("unroll") for (int _i = 0; _i < 2; ++_i) \
;         __builtin_amdgcn_global_load_lds((const unsigned*)((const char*)(gbase) + (voff)[_i]), (PG8_LAS unsigned*)(lds + (bufoff) + ldsw + _i * 8192), 16, 0, 0); } while (0)
; #define PG8_LDA(dst, b, h) do { _Pragma("unroll") for (int m = 0; m < 4; ++m) _Pragma("unroll") for (int k = 0; k < 2; ++k) dst[m][k] = *(const PG8_LAS bf16x8*)(lds + PG8_SA(b, h) + aoff + m * 2048 + k * 1024); } while (0)
; #define PG8_LDB(dst, b, h) do { _Pragma("unroll") for (int n = 0; n < 2; ++n) _Pragma("unroll") for (int k = 0; k < 2; ++k) dst[n][k] = *(const PG8_LAS bf16x8*)(lds + PG8_SB(b, h) + boff + n * 2048 + k * 1024); } while (0)
; #define PG8_MMA(ai, bj, At, Bt) do { __builtin_amdgcn_s_setprio(1); _Pragma("unroll") for (int m = 0; m < 4; ++m) _Pragma("unroll") for (int n = 0; n < 2; ++n) _Pragma("unroll") for (int k = 0; k < 2; ++k) \
;         acc[ai][bj][m][n] = __builtin_amdgcn_mfma_f32_16x16x32_bf16(Bt[n][k], At[m][k], acc[ai][bj][m][n], 0, 0, 0); __builtin_amdgcn_s_setprio(0); } while (0)
; #define PG8_WAIT_V(n) asm volatile("s_waitcnt vmcnt(" #n ")" ::: "memory")
; #define PG8_WAIT_L(n) asm volatile("s_waitcnt lgkmcnt(" #n ")" ::: "memory")
; template <class Epi, class Sched, bool ALIGN_EPI = false, bool SP2 = false>
; __device__ __forceinline__ void gemm_phase(PG8_LAS unsigned char* lds, const Gemm g, const Sched& S, const Epi& E) {
;     ...
;             const bool last = (t == nt - 2);
;             const char* a1 = cA + (size_t)(t + 1) * kstep;
;             const char* a2 = last ? nA : cA + (size_t)(t + 2) * kstep; const char* b2 = last ? nB : cB + (size_t)(t + 2) * kstep;
;             const char* a3 = a2 + kstep; const char* b3 = b2 + kstep;
;             if (last && has_next) S.a_ready(nxt);
;             if constexpr (SP2) {
;             PG8_LDB(B0, 0, 0); PG8_LDB(B1, 0, 1); PG8_SCHED; PG8_LDA(At, 0, 0); PG8_STAGE(PG8_SA(1, 1), a1 + hstep, voffA);
;             PG8_WAIT_V(8); PG8_WAIT_L(0); PG8_BAR; PG8_MMA(0, 0, At, B0); PG8_MMA(0, 1, At, B1); PG8_BAR; PG8_SCHED;
;             PG8_LDA(At, 0, 1); PG8_STAGE(PG8_SB(0, 0), b2, voffB); PG8_STAGE(PG8_SB(0, 1), b2 + hstep, voffB); PG8_STAGE(PG8_SA(0, 0), a2, voffA);
;             PG8_WAIT_V(8); PG8_WAIT_L(0); PG8_BAR; PG8_MMA(1, 0, At, B0); PG8_MMA(1, 1, At, B1); PG8_BAR; PG8_SCHED;
.LBB0_80:
	s_add_i32 s93, s50, 2
	s_add_u32 s28, s46, 0x80
	s_addc_u32 s29, s47, 0
	s_add_i32 s74, s33, 0x100
	s_cmp_eq_u32 s4, s50
	s_cselect_b32 s51, s45, s29
	s_cselect_b32 s50, s44, s28
	v_add_u32_e32 v2, s74, v142
	s_cselect_b32 vcc_hi, s71, s92
	s_cselect_b32 vcc_lo, s70, s25
	s_cselect_b64 s[98:99], s[42:43], 0
	s_cmp_lg_u64 s[98:99], 0
	s_cselect_b32 s98, 0, -1
	v_and_b32_e32 v246, s98, v134
	v_and_b32_e32 v247, s98, v135
	v_and_b32_e32 v248, s98, v0
	v_and_b32_e32 v249, s98, v1
	v_and_b32_e32 v250, s98, v136
	v_and_b32_e32 v251, s98, v137
	v_and_b32_e32 v252, s98, v132
	v_and_b32_e32 v253, s98, v133
	s_add_i32 s28, s21, 0x100
	ds_read_b128 v[144:147], v2
	ds_read_b128 v[148:151], v2 offset:1024
	ds_read_b128 v[152:155], v2 offset:2048
	ds_read_b128 v[156:159], v2 offset:3072
	v_add_u32_e32 v2, s28, v142
	ds_read_b128 v[160:163], v2
	ds_read_b128 v[164:167], v2 offset:1024
	ds_read_b128 v[168:171], v2 offset:2048
	ds_read_b128 v[172:175], v2 offset:3072
	v_lshl_add_u64 v[210:211], s[46:47], 0, v[140:141]
	s_add_i32 m0, s19, 0xc000
	ds_read_b128 v[176:179], v143
	ds_read_b128 v[180:183], v143 offset:1024
	ds_read_b128 v[194:197], v143 offset:2048
	ds_read_b128 v[198:201], v143 offset:3072
	ds_read_b128 v[202:205], v143 offset:4096
	ds_read_b128 v[206:209], v143 offset:5120
	ds_read_b128 v[220:223], v143 offset:6144
	ds_read_b128 v[224:227], v143 offset:7168
	global_load_lds_dwordx4 v[210:211], off
	v_lshl_add_u64 v[210:211], s[46:47], 0, v[138:139]
	s_add_i32 m0, s19, 0xe000
	s_nop 0
	global_load_lds_dwordx4 v[210:211], off
	s_waitcnt vmcnt(8)
	s_waitcnt lgkmcnt(0)
	s_barrier
	s_setprio 1
	s_waitcnt lgkmcnt(0)
	v_mfma_f32_16x16x32_bf16 v[128:131], v[144:147], v[176:179], v[128:131]
	v_mfma_f32_16x16x32_bf16 v[124:127], v[152:155], v[176:179], v[124:127]
	v_mfma_f32_16x16x32_bf16 v[112:115], v[144:147], v[194:197], v[112:115]
	v_mfma_f32_16x16x32_bf16 v[108:111], v[152:155], v[194:197], v[108:111]
	v_mfma_f32_16x16x32_bf16 v[96:99], v[144:147], v[202:205], v[96:99]
	v_mfma_f32_16x16x32_bf16 v[92:95], v[152:155], v[202:205], v[92:95]
	v_mfma_f32_16x16x32_bf16 v[80:83], v[144:147], v[220:223], v[80:83]
	v_mfma_f32_16x16x32_bf16 v[76:79], v[152:155], v[220:223], v[76:79]
	v_mfma_f32_16x16x32_bf16 v[128:131], v[148:151], v[180:183], v[128:131]
	v_mfma_f32_16x16x32_bf16 v[124:127], v[156:159], v[180:183], v[124:127]
	v_mfma_f32_16x16x32_bf16 v[112:115], v[148:151], v[198:201], v[112:115]
	v_mfma_f32_16x16x32_bf16 v[108:111], v[156:159], v[198:201], v[108:111]
	v_mfma_f32_16x16x32_bf16 v[96:99], v[148:151], v[206:209], v[96:99]
	v_mfma_f32_16x16x32_bf16 v[92:95], v[156:159], v[206:209], v[92:95]
	v_mfma_f32_16x16x32_bf16 v[80:83], v[148:151], v[224:227], v[80:83]
	v_mfma_f32_16x16x32_bf16 v[76:79], v[156:159], v[224:227], v[76:79]
	s_setprio 0
	s_setprio 1
	v_mfma_f32_16x16x32_bf16 v[120:123], v[160:163], v[176:179], v[120:123]
	v_mfma_f32_16x16x32_bf16 v[116:119], v[168:171], v[176:179], v[116:119]
	v_mfma_f32_16x16x32_bf16 v[104:107], v[160:163], v[194:197], v[104:107]
	v_mfma_f32_16x16x32_bf16 v[100:103], v[168:171], v[194:197], v[100:103]
	v_mfma_f32_16x16x32_bf16 v[88:91], v[160:163], v[202:205], v[88:91]
	v_mfma_f32_16x16x32_bf16 v[84:87], v[168:171], v[202:205], v[84:87]
	v_mfma_f32_16x16x32_bf16 v[72:75], v[160:163], v[220:223], v[72:75]
	v_mfma_f32_16x16x32_bf16 v[68:71], v[168:171], v[220:223], v[68:71]
	v_mfma_f32_16x16x32_bf16 v[120:123], v[164:167], v[180:183], v[120:123]
	v_mfma_f32_16x16x32_bf16 v[116:119], v[172:175], v[180:183], v[116:119]
	v_mfma_f32_16x16x32_bf16 v[104:107], v[164:167], v[198:201], v[104:107]
	v_mfma_f32_16x16x32_bf16 v[100:103], v[172:175], v[198:201], v[100:103]
	v_mfma_f32_16x16x32_bf16 v[88:91], v[164:167], v[206:209], v[88:91]
	v_mfma_f32_16x16x32_bf16 v[84:87], v[172:175], v[206:209], v[84:87]
	v_mfma_f32_16x16x32_bf16 v[72:75], v[164:167], v[224:227], v[72:75]
	v_mfma_f32_16x16x32_bf16 v[68:71], v[172:175], v[224:227], v[68:71]
	s_setprio 0
	s_barrier
	s_add_i32 s29, s74, s18
	v_lshl_add_u64 v[210:211], vcc, 0, v[246:247]
	s_mov_b32 m0, s29
	ds_read_b128 v[176:179], v143 offset:16384
	ds_read_b128 v[180:183], v143 offset:17408
	ds_read_b128 v[194:197], v143 offset:18432
	ds_read_b128 v[198:201], v143 offset:19456
	ds_read_b128 v[202:205], v143 offset:20480
	ds_read_b128 v[206:209], v143 offset:21504
	ds_read_b128 v[220:223], v143 offset:22528
	ds_read_b128 v[224:227], v143 offset:23552
	global_load_lds_dwordx4 v[210:211], off
	s_add_i32 m0, s29, 0x2000
	v_lshl_add_u64 v[214:215], vcc, 0, v[248:249]
	s_add_u32 vcc_lo, vcc_lo, s58
	s_addc_u32 vcc_hi, vcc_hi, s59
	s_add_i32 s28, s28, s18
	global_load_lds_dwordx4 v[214:215], off
	v_lshl_add_u64 v[218:219], vcc, 0, v[246:247]
	s_mov_b32 m0, s28
	v_lshl_add_u64 v[228:229], vcc, 0, v[248:249]
	global_load_lds_dwordx4 v[218:219], off
	s_add_i32 m0, s28, 0x2000
	v_lshl_add_u64 v[230:231], s[50:51], 0, v[250:251]
	global_load_lds_dwordx4 v[228:229], off
	s_mov_b32 m0, s19
	v_lshl_add_u64 v[232:233], s[50:51], 0, v[252:253]
	global_load_lds_dwordx4 v[230:231], off
	s_mov_b32 m0, s30
	s_nop 0
	global_load_lds_dwordx4 v[232:233], off
	s_waitcnt vmcnt(8)
	s_waitcnt lgkmcnt(0)
	s_barrier
; #define PG8_STAGE(bufoff, gbase, voff) do { _Pragma("unroll") for (int _i = 0; _i < 2; ++_i) \
;         __builtin_amdgcn_global_load_lds((const unsigned*)((const char*)(gbase) + (voff)[_i]), (PG8_LAS unsigned*)(lds + (bufoff) + ldsw + _i * 8192), 16, 0, 0); } while (0)
; #define PG8_LDA(dst, b, h) do { _Pragma("unroll") for (int m = 0; m < 4; ++m) _Pragma("unroll") for (int k = 0; k < 2; ++k) dst[m][k] = *(const PG8_LAS bf16x8*)(lds + PG8_SA(b, h) + aoff + m * 2048 + k * 1024); } while (0)
; #define PG8_LDB(dst, b, h) do { _Pragma("unroll") for (int n = 0; n < 2; ++n) _Pragma("unroll") for (int k = 0; k < 2; ++k) dst[n][k] = *(const PG8_LAS bf16x8*)(lds + PG8_SB(b, h) + boff + n * 2048 + k * 1024); } while (0)
; #define PG8_MMA(ai, bj, At, Bt) do { __builtin_amdgcn_s_setprio(1); _Pragma("unroll") for (int m = 0; m < 4; ++m) _Pragma("unroll") for (int n = 0; n < 2; ++n) _Pragma("unroll") for (int k = 0; k < 2; ++k) \
;         acc[ai][bj][m][n] = __builtin_amdgcn_mfma_f32_16x16x32_bf16(Bt[n][k], At[m][k], acc[ai][bj][m][n], 0, 0, 0); __builtin_amdgcn_s_setprio(0); } while (0)
; #define PG8_WAIT_V(n) asm volatile("s_waitcnt vmcnt(" #n ")" ::: "memory")
; #define PG8_WAIT_L(n) asm volatile("s_waitcnt lgkmcnt(" #n ")" ::: "memory")
; #define PG8_BAR __builtin_amdgcn_s_barrier()
; #define PG8_SCHED __builtin_amdgcn_sched_barrier(0)
; template <class Epi, class Sched, bool ALIGN_EPI = false, bool SP2 = false>
; __device__ __forceinline__ void gemm_phase(PG8_LAS unsigned char* lds, const Gemm g, const Sched& S, const Epi& E) {
;     ...
;             PG8_WAIT_V(8); PG8_WAIT_L(0); PG8_BAR; PG8_MMA(1, 0, At, B0); PG8_MMA(1, 1, At, B1); PG8_BAR; PG8_SCHED;
;             PG8_LDB(B0, 1, 0); PG8_LDB(B1, 1, 1); PG8_SCHED; PG8_LDA(At, 1, 0); PG8_STAGE(PG8_SA(0, 1), a2 + hstep, voffA);
;             PG8_WAIT_V(8); PG8_WAIT_L(0); PG8_BAR; PG8_MMA(0, 0, At, B0); PG8_MMA(0, 1, At, B1); PG8_BAR; PG8_SCHED;
	s_setprio 1
	s_waitcnt lgkmcnt(0)
	v_mfma_f32_16x16x32_bf16 v[64:67], v[144:147], v[176:179], v[64:67]
	v_mfma_f32_16x16x32_bf16 v[60:63], v[152:155], v[176:179], v[60:63]
	v_mfma_f32_16x16x32_bf16 v[48:51], v[144:147], v[194:197], v[48:51]
	v_mfma_f32_16x16x32_bf16 v[44:47], v[152:155], v[194:197], v[44:47]
	v_mfma_f32_16x16x32_bf16 v[32:35], v[144:147], v[202:205], v[32:35]
	v_mfma_f32_16x16x32_bf16 v[28:31], v[152:155], v[202:205], v[28:31]
	v_mfma_f32_16x16x32_bf16 v[16:19], v[144:147], v[220:223], v[16:19]
	v_mfma_f32_16x16x32_bf16 v[12:15], v[152:155], v[220:223], v[12:15]
	v_mfma_f32_16x16x32_bf16 v[64:67], v[148:151], v[180:183], v[64:67]
	v_mfma_f32_16x16x32_bf16 v[60:63], v[156:159], v[180:183], v[60:63]
	v_mfma_f32_16x16x32_bf16 v[48:51], v[148:151], v[198:201], v[48:51]
	v_mfma_f32_16x16x32_bf16 v[44:47], v[156:159], v[198:201], v[44:47]
	v_mfma_f32_16x16x32_bf16 v[32:35], v[148:151], v[206:209], v[32:35]
	v_mfma_f32_16x16x32_bf16 v[28:31], v[156:159], v[206:209], v[28:31]
	v_mfma_f32_16x16x32_bf16 v[16:19], v[148:151], v[224:227], v[16:19]
	v_mfma_f32_16x16x32_bf16 v[12:15], v[156:159], v[224:227], v[12:15]
	s_setprio 0
	s_setprio 1
	v_mfma_f32_16x16x32_bf16 v[56:59], v[160:163], v[176:179], v[56:59]
	v_mfma_f32_16x16x32_bf16 v[52:55], v[168:171], v[176:179], v[52:55]
	v_mfma_f32_16x16x32_bf16 v[40:43], v[160:163], v[194:197], v[40:43]
	v_mfma_f32_16x16x32_bf16 v[36:39], v[168:171], v[194:197], v[36:39]
	v_mfma_f32_16x16x32_bf16 v[24:27], v[160:163], v[202:205], v[24:27]
	v_mfma_f32_16x16x32_bf16 v[20:23], v[168:171], v[202:205], v[20:23]
	v_mfma_f32_16x16x32_bf16 v[8:11], v[160:163], v[220:223], v[8:11]
	v_mfma_f32_16x16x32_bf16 v[4:7], v[168:171], v[220:223], v[4:7]
	v_mfma_f32_16x16x32_bf16 v[56:59], v[164:167], v[180:183], v[56:59]
	v_mfma_f32_16x16x32_bf16 v[52:55], v[172:175], v[180:183], v[52:55]
	v_mfma_f32_16x16x32_bf16 v[40:43], v[164:167], v[198:201], v[40:43]
	v_mfma_f32_16x16x32_bf16 v[36:39], v[172:175], v[198:201], v[36:39]
	v_mfma_f32_16x16x32_bf16 v[24:27], v[164:167], v[206:209], v[24:27]
	v_mfma_f32_16x16x32_bf16 v[20:23], v[172:175], v[206:209], v[20:23]
	v_mfma_f32_16x16x32_bf16 v[8:11], v[164:167], v[224:227], v[8:11]
	v_mfma_f32_16x16x32_bf16 v[4:7], v[172:175], v[224:227], v[4:7]
	s_setprio 0
	s_barrier
	s_add_i32 s28, s82, 0x100
	v_add_u32_e32 v2, s28, v142
	s_add_i32 s29, s78, 0x100
	ds_read_b128 v[144:147], v2
	ds_read_b128 v[148:151], v2 offset:1024
	ds_read_b128 v[152:155], v2 offset:2048
	ds_read_b128 v[156:159], v2 offset:3072
	v_add_u32_e32 v2, s29, v142
	ds_read_b128 v[160:163], v2
	ds_read_b128 v[164:167], v2 offset:1024
	ds_read_b128 v[168:171], v2 offset:2048
	ds_read_b128 v[172:175], v2 offset:3072
	s_add_u32 s50, s50, s58
	s_addc_u32 s51, s51, s59
	s_mov_b32 m0, s88
	v_lshl_add_u64 v[234:235], s[50:51], 0, v[250:251]
	ds_read_b128 v[176:179], v143 offset:32768
	ds_read_b128 v[180:183], v143 offset:33792
	ds_read_b128 v[194:197], v143 offset:34816
	ds_read_b128 v[198:201], v143 offset:35840
	ds_read_b128 v[202:205], v143 offset:36864
	ds_read_b128 v[206:209], v143 offset:37888
	ds_read_b128 v[220:223], v143 offset:38912
	ds_read_b128 v[224:227], v143 offset:39936
	global_load_lds_dwordx4 v[234:235], off
	v_lshl_add_u64 v[234:235], s[50:51], 0, v[252:253]
	s_mov_b32 m0, s89
	s_nop 0
	global_load_lds_dwordx4 v[234:235], off
	s_waitcnt vmcnt(8)
	s_waitcnt lgkmcnt(0)
	s_barrier
	s_setprio 1
	s_waitcnt lgkmcnt(0)
	v_mfma_f32_16x16x32_bf16 v[128:131], v[144:147], v[176:179], v[128:131]
	v_mfma_f32_16x16x32_bf16 v[124:127], v[152:155], v[176:179], v[124:127]
	v_mfma_f32_16x16x32_bf16 v[112:115], v[144:147], v[194:197], v[112:115]
	v_mfma_f32_16x16x32_bf16 v[108:111], v[152:155], v[194:197], v[108:111]
	v_mfma_f32_16x16x32_bf16 v[96:99], v[144:147], v[202:205], v[96:99]
	v_mfma_f32_16x16x32_bf16 v[92:95], v[152:155], v[202:205], v[92:95]
	v_mfma_f32_16x16x32_bf16 v[80:83], v[144:147], v[220:223], v[80:83]
	v_mfma_f32_16x16x32_bf16 v[76:79], v[152:155], v[220:223], v[76:79]
	v_mfma_f32_16x16x32_bf16 v[128:131], v[148:151], v[180:183], v[128:131]
	v_mfma_f32_16x16x32_bf16 v[124:127], v[156:159], v[180:183], v[124:127]
	v_mfma_f32_16x16x32_bf16 v[112:115], v[148:151], v[198:201], v[112:115]
	v_mfma_f32_16x16x32_bf16 v[108:111], v[156:159], v[198:201], v[108:111]
	v_mfma_f32_16x16x32_bf16 v[96:99], v[148:151], v[206:209], v[96:99]
	v_mfma_f32_16x16x32_bf16 v[92:95], v[156:159], v[206:209], v[92:95]
	v_mfma_f32_16x16x32_bf16 v[80:83], v[148:151], v[224:227], v[80:83]
	v_mfma_f32_16x16x32_bf16 v[76:79], v[156:159], v[224:227], v[76:79]
	s_setprio 0
	s_setprio 1
	v_mfma_f32_16x16x32_bf16 v[120:123], v[160:163], v[176:179], v[120:123]
	v_mfma_f32_16x16x32_bf16 v[116:119], v[168:171], v[176:179], v[116:119]
	v_mfma_f32_16x16x32_bf16 v[104:107], v[160:163], v[194:197], v[104:107]
	v_mfma_f32_16x16x32_bf16 v[100:103], v[168:171], v[194:197], v[100:103]
	v_mfma_f32_16x16x32_bf16 v[88:91], v[160:163], v[202:205], v[88:91]
	v_mfma_f32_16x16x32_bf16 v[84:87], v[168:171], v[202:205], v[84:87]
	v_mfma_f32_16x16x32_bf16 v[72:75], v[160:163], v[220:223], v[72:75]
	v_mfma_f32_16x16x32_bf16 v[68:71], v[168:171], v[220:223], v[68:71]
	v_mfma_f32_16x16x32_bf16 v[120:123], v[164:167], v[180:183], v[120:123]
	v_mfma_f32_16x16x32_bf16 v[116:119], v[172:175], v[180:183], v[116:119]
	v_mfma_f32_16x16x32_bf16 v[104:107], v[164:167], v[198:201], v[104:107]
	v_mfma_f32_16x16x32_bf16 v[100:103], v[172:175], v[198:201], v[100:103]
	v_mfma_f32_16x16x32_bf16 v[88:91], v[164:167], v[206:209], v[88:91]
	v_mfma_f32_16x16x32_bf16 v[84:87], v[172:175], v[206:209], v[84:87]
	v_mfma_f32_16x16x32_bf16 v[72:75], v[164:167], v[224:227], v[72:75]
	v_mfma_f32_16x16x32_bf16 v[68:71], v[172:175], v[224:227], v[68:71]
	s_setprio 0
	s_barrier
; #define PG8_STAGE(bufoff, gbase, voff) do { _Pragma("unroll") for (int _i = 0; _i < 2; ++_i) \
;         __builtin_amdgcn_global_load_lds((const unsigned*)((const char*)(gbase) + (voff)[_i]), (PG8_LAS unsigned*)(lds + (bufoff) + ldsw + _i * 8192), 16, 0, 0); } while (0)
; #define PG8_LDA(dst, b, h) do { _Pragma("unroll") for (int m = 0; m < 4; ++m) _Pragma("unroll") for (int k = 0; k < 2; ++k) dst[m][k] = *(const PG8_LAS bf16x8*)(lds + PG8_SA(b, h) + aoff + m * 2048 + k * 1024); } while (0)
; #define PG8_MMA(ai, bj, At, Bt) do { __builtin_amdgcn_s_setprio(1); _Pragma("unroll") for (int m = 0; m < 4; ++m) _Pragma("unroll") for (int n = 0; n < 2; ++n) _Pragma("unroll") for (int k = 0; k < 2; ++k) \
;         acc[ai][bj][m][n] = __builtin_amdgcn_mfma_f32_16x16x32_bf16(Bt[n][k], At[m][k], acc[ai][bj][m][n], 0, 0, 0); __builtin_amdgcn_s_setprio(0); } while (0)
; #define PG8_WAIT_V(n) asm volatile("s_waitcnt vmcnt(" #n ")" ::: "memory")
; #define PG8_WAIT_L(n) asm volatile("s_waitcnt lgkmcnt(" #n ")" ::: "memory")
; #define PG8_BAR __builtin_amdgcn_s_barrier()
; #define PG8_SCHED __builtin_amdgcn_sched_barrier(0)
; template <class Epi, class Sched, bool ALIGN_EPI = false, bool SP2 = false>
; __device__ __forceinline__ void gemm_phase(PG8_LAS unsigned char* lds, const Gemm g, const Sched& S, const Epi& E) {
;     ...
;             PG8_LDA(At, 1, 1); PG8_STAGE(PG8_SB(1, 0), b3, voffB); PG8_STAGE(PG8_SB(1, 1), b3 + hstep, voffB); PG8_STAGE(PG8_SA(1, 0), a3, voffA);
;             PG8_WAIT_V(8); PG8_WAIT_L(0); PG8_BAR; PG8_MMA(1, 0, At, B0); PG8_MMA(1, 1, At, B1); PG8_BAR; PG8_SCHED;
	s_add_i32 s28, s28, s18
	v_lshl_add_u64 v[210:211], v[210:211], 0, s[8:9]
	s_mov_b32 m0, s28
	ds_read_b128 v[176:179], v143 offset:49152
	ds_read_b128 v[180:183], v143 offset:50176
	ds_read_b128 v[194:197], v143 offset:51200
	ds_read_b128 v[198:201], v143 offset:52224
	ds_read_b128 v[202:205], v143 offset:53248
	ds_read_b128 v[206:209], v143 offset:54272
	ds_read_b128 v[220:223], v143 offset:55296
	ds_read_b128 v[224:227], v143 offset:56320
	global_load_lds_dwordx4 v[210:211], off
	v_lshl_add_u64 v[210:211], v[214:215], 0, s[8:9]
	s_add_i32 m0, s28, 0x2000
	s_add_i32 s28, s29, s18
	global_load_lds_dwordx4 v[210:211], off
	v_lshl_add_u64 v[210:211], v[218:219], 0, s[8:9]
	s_mov_b32 m0, s28
	s_nop 0
	global_load_lds_dwordx4 v[210:211], off
	v_lshl_add_u64 v[210:211], v[228:229], 0, s[8:9]
	s_add_i32 m0, s28, 0x2000
	s_nop 0
	global_load_lds_dwordx4 v[210:211], off
	v_lshl_add_u64 v[210:211], v[230:231], 0, s[8:9]
	s_mov_b32 m0, s90
	s_nop 0
	global_load_lds_dwordx4 v[210:211], off
	v_lshl_add_u64 v[210:211], v[232:233], 0, s[8:9]
	s_mov_b32 m0, s91
	s_nop 0
	global_load_lds_dwordx4 v[210:211], off
	s_waitcnt vmcnt(8)
	s_waitcnt lgkmcnt(0)
	s_barrier
	s_setprio 1
	s_waitcnt lgkmcnt(0)
	v_mfma_f32_16x16x32_bf16 v[64:67], v[144:147], v[176:179], v[64:67]
	v_mfma_f32_16x16x32_bf16 v[60:63], v[152:155], v[176:179], v[60:63]
	v_mfma_f32_16x16x32_bf16 v[48:51], v[144:147], v[194:197], v[48:51]
	v_mfma_f32_16x16x32_bf16 v[44:47], v[152:155], v[194:197], v[44:47]
	v_mfma_f32_16x16x32_bf16 v[32:35], v[144:147], v[202:205], v[32:35]
	v_mfma_f32_16x16x32_bf16 v[28:31], v[152:155], v[202:205], v[28:31]
	v_mfma_f32_16x16x32_bf16 v[16:19], v[144:147], v[220:223], v[16:19]
	v_mfma_f32_16x16x32_bf16 v[12:15], v[152:155], v[220:223], v[12:15]
	v_mfma_f32_16x16x32_bf16 v[64:67], v[148:151], v[180:183], v[64:67]
	v_mfma_f32_16x16x32_bf16 v[60:63], v[156:159], v[180:183], v[60:63]
	v_mfma_f32_16x16x32_bf16 v[48:51], v[148:151], v[198:201], v[48:51]
	v_mfma_f32_16x16x32_bf16 v[44:47], v[156:159], v[198:201], v[44:47]
	v_mfma_f32_16x16x32_bf16 v[32:35], v[148:151], v[206:209], v[32:35]
	v_mfma_f32_16x16x32_bf16 v[28:31], v[156:159], v[206:209], v[28:31]
	v_mfma_f32_16x16x32_bf16 v[16:19], v[148:151], v[224:227], v[16:19]
	v_mfma_f32_16x16x32_bf16 v[12:15], v[156:159], v[224:227], v[12:15]
	s_setprio 0
	s_setprio 1
	v_mfma_f32_16x16x32_bf16 v[56:59], v[160:163], v[176:179], v[56:59]
	v_mfma_f32_16x16x32_bf16 v[52:55], v[168:171], v[176:179], v[52:55]
	v_mfma_f32_16x16x32_bf16 v[40:43], v[160:163], v[194:197], v[40:43]
	v_mfma_f32_16x16x32_bf16 v[36:39], v[168:171], v[194:197], v[36:39]
	v_mfma_f32_16x16x32_bf16 v[24:27], v[160:163], v[202:205], v[24:27]
	v_mfma_f32_16x16x32_bf16 v[20:23], v[168:171], v[202:205], v[20:23]
	v_mfma_f32_16x16x32_bf16 v[8:11], v[160:163], v[220:223], v[8:11]
	v_mfma_f32_16x16x32_bf16 v[4:7], v[168:171], v[220:223], v[4:7]
	v_mfma_f32_16x16x32_bf16 v[56:59], v[164:167], v[180:183], v[56:59]
	v_mfma_f32_16x16x32_bf16 v[52:55], v[172:175], v[180:183], v[52:55]
	v_mfma_f32_16x16x32_bf16 v[40:43], v[164:167], v[198:201], v[40:43]
	v_mfma_f32_16x16x32_bf16 v[36:39], v[172:175], v[198:201], v[36:39]
	v_mfma_f32_16x16x32_bf16 v[24:27], v[164:167], v[206:209], v[24:27]
	v_mfma_f32_16x16x32_bf16 v[20:23], v[172:175], v[206:209], v[20:23]
	v_mfma_f32_16x16x32_bf16 v[8:11], v[164:167], v[224:227], v[8:11]
	v_mfma_f32_16x16x32_bf16 v[4:7], v[172:175], v[224:227], v[4:7]
	s_setprio 0
	s_barrier
	s_add_u32 s25, s25, 0x100
	s_addc_u32 s92, s92, 0
	s_add_u32 s46, s46, 0x100
	s_addc_u32 s47, s47, 0
	s_cmp_ge_i32 s93, s26
	s_mov_b32 s50, s93
	s_cbranch_scc0 .LBB0_80

; #define PG8_STAGE(bufoff, gbase, voff) do { _Pragma("unroll") for (int _i = 0; _i < 2; ++_i) \
;         __builtin_amdgcn_global_load_lds((const unsigned*)((const char*)(gbase) + (voff)[_i]), (PG8_LAS unsigned*)(lds + (bufoff) + ldsw + _i * 8192), 16, 0, 0); } while (0)
; #define PG8_LDA(dst, b, h) do { _Pragma("unroll") for (int m = 0; m < 4; ++m) _Pragma("unroll") for (int k = 0; k < 2; ++k) dst[m][k] = *(const PG8_LAS bf16x8*)(lds + PG8_SA(b, h) + aoff + m * 2048 + k * 1024); } while (0)
; #define PG8_LDB(dst, b, h) do { _Pragma("unroll") for (int n = 0; n < 2; ++n) _Pragma("unroll") for (int k = 0; k < 2; ++k) dst[n][k] = *(const PG8_LAS bf16x8*)(lds + PG8_SB(b, h) + boff + n * 2048 + k * 1024); } while (0)
; #define PG8_MMA(ai, bj, At, Bt) do { __builtin_amdgcn_s_setprio(1); _Pragma("unroll") for (int m = 0; m < 4; ++m) _Pragma("unroll") for (int n = 0; n < 2; ++n) _Pragma("unroll") for (int k = 0; k < 2; ++k) \
;         acc[ai][bj][m][n] = __builtin_amdgcn_mfma_f32_16x16x32_bf16(Bt[n][k], At[m][k], acc[ai][bj][m][n], 0, 0, 0); __builtin_amdgcn_s_setprio(0); } while (0)
; #define PG8_WAIT_V(n) asm volatile("s_waitcnt vmcnt(" #n ")" ::: "memory")
; #define PG8_WAIT_L(n) asm volatile("s_waitcnt lgkmcnt(" #n ")" ::: "memory")
; template <class Epi, class Sched, bool ALIGN_EPI = false, bool SP2 = false>
; __device__ __forceinline__ void gemm_phase(PG8_LAS unsigned char* lds, const Gemm g, const Sched& S, const Epi& E) {
;     ...
;             const bool last = (t == nt - 2);
;             const char* a1 = cA + (size_t)(t + 1) * kstep;
;             const char* a2 = last ? nA : cA + (size_t)(t + 2) * kstep; const char* b2 = last ? nB : cB + (size_t)(t + 2) * kstep;
;             const char* a3 = a2 + kstep; const char* b3 = b2 + kstep;
;             if (last && has_next) S.a_ready(nxt);
;             if constexpr (SP2) {
;             PG8_LDB(B0, 0, 0); PG8_LDB(B1, 0, 1); PG8_SCHED; PG8_LDA(At, 0, 0); PG8_STAGE(PG8_SA(1, 1), a1 + hstep, voffA);
;             PG8_WAIT_V(8); PG8_WAIT_L(0); PG8_BAR; PG8_MMA(0, 0, At, B0); PG8_MMA(0, 1, At, B1); PG8_BAR; PG8_SCHED;
;             PG8_LDA(At, 0, 1); PG8_STAGE(PG8_SB(0, 0), b2, voffB); PG8_STAGE(PG8_SB(0, 1), b2 + hstep, voffB); PG8_STAGE(PG8_SA(0, 0), a2, voffA);
;             PG8_WAIT_V(8); PG8_WAIT_L(0); PG8_BAR; PG8_MMA(1, 0, At, B0); PG8_MMA(1, 1, At, B1); PG8_BAR; PG8_SCHED;
.LBB0_105:
	s_add_i32 s50, s46, 2
	s_add_u32 s28, s42, 0x80
	s_addc_u32 s29, s43, 0
	s_add_i32 s51, s33, 0x100
	s_cmp_eq_u32 s89, s46
	s_cselect_b32 s47, s71, s29
	s_cselect_b32 s46, s70, s28
	v_add_u32_e32 v2, s51, v146
	s_cselect_b32 s29, s93, vcc_hi
	s_cselect_b32 s28, s92, vcc_lo
	s_cselect_b64 s[98:99], s[40:41], 0
	s_cmp_lg_u64 s[98:99], 0
	s_cselect_b32 s98, 0, -1
	v_and_b32_e32 v246, s98, v134
	v_and_b32_e32 v247, s98, v135
	v_and_b32_e32 v248, s98, v0
	v_and_b32_e32 v249, s98, v1
	v_and_b32_e32 v250, s98, v136
	v_and_b32_e32 v251, s98, v137
	v_and_b32_e32 v252, s98, v132
	v_and_b32_e32 v253, s98, v133
	s_add_i32 s74, s21, 0x100
	ds_read_b128 v[142:145], v2
	ds_read_b128 v[148:151], v2 offset:1024
	ds_read_b128 v[152:155], v2 offset:2048
	ds_read_b128 v[156:159], v2 offset:3072
	v_add_u32_e32 v2, s74, v146
	ds_read_b128 v[160:163], v2
	ds_read_b128 v[164:167], v2 offset:1024
	ds_read_b128 v[168:171], v2 offset:2048
	ds_read_b128 v[172:175], v2 offset:3072
	v_lshl_add_u64 v[210:211], s[42:43], 0, v[140:141]
	s_add_i32 m0, s18, 0xc000
	ds_read_b128 v[176:179], v147
	ds_read_b128 v[180:183], v147 offset:1024
	ds_read_b128 v[194:197], v147 offset:2048
	ds_read_b128 v[198:201], v147 offset:3072
	ds_read_b128 v[202:205], v147 offset:4096
	ds_read_b128 v[206:209], v147 offset:5120
	ds_read_b128 v[220:223], v147 offset:6144
	ds_read_b128 v[224:227], v147 offset:7168
	global_load_lds_dwordx4 v[210:211], off
	v_lshl_add_u64 v[210:211], s[42:43], 0, v[138:139]
	s_add_i32 m0, s18, 0xe000
	s_nop 0
	global_load_lds_dwordx4 v[210:211], off
	s_waitcnt vmcnt(8)
	s_waitcnt lgkmcnt(0)
	s_barrier
	s_setprio 1
	s_waitcnt lgkmcnt(0)
	v_mfma_f32_16x16x32_bf16 v[128:131], v[142:145], v[176:179], v[128:131]
	v_mfma_f32_16x16x32_bf16 v[124:127], v[152:155], v[176:179], v[124:127]
	v_mfma_f32_16x16x32_bf16 v[112:115], v[142:145], v[194:197], v[112:115]
	v_mfma_f32_16x16x32_bf16 v[108:111], v[152:155], v[194:197], v[108:111]
	v_mfma_f32_16x16x32_bf16 v[96:99], v[142:145], v[202:205], v[96:99]
	v_mfma_f32_16x16x32_bf16 v[92:95], v[152:155], v[202:205], v[92:95]
	v_mfma_f32_16x16x32_bf16 v[80:83], v[142:145], v[220:223], v[80:83]
	v_mfma_f32_16x16x32_bf16 v[76:79], v[152:155], v[220:223], v[76:79]
	v_mfma_f32_16x16x32_bf16 v[128:131], v[148:151], v[180:183], v[128:131]
	v_mfma_f32_16x16x32_bf16 v[124:127], v[156:159], v[180:183], v[124:127]
	v_mfma_f32_16x16x32_bf16 v[112:115], v[148:151], v[198:201], v[112:115]
	v_mfma_f32_16x16x32_bf16 v[108:111], v[156:159], v[198:201], v[108:111]
	v_mfma_f32_16x16x32_bf16 v[96:99], v[148:151], v[206:209], v[96:99]
	v_mfma_f32_16x16x32_bf16 v[92:95], v[156:159], v[206:209], v[92:95]
	v_mfma_f32_16x16x32_bf16 v[80:83], v[148:151], v[224:227], v[80:83]
	v_mfma_f32_16x16x32_bf16 v[76:79], v[156:159], v[224:227], v[76:79]
	s_setprio 0
	s_setprio 1
	v_mfma_f32_16x16x32_bf16 v[120:123], v[160:163], v[176:179], v[120:123]
	v_mfma_f32_16x16x32_bf16 v[116:119], v[168:171], v[176:179], v[116:119]
	v_mfma_f32_16x16x32_bf16 v[104:107], v[160:163], v[194:197], v[104:107]
	v_mfma_f32_16x16x32_bf16 v[100:103], v[168:171], v[194:197], v[100:103]
	v_mfma_f32_16x16x32_bf16 v[88:91], v[160:163], v[202:205], v[88:91]
	v_mfma_f32_16x16x32_bf16 v[84:87], v[168:171], v[202:205], v[84:87]
	v_mfma_f32_16x16x32_bf16 v[72:75], v[160:163], v[220:223], v[72:75]
	v_mfma_f32_16x16x32_bf16 v[68:71], v[168:171], v[220:223], v[68:71]
	v_mfma_f32_16x16x32_bf16 v[120:123], v[164:167], v[180:183], v[120:123]
	v_mfma_f32_16x16x32_bf16 v[116:119], v[172:175], v[180:183], v[116:119]
	v_mfma_f32_16x16x32_bf16 v[104:107], v[164:167], v[198:201], v[104:107]
	v_mfma_f32_16x16x32_bf16 v[100:103], v[172:175], v[198:201], v[100:103]
	v_mfma_f32_16x16x32_bf16 v[88:91], v[164:167], v[206:209], v[88:91]
	v_mfma_f32_16x16x32_bf16 v[84:87], v[172:175], v[206:209], v[84:87]
	v_mfma_f32_16x16x32_bf16 v[72:75], v[164:167], v[224:227], v[72:75]
	v_mfma_f32_16x16x32_bf16 v[68:71], v[172:175], v[224:227], v[68:71]
	s_setprio 0
	s_barrier
	s_add_i32 s51, s51, s15
	v_lshl_add_u64 v[210:211], s[28:29], 0, v[246:247]
	s_mov_b32 m0, s51
	ds_read_b128 v[176:179], v147 offset:16384
	ds_read_b128 v[180:183], v147 offset:17408
	ds_read_b128 v[194:197], v147 offset:18432
	ds_read_b128 v[198:201], v147 offset:19456
	ds_read_b128 v[202:205], v147 offset:20480
	ds_read_b128 v[206:209], v147 offset:21504
	ds_read_b128 v[220:223], v147 offset:22528
	ds_read_b128 v[224:227], v147 offset:23552
	global_load_lds_dwordx4 v[210:211], off
	s_add_i32 m0, s51, 0x2000
	v_lshl_add_u64 v[214:215], s[28:29], 0, v[248:249]
	s_add_u32 s28, s28, s58
	s_addc_u32 s29, s29, s59
	s_add_i32 s51, s74, s15
	global_load_lds_dwordx4 v[214:215], off
	v_lshl_add_u64 v[218:219], s[28:29], 0, v[246:247]
	s_mov_b32 m0, s51
	v_lshl_add_u64 v[228:229], s[28:29], 0, v[248:249]
	global_load_lds_dwordx4 v[218:219], off
	s_add_i32 m0, s51, 0x2000
	v_lshl_add_u64 v[230:231], s[46:47], 0, v[250:251]
	global_load_lds_dwordx4 v[228:229], off
	s_mov_b32 m0, s18
	v_lshl_add_u64 v[232:233], s[46:47], 0, v[252:253]
	global_load_lds_dwordx4 v[230:231], off
	s_mov_b32 m0, s19
	s_nop 0
	global_load_lds_dwordx4 v[232:233], off
	s_waitcnt vmcnt(8)
	s_waitcnt lgkmcnt(0)
	s_barrier
; #define PG8_STAGE(bufoff, gbase, voff) do { _Pragma("unroll") for (int _i = 0; _i < 2; ++_i) \
;         __builtin_amdgcn_global_load_lds((const unsigned*)((const char*)(gbase) + (voff)[_i]), (PG8_LAS unsigned*)(lds + (bufoff) + ldsw + _i * 8192), 16, 0, 0); } while (0)
; #define PG8_LDA(dst, b, h) do { _Pragma("unroll") for (int m = 0; m < 4; ++m) _Pragma("unroll") for (int k = 0; k < 2; ++k) dst[m][k] = *(const PG8_LAS bf16x8*)(lds + PG8_SA(b, h) + aoff + m * 2048 + k * 1024); } while (0)
; #define PG8_LDB(dst, b, h) do { _Pragma("unroll") for (int n = 0; n < 2; ++n) _Pragma("unroll") for (int k = 0; k < 2; ++k) dst[n][k] = *(const PG8_LAS bf16x8*)(lds + PG8_SB(b, h) + boff + n * 2048 + k * 1024); } while (0)
; #define PG8_MMA(ai, bj, At, Bt) do { __builtin_amdgcn_s_setprio(1); _Pragma("unroll") for (int m = 0; m < 4; ++m) _Pragma("unroll") for (int n = 0; n < 2; ++n) _Pragma("unroll") for (int k = 0; k < 2; ++k) \
;         acc[ai][bj][m][n] = __builtin_amdgcn_mfma_f32_16x16x32_bf16(Bt[n][k], At[m][k], acc[ai][bj][m][n], 0, 0, 0); __builtin_amdgcn_s_setprio(0); } while (0)
; #define PG8_WAIT_V(n) asm volatile("s_waitcnt vmcnt(" #n ")" ::: "memory")
; #define PG8_WAIT_L(n) asm volatile("s_waitcnt lgkmcnt(" #n ")" ::: "memory")
; #define PG8_BAR __builtin_amdgcn_s_barrier()
; #define PG8_SCHED __builtin_amdgcn_sched_barrier(0)
; template <class Epi, class Sched, bool ALIGN_EPI = false, bool SP2 = false>
; __device__ __forceinline__ void gemm_phase(PG8_LAS unsigned char* lds, const Gemm g, const Sched& S, const Epi& E) {
;     ...
;             PG8_WAIT_V(8); PG8_WAIT_L(0); PG8_BAR; PG8_MMA(1, 0, At, B0); PG8_MMA(1, 1, At, B1); PG8_BAR; PG8_SCHED;
;             PG8_LDB(B0, 1, 0); PG8_LDB(B1, 1, 1); PG8_SCHED; PG8_LDA(At, 1, 0); PG8_STAGE(PG8_SA(0, 1), a2 + hstep, voffA);
;             PG8_WAIT_V(8); PG8_WAIT_L(0); PG8_BAR; PG8_MMA(0, 0, At, B0); PG8_MMA(0, 1, At, B1); PG8_BAR; PG8_SCHED;
	s_setprio 1
	s_waitcnt lgkmcnt(0)
	v_mfma_f32_16x16x32_bf16 v[64:67], v[142:145], v[176:179], v[64:67]
	v_mfma_f32_16x16x32_bf16 v[60:63], v[152:155], v[176:179], v[60:63]
	v_mfma_f32_16x16x32_bf16 v[48:51], v[142:145], v[194:197], v[48:51]
	v_mfma_f32_16x16x32_bf16 v[44:47], v[152:155], v[194:197], v[44:47]
	v_mfma_f32_16x16x32_bf16 v[32:35], v[142:145], v[202:205], v[32:35]
	v_mfma_f32_16x16x32_bf16 v[28:31], v[152:155], v[202:205], v[28:31]
	v_mfma_f32_16x16x32_bf16 v[16:19], v[142:145], v[220:223], v[16:19]
	v_mfma_f32_16x16x32_bf16 v[12:15], v[152:155], v[220:223], v[12:15]
	v_mfma_f32_16x16x32_bf16 v[64:67], v[148:151], v[180:183], v[64:67]
	v_mfma_f32_16x16x32_bf16 v[60:63], v[156:159], v[180:183], v[60:63]
	v_mfma_f32_16x16x32_bf16 v[48:51], v[148:151], v[198:201], v[48:51]
	v_mfma_f32_16x16x32_bf16 v[44:47], v[156:159], v[198:201], v[44:47]
	v_mfma_f32_16x16x32_bf16 v[32:35], v[148:151], v[206:209], v[32:35]
	v_mfma_f32_16x16x32_bf16 v[28:31], v[156:159], v[206:209], v[28:31]
	v_mfma_f32_16x16x32_bf16 v[16:19], v[148:151], v[224:227], v[16:19]
	v_mfma_f32_16x16x32_bf16 v[12:15], v[156:159], v[224:227], v[12:15]
	s_setprio 0
	s_setprio 1
	v_mfma_f32_16x16x32_bf16 v[56:59], v[160:163], v[176:179], v[56:59]
	v_mfma_f32_16x16x32_bf16 v[52:55], v[168:171], v[176:179], v[52:55]
	v_mfma_f32_16x16x32_bf16 v[40:43], v[160:163], v[194:197], v[40:43]
	v_mfma_f32_16x16x32_bf16 v[36:39], v[168:171], v[194:197], v[36:39]
	v_mfma_f32_16x16x32_bf16 v[24:27], v[160:163], v[202:205], v[24:27]
	v_mfma_f32_16x16x32_bf16 v[20:23], v[168:171], v[202:205], v[20:23]
	v_mfma_f32_16x16x32_bf16 v[8:11], v[160:163], v[220:223], v[8:11]
	v_mfma_f32_16x16x32_bf16 v[4:7], v[168:171], v[220:223], v[4:7]
	v_mfma_f32_16x16x32_bf16 v[56:59], v[164:167], v[180:183], v[56:59]
	v_mfma_f32_16x16x32_bf16 v[52:55], v[172:175], v[180:183], v[52:55]
	v_mfma_f32_16x16x32_bf16 v[40:43], v[164:167], v[198:201], v[40:43]
	v_mfma_f32_16x16x32_bf16 v[36:39], v[172:175], v[198:201], v[36:39]
	v_mfma_f32_16x16x32_bf16 v[24:27], v[164:167], v[206:209], v[24:27]
	v_mfma_f32_16x16x32_bf16 v[20:23], v[172:175], v[206:209], v[20:23]
	v_mfma_f32_16x16x32_bf16 v[8:11], v[164:167], v[224:227], v[8:11]
	v_mfma_f32_16x16x32_bf16 v[4:7], v[172:175], v[224:227], v[4:7]
	s_setprio 0
	s_barrier
	s_add_i32 s51, s82, 0x100
	v_add_u32_e32 v2, s51, v146
	s_add_i32 s74, s78, 0x100
	ds_read_b128 v[142:145], v2
	ds_read_b128 v[148:151], v2 offset:1024
	ds_read_b128 v[152:155], v2 offset:2048
	ds_read_b128 v[156:159], v2 offset:3072
	v_add_u32_e32 v2, s74, v146
	ds_read_b128 v[160:163], v2
	ds_read_b128 v[164:167], v2 offset:1024
	ds_read_b128 v[168:171], v2 offset:2048
	ds_read_b128 v[172:175], v2 offset:3072
	s_add_u32 s28, s46, s58
	s_addc_u32 s29, s47, s59
	s_mov_b32 m0, s23
	v_lshl_add_u64 v[234:235], s[28:29], 0, v[250:251]
	ds_read_b128 v[176:179], v147 offset:32768
	ds_read_b128 v[180:183], v147 offset:33792
	ds_read_b128 v[194:197], v147 offset:34816
	ds_read_b128 v[198:201], v147 offset:35840
	ds_read_b128 v[202:205], v147 offset:36864
	ds_read_b128 v[206:209], v147 offset:37888
	ds_read_b128 v[220:223], v147 offset:38912
	ds_read_b128 v[224:227], v147 offset:39936
	global_load_lds_dwordx4 v[234:235], off
	v_lshl_add_u64 v[234:235], s[28:29], 0, v[252:253]
	s_mov_b32 m0, s26
	s_nop 0
	global_load_lds_dwordx4 v[234:235], off
	s_waitcnt vmcnt(8)
	s_waitcnt lgkmcnt(0)
	s_barrier
	s_setprio 1
	s_waitcnt lgkmcnt(0)
	v_mfma_f32_16x16x32_bf16 v[128:131], v[142:145], v[176:179], v[128:131]
	v_mfma_f32_16x16x32_bf16 v[124:127], v[152:155], v[176:179], v[124:127]
	v_mfma_f32_16x16x32_bf16 v[112:115], v[142:145], v[194:197], v[112:115]
	v_mfma_f32_16x16x32_bf16 v[108:111], v[152:155], v[194:197], v[108:111]
	v_mfma_f32_16x16x32_bf16 v[96:99], v[142:145], v[202:205], v[96:99]
	v_mfma_f32_16x16x32_bf16 v[92:95], v[152:155], v[202:205], v[92:95]
	v_mfma_f32_16x16x32_bf16 v[80:83], v[142:145], v[220:223], v[80:83]
	v_mfma_f32_16x16x32_bf16 v[76:79], v[152:155], v[220:223], v[76:79]
	v_mfma_f32_16x16x32_bf16 v[128:131], v[148:151], v[180:183], v[128:131]
	v_mfma_f32_16x16x32_bf16 v[124:127], v[156:159], v[180:183], v[124:127]
	v_mfma_f32_16x16x32_bf16 v[112:115], v[148:151], v[198:201], v[112:115]
	v_mfma_f32_16x16x32_bf16 v[108:111], v[156:159], v[198:201], v[108:111]
	v_mfma_f32_16x16x32_bf16 v[96:99], v[148:151], v[206:209], v[96:99]
	v_mfma_f32_16x16x32_bf16 v[92:95], v[156:159], v[206:209], v[92:95]
	v_mfma_f32_16x16x32_bf16 v[80:83], v[148:151], v[224:227], v[80:83]
	v_mfma_f32_16x16x32_bf16 v[76:79], v[156:159], v[224:227], v[76:79]
	s_setprio 0
	s_setprio 1
	v_mfma_f32_16x16x32_bf16 v[120:123], v[160:163], v[176:179], v[120:123]
	v_mfma_f32_16x16x32_bf16 v[116:119], v[168:171], v[176:179], v[116:119]
	v_mfma_f32_16x16x32_bf16 v[104:107], v[160:163], v[194:197], v[104:107]
	v_mfma_f32_16x16x32_bf16 v[100:103], v[168:171], v[194:197], v[100:103]
	v_mfma_f32_16x16x32_bf16 v[88:91], v[160:163], v[202:205], v[88:91]
	v_mfma_f32_16x16x32_bf16 v[84:87], v[168:171], v[202:205], v[84:87]
	v_mfma_f32_16x16x32_bf16 v[72:75], v[160:163], v[220:223], v[72:75]
	v_mfma_f32_16x16x32_bf16 v[68:71], v[168:171], v[220:223], v[68:71]
	v_mfma_f32_16x16x32_bf16 v[120:123], v[164:167], v[180:183], v[120:123]
	v_mfma_f32_16x16x32_bf16 v[116:119], v[172:175], v[180:183], v[116:119]
	v_mfma_f32_16x16x32_bf16 v[104:107], v[164:167], v[198:201], v[104:107]
	v_mfma_f32_16x16x32_bf16 v[100:103], v[172:175], v[198:201], v[100:103]
	v_mfma_f32_16x16x32_bf16 v[88:91], v[164:167], v[206:209], v[88:91]
	v_mfma_f32_16x16x32_bf16 v[84:87], v[172:175], v[206:209], v[84:87]
	v_mfma_f32_16x16x32_bf16 v[72:75], v[164:167], v[224:227], v[72:75]
	v_mfma_f32_16x16x32_bf16 v[68:71], v[172:175], v[224:227], v[68:71]
	s_setprio 0
	s_barrier
; #define PG8_STAGE(bufoff, gbase, voff) do { _Pragma("unroll") for (int _i = 0; _i < 2; ++_i) \
;         __builtin_amdgcn_global_load_lds((const unsigned*)((const char*)(gbase) + (voff)[_i]), (PG8_LAS unsigned*)(lds + (bufoff) + ldsw + _i * 8192), 16, 0, 0); } while (0)
; #define PG8_LDA(dst, b, h) do { _Pragma("unroll") for (int m = 0; m < 4; ++m) _Pragma("unroll") for (int k = 0; k < 2; ++k) dst[m][k] = *(const PG8_LAS bf16x8*)(lds + PG8_SA(b, h) + aoff + m * 2048 + k * 1024); } while (0)
; #define PG8_MMA(ai, bj, At, Bt) do { __builtin_amdgcn_s_setprio(1); _Pragma("unroll") for (int m = 0; m < 4; ++m) _Pragma("unroll") for (int n = 0; n < 2; ++n) _Pragma("unroll") for (int k = 0; k < 2; ++k) \
;         acc[ai][bj][m][n] = __builtin_amdgcn_mfma_f32_16x16x32_bf16(Bt[n][k], At[m][k], acc[ai][bj][m][n], 0, 0, 0); __builtin_amdgcn_s_setprio(0); } while (0)
; #define PG8_WAIT_V(n) asm volatile("s_waitcnt vmcnt(" #n ")" ::: "memory")
; #define PG8_WAIT_L(n) asm volatile("s_waitcnt lgkmcnt(" #n ")" ::: "memory")
; #define PG8_BAR __builtin_amdgcn_s_barrier()
; #define PG8_SCHED __builtin_amdgcn_sched_barrier(0)
; template <class Epi, class Sched, bool ALIGN_EPI = false, bool SP2 = false>
; __device__ __forceinline__ void gemm_phase(PG8_LAS unsigned char* lds, const Gemm g, const Sched& S, const Epi& E) {
;     ...
;             PG8_LDA(At, 1, 1); PG8_STAGE(PG8_SB(1, 0), b3, voffB); PG8_STAGE(PG8_SB(1, 1), b3 + hstep, voffB); PG8_STAGE(PG8_SA(1, 0), a3, voffA);
;             PG8_WAIT_V(8); PG8_WAIT_L(0); PG8_BAR; PG8_MMA(1, 0, At, B0); PG8_MMA(1, 1, At, B1); PG8_BAR; PG8_SCHED;
	s_add_i32 s28, s51, s15
	v_lshl_add_u64 v[210:211], v[210:211], 0, s[8:9]
	s_mov_b32 m0, s28
	ds_read_b128 v[176:179], v147 offset:49152
	ds_read_b128 v[180:183], v147 offset:50176
	ds_read_b128 v[194:197], v147 offset:51200
	ds_read_b128 v[198:201], v147 offset:52224
	ds_read_b128 v[202:205], v147 offset:53248
	ds_read_b128 v[206:209], v147 offset:54272
	ds_read_b128 v[220:223], v147 offset:55296
	ds_read_b128 v[224:227], v147 offset:56320
	global_load_lds_dwordx4 v[210:211], off
	v_lshl_add_u64 v[210:211], v[214:215], 0, s[8:9]
	s_add_i32 m0, s28, 0x2000
	s_add_i32 s28, s74, s15
	global_load_lds_dwordx4 v[210:211], off
	v_lshl_add_u64 v[210:211], v[218:219], 0, s[8:9]
	s_mov_b32 m0, s28
	s_nop 0
	global_load_lds_dwordx4 v[210:211], off
	v_lshl_add_u64 v[210:211], v[228:229], 0, s[8:9]
	s_add_i32 m0, s28, 0x2000
	s_nop 0
	global_load_lds_dwordx4 v[210:211], off
	v_lshl_add_u64 v[210:211], v[230:231], 0, s[8:9]
	s_mov_b32 m0, s27
	s_nop 0
	global_load_lds_dwordx4 v[210:211], off
	v_lshl_add_u64 v[210:211], v[232:233], 0, s[8:9]
	s_mov_b32 m0, s30
	s_nop 0
	global_load_lds_dwordx4 v[210:211], off
	s_waitcnt vmcnt(8)
	s_waitcnt lgkmcnt(0)
	s_barrier
	s_setprio 1
	s_waitcnt lgkmcnt(0)
	v_mfma_f32_16x16x32_bf16 v[64:67], v[142:145], v[176:179], v[64:67]
	v_mfma_f32_16x16x32_bf16 v[60:63], v[152:155], v[176:179], v[60:63]
	v_mfma_f32_16x16x32_bf16 v[48:51], v[142:145], v[194:197], v[48:51]
	v_mfma_f32_16x16x32_bf16 v[44:47], v[152:155], v[194:197], v[44:47]
	v_mfma_f32_16x16x32_bf16 v[32:35], v[142:145], v[202:205], v[32:35]
	v_mfma_f32_16x16x32_bf16 v[28:31], v[152:155], v[202:205], v[28:31]
	v_mfma_f32_16x16x32_bf16 v[16:19], v[142:145], v[220:223], v[16:19]
	v_mfma_f32_16x16x32_bf16 v[12:15], v[152:155], v[220:223], v[12:15]
	v_mfma_f32_16x16x32_bf16 v[64:67], v[148:151], v[180:183], v[64:67]
	v_mfma_f32_16x16x32_bf16 v[60:63], v[156:159], v[180:183], v[60:63]
	v_mfma_f32_16x16x32_bf16 v[48:51], v[148:151], v[198:201], v[48:51]
	v_mfma_f32_16x16x32_bf16 v[44:47], v[156:159], v[198:201], v[44:47]
	v_mfma_f32_16x16x32_bf16 v[32:35], v[148:151], v[206:209], v[32:35]
	v_mfma_f32_16x16x32_bf16 v[28:31], v[156:159], v[206:209], v[28:31]
	v_mfma_f32_16x16x32_bf16 v[16:19], v[148:151], v[224:227], v[16:19]
	v_mfma_f32_16x16x32_bf16 v[12:15], v[156:159], v[224:227], v[12:15]
	s_setprio 0
	s_setprio 1
	v_mfma_f32_16x16x32_bf16 v[56:59], v[160:163], v[176:179], v[56:59]
	v_mfma_f32_16x16x32_bf16 v[52:55], v[168:171], v[176:179], v[52:55]
	v_mfma_f32_16x16x32_bf16 v[40:43], v[160:163], v[194:197], v[40:43]
	v_mfma_f32_16x16x32_bf16 v[36:39], v[168:171], v[194:197], v[36:39]
	v_mfma_f32_16x16x32_bf16 v[24:27], v[160:163], v[202:205], v[24:27]
	v_mfma_f32_16x16x32_bf16 v[20:23], v[168:171], v[202:205], v[20:23]
	v_mfma_f32_16x16x32_bf16 v[8:11], v[160:163], v[220:223], v[8:11]
	v_mfma_f32_16x16x32_bf16 v[4:7], v[168:171], v[220:223], v[4:7]
	v_mfma_f32_16x16x32_bf16 v[56:59], v[164:167], v[180:183], v[56:59]
	v_mfma_f32_16x16x32_bf16 v[52:55], v[172:175], v[180:183], v[52:55]
	v_mfma_f32_16x16x32_bf16 v[40:43], v[164:167], v[198:201], v[40:43]
	v_mfma_f32_16x16x32_bf16 v[36:39], v[172:175], v[198:201], v[36:39]
	v_mfma_f32_16x16x32_bf16 v[24:27], v[164:167], v[206:209], v[24:27]
	v_mfma_f32_16x16x32_bf16 v[20:23], v[172:175], v[206:209], v[20:23]
	v_mfma_f32_16x16x32_bf16 v[8:11], v[164:167], v[224:227], v[8:11]
	v_mfma_f32_16x16x32_bf16 v[4:7], v[172:175], v[224:227], v[4:7]
	s_setprio 0
	s_barrier
	s_add_u32 vcc_lo, vcc_lo, 0x100
	s_addc_u32 vcc_hi, vcc_hi, 0
	s_add_u32 s42, s42, 0x100
	s_addc_u32 s43, s43, 0
	s_cmp_ge_i32 s50, s76
	s_mov_b32 s46, s50
	s_cbranch_scc0 .LBB0_105

; #define PG8_STAGE(bufoff, gbase, voff) do { _Pragma("unroll") for (int _i = 0; _i < 2; ++_i) \
;         __builtin_amdgcn_global_load_lds((const unsigned*)((const char*)(gbase) + (voff)[_i]), (PG8_LAS unsigned*)(lds + (bufoff) + ldsw + _i * 8192), 16, 0, 0); } while (0)
; #define PG8_LDA(dst, b, h) do { _Pragma("unroll") for (int m = 0; m < 4; ++m) _Pragma("unroll") for (int k = 0; k < 2; ++k) dst[m][k] = *(const PG8_LAS bf16x8*)(lds + PG8_SA(b, h) + aoff + m * 2048 + k * 1024); } while (0)
; #define PG8_LDB(dst, b, h) do { _Pragma("unroll") for (int n = 0; n < 2; ++n) _Pragma("unroll") for (int k = 0; k < 2; ++k) dst[n][k] = *(const PG8_LAS bf16x8*)(lds + PG8_SB(b, h) + boff + n * 2048 + k * 1024); } while (0)
; #define PG8_MMA(ai, bj, At, Bt) do { __builtin_amdgcn_s_setprio(1); _Pragma("unroll") for (int m = 0; m < 4; ++m) _Pragma("unroll") for (int n = 0; n < 2; ++n) _Pragma("unroll") for (int k = 0; k < 2; ++k) \
;         acc[ai][bj][m][n] = __builtin_amdgcn_mfma_f32_16x16x32_bf16(Bt[n][k], At[m][k], acc[ai][bj][m][n], 0, 0, 0); __builtin_amdgcn_s_setprio(0); } while (0)
; #define PG8_WAIT_V(n) asm volatile("s_waitcnt vmcnt(" #n ")" ::: "memory")
; #define PG8_WAIT_L(n) asm volatile("s_waitcnt lgkmcnt(" #n ")" ::: "memory")
; template <class Epi, class Sched, bool ALIGN_EPI = false, bool SP2 = false>
; __device__ __forceinline__ void gemm_phase(PG8_LAS unsigned char* lds, const Gemm g, const Sched& S, const Epi& E) {
;     ...
;             const bool last = (t == nt - 2);
;             const char* a1 = cA + (size_t)(t + 1) * kstep;
;             const char* a2 = last ? nA : cA + (size_t)(t + 2) * kstep; const char* b2 = last ? nB : cB + (size_t)(t + 2) * kstep;
;             const char* a3 = a2 + kstep; const char* b3 = b2 + kstep;
;             if (last && has_next) S.a_ready(nxt);
;             if constexpr (SP2) {
;             PG8_LDB(B0, 0, 0); PG8_LDB(B1, 0, 1); PG8_SCHED; PG8_LDA(At, 0, 0); PG8_STAGE(PG8_SA(1, 1), a1 + hstep, voffA);
;             PG8_WAIT_V(8); PG8_WAIT_L(0); PG8_BAR; PG8_MMA(0, 0, At, B0); PG8_MMA(0, 1, At, B1); PG8_BAR; PG8_SCHED;
;             PG8_LDA(At, 0, 1); PG8_STAGE(PG8_SB(0, 0), b2, voffB); PG8_STAGE(PG8_SB(0, 1), b2 + hstep, voffB); PG8_STAGE(PG8_SA(0, 0), a2, voffA);
;             PG8_WAIT_V(8); PG8_WAIT_L(0); PG8_BAR; PG8_MMA(1, 0, At, B0); PG8_MMA(1, 1, At, B1); PG8_BAR; PG8_SCHED;
.LBB0_324:
	s_add_i32 s58, s52, 2
	s_add_u32 s28, s56, 0x80
	s_addc_u32 s29, s57, 0
	s_add_i32 s59, s33, 0x100
	s_cmp_eq_u32 s62, s52
	s_cselect_b32 s53, s43, s29
	s_cselect_b32 s52, s42, s28
	v_add_u32_e32 v2, s59, v142
	s_cselect_b32 s77, s55, s70
	s_cselect_b32 s76, s54, s69
	s_cselect_b64 s[98:99], s[40:41], 0
	s_cmp_lg_u64 s[98:99], 0
	s_cselect_b32 s98, 0, -1
	v_and_b32_e32 v246, s98, v134
	v_and_b32_e32 v247, s98, v135
	v_and_b32_e32 v248, s98, v0
	v_and_b32_e32 v249, s98, v1
	v_and_b32_e32 v250, s98, v136
	v_and_b32_e32 v251, s98, v137
	v_and_b32_e32 v252, s98, v132
	v_and_b32_e32 v253, s98, v133
	s_add_i32 s28, s21, 0x100
	ds_read_b128 v[144:147], v2
	ds_read_b128 v[148:151], v2 offset:1024
	ds_read_b128 v[152:155], v2 offset:2048
	ds_read_b128 v[156:159], v2 offset:3072
	v_add_u32_e32 v2, s28, v142
	ds_read_b128 v[160:163], v2
	ds_read_b128 v[164:167], v2 offset:1024
	ds_read_b128 v[168:171], v2 offset:2048
	ds_read_b128 v[172:175], v2 offset:3072
	v_lshl_add_u64 v[210:211], s[56:57], 0, v[140:141]
	s_add_i32 m0, s19, 0xc000
	ds_read_b128 v[176:179], v143
	ds_read_b128 v[180:183], v143 offset:1024
	ds_read_b128 v[194:197], v143 offset:2048
	ds_read_b128 v[198:201], v143 offset:3072
	ds_read_b128 v[202:205], v143 offset:4096
	ds_read_b128 v[206:209], v143 offset:5120
	ds_read_b128 v[220:223], v143 offset:6144
	ds_read_b128 v[224:227], v143 offset:7168
	global_load_lds_dwordx4 v[210:211], off
	v_lshl_add_u64 v[210:211], s[56:57], 0, v[138:139]
	s_add_i32 m0, s19, 0xe000
	s_nop 0
	global_load_lds_dwordx4 v[210:211], off
	s_waitcnt vmcnt(8)
	s_waitcnt lgkmcnt(0)
	s_barrier
	s_setprio 1
	s_waitcnt lgkmcnt(0)
	v_mfma_f32_16x16x32_bf16 v[124:127], v[144:147], v[176:179], v[124:127]
	v_mfma_f32_16x16x32_bf16 v[128:131], v[152:155], v[176:179], v[128:131]
	v_mfma_f32_16x16x32_bf16 v[112:115], v[144:147], v[194:197], v[112:115]
	v_mfma_f32_16x16x32_bf16 v[108:111], v[152:155], v[194:197], v[108:111]
	v_mfma_f32_16x16x32_bf16 v[96:99], v[144:147], v[202:205], v[96:99]
	v_mfma_f32_16x16x32_bf16 v[92:95], v[152:155], v[202:205], v[92:95]
	v_mfma_f32_16x16x32_bf16 v[80:83], v[144:147], v[220:223], v[80:83]
	v_mfma_f32_16x16x32_bf16 v[76:79], v[152:155], v[220:223], v[76:79]
	v_mfma_f32_16x16x32_bf16 v[124:127], v[148:151], v[180:183], v[124:127]
	v_mfma_f32_16x16x32_bf16 v[128:131], v[156:159], v[180:183], v[128:131]
	v_mfma_f32_16x16x32_bf16 v[112:115], v[148:151], v[198:201], v[112:115]
	v_mfma_f32_16x16x32_bf16 v[108:111], v[156:159], v[198:201], v[108:111]
	v_mfma_f32_16x16x32_bf16 v[96:99], v[148:151], v[206:209], v[96:99]
	v_mfma_f32_16x16x32_bf16 v[92:95], v[156:159], v[206:209], v[92:95]
	v_mfma_f32_16x16x32_bf16 v[80:83], v[148:151], v[224:227], v[80:83]
	v_mfma_f32_16x16x32_bf16 v[76:79], v[156:159], v[224:227], v[76:79]
	s_setprio 0
	s_setprio 1
	v_mfma_f32_16x16x32_bf16 v[120:123], v[160:163], v[176:179], v[120:123]
	v_mfma_f32_16x16x32_bf16 v[116:119], v[168:171], v[176:179], v[116:119]
	v_mfma_f32_16x16x32_bf16 v[104:107], v[160:163], v[194:197], v[104:107]
	v_mfma_f32_16x16x32_bf16 v[100:103], v[168:171], v[194:197], v[100:103]
	v_mfma_f32_16x16x32_bf16 v[88:91], v[160:163], v[202:205], v[88:91]
	v_mfma_f32_16x16x32_bf16 v[84:87], v[168:171], v[202:205], v[84:87]
	v_mfma_f32_16x16x32_bf16 v[72:75], v[160:163], v[220:223], v[72:75]
	v_mfma_f32_16x16x32_bf16 v[68:71], v[168:171], v[220:223], v[68:71]
	v_mfma_f32_16x16x32_bf16 v[120:123], v[164:167], v[180:183], v[120:123]
	v_mfma_f32_16x16x32_bf16 v[116:119], v[172:175], v[180:183], v[116:119]
	v_mfma_f32_16x16x32_bf16 v[104:107], v[164:167], v[198:201], v[104:107]
	v_mfma_f32_16x16x32_bf16 v[100:103], v[172:175], v[198:201], v[100:103]
	v_mfma_f32_16x16x32_bf16 v[88:91], v[164:167], v[206:209], v[88:91]
	v_mfma_f32_16x16x32_bf16 v[84:87], v[172:175], v[206:209], v[84:87]
	v_mfma_f32_16x16x32_bf16 v[72:75], v[164:167], v[224:227], v[72:75]
	v_mfma_f32_16x16x32_bf16 v[68:71], v[172:175], v[224:227], v[68:71]
	s_setprio 0
	s_barrier
	s_add_i32 s29, s59, s15
	v_lshl_add_u64 v[210:211], s[76:77], 0, v[246:247]
	s_mov_b32 m0, s29
	ds_read_b128 v[176:179], v143 offset:16384
	ds_read_b128 v[180:183], v143 offset:17408
	ds_read_b128 v[194:197], v143 offset:18432
	ds_read_b128 v[198:201], v143 offset:19456
	ds_read_b128 v[202:205], v143 offset:20480
	ds_read_b128 v[206:209], v143 offset:21504
	ds_read_b128 v[220:223], v143 offset:22528
	ds_read_b128 v[224:227], v143 offset:23552
	global_load_lds_dwordx4 v[210:211], off
	s_add_i32 m0, s29, 0x2000
	v_lshl_add_u64 v[228:229], s[76:77], 0, v[248:249]
	s_add_u32 s76, s76, s36
	s_addc_u32 s77, s77, s37
	s_add_i32 s28, s28, s15
	global_load_lds_dwordx4 v[228:229], off
	v_lshl_add_u64 v[230:231], s[76:77], 0, v[246:247]
	s_mov_b32 m0, s28
	v_lshl_add_u64 v[232:233], s[76:77], 0, v[248:249]
	global_load_lds_dwordx4 v[230:231], off
	s_add_i32 m0, s28, 0x2000
	v_lshl_add_u64 v[234:235], s[52:53], 0, v[250:251]
	global_load_lds_dwordx4 v[232:233], off
	s_mov_b32 m0, s19
	v_lshl_add_u64 v[236:237], s[52:53], 0, v[252:253]
	global_load_lds_dwordx4 v[234:235], off
	s_mov_b32 m0, s23
	s_nop 0
	global_load_lds_dwordx4 v[236:237], off
	s_waitcnt vmcnt(8)
	s_waitcnt lgkmcnt(0)
	s_barrier
; #define PG8_STAGE(bufoff, gbase, voff) do { _Pragma("unroll") for (int _i = 0; _i < 2; ++_i) \
;         __builtin_amdgcn_global_load_lds((const unsigned*)((const char*)(gbase) + (voff)[_i]), (PG8_LAS unsigned*)(lds + (bufoff) + ldsw + _i * 8192), 16, 0, 0); } while (0)
; #define PG8_LDA(dst, b, h) do { _Pragma("unroll") for (int m = 0; m < 4; ++m) _Pragma("unroll") for (int k = 0; k < 2; ++k) dst[m][k] = *(const PG8_LAS bf16x8*)(lds + PG8_SA(b, h) + aoff + m * 2048 + k * 1024); } while (0)
; #define PG8_LDB(dst, b, h) do { _Pragma("unroll") for (int n = 0; n < 2; ++n) _Pragma("unroll") for (int k = 0; k < 2; ++k) dst[n][k] = *(const PG8_LAS bf16x8*)(lds + PG8_SB(b, h) + boff + n * 2048 + k * 1024); } while (0)
; #define PG8_MMA(ai, bj, At, Bt) do { __builtin_amdgcn_s_setprio(1); _Pragma("unroll") for (int m = 0; m < 4; ++m) _Pragma("unroll") for (int n = 0; n < 2; ++n) _Pragma("unroll") for (int k = 0; k < 2; ++k) \
;         acc[ai][bj][m][n] = __builtin_amdgcn_mfma_f32_16x16x32_bf16(Bt[n][k], At[m][k], acc[ai][bj][m][n], 0, 0, 0); __builtin_amdgcn_s_setprio(0); } while (0)
; #define PG8_WAIT_V(n) asm volatile("s_waitcnt vmcnt(" #n ")" ::: "memory")
; #define PG8_WAIT_L(n) asm volatile("s_waitcnt lgkmcnt(" #n ")" ::: "memory")
; #define PG8_BAR __builtin_amdgcn_s_barrier()
; #define PG8_SCHED __builtin_amdgcn_sched_barrier(0)
; template <class Epi, class Sched, bool ALIGN_EPI = false, bool SP2 = false>
; __device__ __forceinline__ void gemm_phase(PG8_LAS unsigned char* lds, const Gemm g, const Sched& S, const Epi& E) {
;     ...
;             PG8_WAIT_V(8); PG8_WAIT_L(0); PG8_BAR; PG8_MMA(1, 0, At, B0); PG8_MMA(1, 1, At, B1); PG8_BAR; PG8_SCHED;
;             PG8_LDB(B0, 1, 0); PG8_LDB(B1, 1, 1); PG8_SCHED; PG8_LDA(At, 1, 0); PG8_STAGE(PG8_SA(0, 1), a2 + hstep, voffA);
;             PG8_WAIT_V(8); PG8_WAIT_L(0); PG8_BAR; PG8_MMA(0, 0, At, B0); PG8_MMA(0, 1, At, B1); PG8_BAR; PG8_SCHED;
	s_setprio 1
	s_waitcnt lgkmcnt(0)
	v_mfma_f32_16x16x32_bf16 v[64:67], v[144:147], v[176:179], v[64:67]
	v_mfma_f32_16x16x32_bf16 v[60:63], v[152:155], v[176:179], v[60:63]
	v_mfma_f32_16x16x32_bf16 v[48:51], v[144:147], v[194:197], v[48:51]
	v_mfma_f32_16x16x32_bf16 v[44:47], v[152:155], v[194:197], v[44:47]
	v_mfma_f32_16x16x32_bf16 v[32:35], v[144:147], v[202:205], v[32:35]
	v_mfma_f32_16x16x32_bf16 v[28:31], v[152:155], v[202:205], v[28:31]
	v_mfma_f32_16x16x32_bf16 v[16:19], v[144:147], v[220:223], v[16:19]
	v_mfma_f32_16x16x32_bf16 v[12:15], v[152:155], v[220:223], v[12:15]
	v_mfma_f32_16x16x32_bf16 v[64:67], v[148:151], v[180:183], v[64:67]
	v_mfma_f32_16x16x32_bf16 v[60:63], v[156:159], v[180:183], v[60:63]
	v_mfma_f32_16x16x32_bf16 v[48:51], v[148:151], v[198:201], v[48:51]
	v_mfma_f32_16x16x32_bf16 v[44:47], v[156:159], v[198:201], v[44:47]
	v_mfma_f32_16x16x32_bf16 v[32:35], v[148:151], v[206:209], v[32:35]
	v_mfma_f32_16x16x32_bf16 v[28:31], v[156:159], v[206:209], v[28:31]
	v_mfma_f32_16x16x32_bf16 v[16:19], v[148:151], v[224:227], v[16:19]
	v_mfma_f32_16x16x32_bf16 v[12:15], v[156:159], v[224:227], v[12:15]
	s_setprio 0
	s_setprio 1
	v_mfma_f32_16x16x32_bf16 v[56:59], v[160:163], v[176:179], v[56:59]
	v_mfma_f32_16x16x32_bf16 v[52:55], v[168:171], v[176:179], v[52:55]
	v_mfma_f32_16x16x32_bf16 v[40:43], v[160:163], v[194:197], v[40:43]
	v_mfma_f32_16x16x32_bf16 v[36:39], v[168:171], v[194:197], v[36:39]
	v_mfma_f32_16x16x32_bf16 v[24:27], v[160:163], v[202:205], v[24:27]
	v_mfma_f32_16x16x32_bf16 v[20:23], v[168:171], v[202:205], v[20:23]
	v_mfma_f32_16x16x32_bf16 v[8:11], v[160:163], v[220:223], v[8:11]
	v_mfma_f32_16x16x32_bf16 v[4:7], v[168:171], v[220:223], v[4:7]
	v_mfma_f32_16x16x32_bf16 v[56:59], v[164:167], v[180:183], v[56:59]
	v_mfma_f32_16x16x32_bf16 v[52:55], v[172:175], v[180:183], v[52:55]
	v_mfma_f32_16x16x32_bf16 v[40:43], v[164:167], v[198:201], v[40:43]
	v_mfma_f32_16x16x32_bf16 v[36:39], v[172:175], v[198:201], v[36:39]
	v_mfma_f32_16x16x32_bf16 v[24:27], v[164:167], v[206:209], v[24:27]
	v_mfma_f32_16x16x32_bf16 v[20:23], v[172:175], v[206:209], v[20:23]
	v_mfma_f32_16x16x32_bf16 v[8:11], v[164:167], v[224:227], v[8:11]
	v_mfma_f32_16x16x32_bf16 v[4:7], v[172:175], v[224:227], v[4:7]
	s_setprio 0
	s_barrier
	s_add_i32 s28, s82, 0x100
	v_add_u32_e32 v2, s28, v142
	s_add_i32 s29, s78, 0x100
	ds_read_b128 v[144:147], v2
	ds_read_b128 v[148:151], v2 offset:1024
	ds_read_b128 v[152:155], v2 offset:2048
	ds_read_b128 v[156:159], v2 offset:3072
	v_add_u32_e32 v2, s29, v142
	ds_read_b128 v[160:163], v2
	ds_read_b128 v[164:167], v2 offset:1024
	ds_read_b128 v[168:171], v2 offset:2048
	ds_read_b128 v[172:175], v2 offset:3072
	s_add_u32 s52, s52, s36
	s_addc_u32 s53, s53, s37
	s_mov_b32 m0, s25
	v_lshl_add_u64 v[238:239], s[52:53], 0, v[250:251]
	ds_read_b128 v[176:179], v143 offset:32768
	ds_read_b128 v[180:183], v143 offset:33792
	ds_read_b128 v[194:197], v143 offset:34816
	ds_read_b128 v[198:201], v143 offset:35840
	ds_read_b128 v[202:205], v143 offset:36864
	ds_read_b128 v[206:209], v143 offset:37888
	ds_read_b128 v[220:223], v143 offset:38912
	ds_read_b128 v[224:227], v143 offset:39936
	global_load_lds_dwordx4 v[238:239], off
	v_lshl_add_u64 v[238:239], s[52:53], 0, v[252:253]
	s_mov_b32 m0, s26
	s_nop 0
	global_load_lds_dwordx4 v[238:239], off
	s_waitcnt vmcnt(8)
	s_waitcnt lgkmcnt(0)
	s_barrier
	s_setprio 1
	s_waitcnt lgkmcnt(0)
	v_mfma_f32_16x16x32_bf16 v[124:127], v[144:147], v[176:179], v[124:127]
	v_mfma_f32_16x16x32_bf16 v[128:131], v[152:155], v[176:179], v[128:131]
	v_mfma_f32_16x16x32_bf16 v[112:115], v[144:147], v[194:197], v[112:115]
	v_mfma_f32_16x16x32_bf16 v[108:111], v[152:155], v[194:197], v[108:111]
	v_mfma_f32_16x16x32_bf16 v[96:99], v[144:147], v[202:205], v[96:99]
	v_mfma_f32_16x16x32_bf16 v[92:95], v[152:155], v[202:205], v[92:95]
	v_mfma_f32_16x16x32_bf16 v[80:83], v[144:147], v[220:223], v[80:83]
	v_mfma_f32_16x16x32_bf16 v[76:79], v[152:155], v[220:223], v[76:79]
	v_mfma_f32_16x16x32_bf16 v[124:127], v[148:151], v[180:183], v[124:127]
	v_mfma_f32_16x16x32_bf16 v[128:131], v[156:159], v[180:183], v[128:131]
	v_mfma_f32_16x16x32_bf16 v[112:115], v[148:151], v[198:201], v[112:115]
	v_mfma_f32_16x16x32_bf16 v[108:111], v[156:159], v[198:201], v[108:111]
	v_mfma_f32_16x16x32_bf16 v[96:99], v[148:151], v[206:209], v[96:99]
	v_mfma_f32_16x16x32_bf16 v[92:95], v[156:159], v[206:209], v[92:95]
	v_mfma_f32_16x16x32_bf16 v[80:83], v[148:151], v[224:227], v[80:83]
	v_mfma_f32_16x16x32_bf16 v[76:79], v[156:159], v[224:227], v[76:79]
	s_setprio 0
	s_setprio 1
	v_mfma_f32_16x16x32_bf16 v[120:123], v[160:163], v[176:179], v[120:123]
	v_mfma_f32_16x16x32_bf16 v[116:119], v[168:171], v[176:179], v[116:119]
	v_mfma_f32_16x16x32_bf16 v[104:107], v[160:163], v[194:197], v[104:107]
	v_mfma_f32_16x16x32_bf16 v[100:103], v[168:171], v[194:197], v[100:103]
	v_mfma_f32_16x16x32_bf16 v[88:91], v[160:163], v[202:205], v[88:91]
	v_mfma_f32_16x16x32_bf16 v[84:87], v[168:171], v[202:205], v[84:87]
	v_mfma_f32_16x16x32_bf16 v[72:75], v[160:163], v[220:223], v[72:75]
	v_mfma_f32_16x16x32_bf16 v[68:71], v[168:171], v[220:223], v[68:71]
	v_mfma_f32_16x16x32_bf16 v[120:123], v[164:167], v[180:183], v[120:123]
	v_mfma_f32_16x16x32_bf16 v[116:119], v[172:175], v[180:183], v[116:119]
	v_mfma_f32_16x16x32_bf16 v[104:107], v[164:167], v[198:201], v[104:107]
	v_mfma_f32_16x16x32_bf16 v[100:103], v[172:175], v[198:201], v[100:103]
	v_mfma_f32_16x16x32_bf16 v[88:91], v[164:167], v[206:209], v[88:91]
	v_mfma_f32_16x16x32_bf16 v[84:87], v[172:175], v[206:209], v[84:87]
	v_mfma_f32_16x16x32_bf16 v[72:75], v[164:167], v[224:227], v[72:75]
	v_mfma_f32_16x16x32_bf16 v[68:71], v[172:175], v[224:227], v[68:71]
	s_setprio 0
	s_barrier
; #define PG8_STAGE(bufoff, gbase, voff) do { _Pragma("unroll") for (int _i = 0; _i < 2; ++_i) \
;         __builtin_amdgcn_global_load_lds((const unsigned*)((const char*)(gbase) + (voff)[_i]), (PG8_LAS unsigned*)(lds + (bufoff) + ldsw + _i * 8192), 16, 0, 0); } while (0)
; #define PG8_LDA(dst, b, h) do { _Pragma("unroll") for (int m = 0; m < 4; ++m) _Pragma("unroll") for (int k = 0; k < 2; ++k) dst[m][k] = *(const PG8_LAS bf16x8*)(lds + PG8_SA(b, h) + aoff + m * 2048 + k * 1024); } while (0)
; #define PG8_MMA(ai, bj, At, Bt) do { __builtin_amdgcn_s_setprio(1); _Pragma("unroll") for (int m = 0; m < 4; ++m) _Pragma("unroll") for (int n = 0; n < 2; ++n) _Pragma("unroll") for (int k = 0; k < 2; ++k) \
;         acc[ai][bj][m][n] = __builtin_amdgcn_mfma_f32_16x16x32_bf16(Bt[n][k], At[m][k], acc[ai][bj][m][n], 0, 0, 0); __builtin_amdgcn_s_setprio(0); } while (0)
; #define PG8_WAIT_V(n) asm volatile("s_waitcnt vmcnt(" #n ")" ::: "memory")
; #define PG8_WAIT_L(n) asm volatile("s_waitcnt lgkmcnt(" #n ")" ::: "memory")
; #define PG8_BAR __builtin_amdgcn_s_barrier()
; #define PG8_SCHED __builtin_amdgcn_sched_barrier(0)
; template <class Epi, class Sched, bool ALIGN_EPI = false, bool SP2 = false>
; __device__ __forceinline__ void gemm_phase(PG8_LAS unsigned char* lds, const Gemm g, const Sched& S, const Epi& E) {
;     ...
;             PG8_LDA(At, 1, 1); PG8_STAGE(PG8_SB(1, 0), b3, voffB); PG8_STAGE(PG8_SB(1, 1), b3 + hstep, voffB); PG8_STAGE(PG8_SA(1, 0), a3, voffA);
;             PG8_WAIT_V(8); PG8_WAIT_L(0); PG8_BAR; PG8_MMA(1, 0, At, B0); PG8_MMA(1, 1, At, B1); PG8_BAR; PG8_SCHED;
	s_add_i32 s28, s28, s15
	v_lshl_add_u64 v[210:211], v[210:211], 0, s[8:9]
	s_mov_b32 m0, s28
	ds_read_b128 v[176:179], v143 offset:49152
	ds_read_b128 v[180:183], v143 offset:50176
	ds_read_b128 v[194:197], v143 offset:51200
	ds_read_b128 v[198:201], v143 offset:52224
	ds_read_b128 v[202:205], v143 offset:53248
	ds_read_b128 v[206:209], v143 offset:54272
	ds_read_b128 v[220:223], v143 offset:55296
	ds_read_b128 v[224:227], v143 offset:56320
	global_load_lds_dwordx4 v[210:211], off
	v_lshl_add_u64 v[210:211], v[228:229], 0, s[8:9]
	s_add_i32 m0, s28, 0x2000
	s_add_i32 s28, s29, s15
	global_load_lds_dwordx4 v[210:211], off
	v_lshl_add_u64 v[210:211], v[230:231], 0, s[8:9]
	s_mov_b32 m0, s28
	s_nop 0
	global_load_lds_dwordx4 v[210:211], off
	v_lshl_add_u64 v[210:211], v[232:233], 0, s[8:9]
	s_add_i32 m0, s28, 0x2000
	s_nop 0
	global_load_lds_dwordx4 v[210:211], off
	v_lshl_add_u64 v[210:211], v[234:235], 0, s[8:9]
	s_mov_b32 m0, s20
	s_nop 0
	global_load_lds_dwordx4 v[210:211], off
	v_lshl_add_u64 v[210:211], v[236:237], 0, s[8:9]
	s_mov_b32 m0, s27
	s_nop 0
	global_load_lds_dwordx4 v[210:211], off
	s_waitcnt vmcnt(8)
	s_waitcnt lgkmcnt(0)
	s_barrier
	s_setprio 1
	s_waitcnt lgkmcnt(0)
	v_mfma_f32_16x16x32_bf16 v[64:67], v[144:147], v[176:179], v[64:67]
	v_mfma_f32_16x16x32_bf16 v[60:63], v[152:155], v[176:179], v[60:63]
	v_mfma_f32_16x16x32_bf16 v[48:51], v[144:147], v[194:197], v[48:51]
	v_mfma_f32_16x16x32_bf16 v[44:47], v[152:155], v[194:197], v[44:47]
	v_mfma_f32_16x16x32_bf16 v[32:35], v[144:147], v[202:205], v[32:35]
	v_mfma_f32_16x16x32_bf16 v[28:31], v[152:155], v[202:205], v[28:31]
	v_mfma_f32_16x16x32_bf16 v[16:19], v[144:147], v[220:223], v[16:19]
	v_mfma_f32_16x16x32_bf16 v[12:15], v[152:155], v[220:223], v[12:15]
	v_mfma_f32_16x16x32_bf16 v[64:67], v[148:151], v[180:183], v[64:67]
	v_mfma_f32_16x16x32_bf16 v[60:63], v[156:159], v[180:183], v[60:63]
	v_mfma_f32_16x16x32_bf16 v[48:51], v[148:151], v[198:201], v[48:51]
	v_mfma_f32_16x16x32_bf16 v[44:47], v[156:159], v[198:201], v[44:47]
	v_mfma_f32_16x16x32_bf16 v[32:35], v[148:151], v[206:209], v[32:35]
	v_mfma_f32_16x16x32_bf16 v[28:31], v[156:159], v[206:209], v[28:31]
	v_mfma_f32_16x16x32_bf16 v[16:19], v[148:151], v[224:227], v[16:19]
	v_mfma_f32_16x16x32_bf16 v[12:15], v[156:159], v[224:227], v[12:15]
	s_setprio 0
	s_setprio 1
	v_mfma_f32_16x16x32_bf16 v[56:59], v[160:163], v[176:179], v[56:59]
	v_mfma_f32_16x16x32_bf16 v[52:55], v[168:171], v[176:179], v[52:55]
	v_mfma_f32_16x16x32_bf16 v[40:43], v[160:163], v[194:197], v[40:43]
	v_mfma_f32_16x16x32_bf16 v[36:39], v[168:171], v[194:197], v[36:39]
	v_mfma_f32_16x16x32_bf16 v[24:27], v[160:163], v[202:205], v[24:27]
	v_mfma_f32_16x16x32_bf16 v[20:23], v[168:171], v[202:205], v[20:23]
	v_mfma_f32_16x16x32_bf16 v[8:11], v[160:163], v[220:223], v[8:11]
	v_mfma_f32_16x16x32_bf16 v[4:7], v[168:171], v[220:223], v[4:7]
	v_mfma_f32_16x16x32_bf16 v[56:59], v[164:167], v[180:183], v[56:59]
	v_mfma_f32_16x16x32_bf16 v[52:55], v[172:175], v[180:183], v[52:55]
	v_mfma_f32_16x16x32_bf16 v[40:43], v[164:167], v[198:201], v[40:43]
	v_mfma_f32_16x16x32_bf16 v[36:39], v[172:175], v[198:201], v[36:39]
	v_mfma_f32_16x16x32_bf16 v[24:27], v[164:167], v[206:209], v[24:27]
	v_mfma_f32_16x16x32_bf16 v[20:23], v[172:175], v[206:209], v[20:23]
	v_mfma_f32_16x16x32_bf16 v[8:11], v[164:167], v[224:227], v[8:11]
	v_mfma_f32_16x16x32_bf16 v[4:7], v[172:175], v[224:227], v[4:7]
	s_setprio 0
	s_barrier
	s_add_u32 s69, s69, 0x100
	s_addc_u32 s70, s70, 0
	s_add_u32 s56, s56, 0x100
	s_addc_u32 s57, s57, 0
	s_cmp_ge_i32 s58, s6
	s_mov_b32 s52, s58
	s_cbranch_scc0 .LBB0_324

; #define PG8_STAGE(bufoff, gbase, voff) do { _Pragma("unroll") for (int _i = 0; _i < 2; ++_i) \
;         __builtin_amdgcn_global_load_lds((const unsigned*)((const char*)(gbase) + (voff)[_i]), (PG8_LAS unsigned*)(lds + (bufoff) + ldsw + _i * 8192), 16, 0, 0); } while (0)
; #define PG8_LDA(dst, b, h) do { _Pragma("unroll") for (int m = 0; m < 4; ++m) _Pragma("unroll") for (int k = 0; k < 2; ++k) dst[m][k] = *(const PG8_LAS bf16x8*)(lds + PG8_SA(b, h) + aoff + m * 2048 + k * 1024); } while (0)
; #define PG8_LDB(dst, b, h) do { _Pragma("unroll") for (int n = 0; n < 2; ++n) _Pragma("unroll") for (int k = 0; k < 2; ++k) dst[n][k] = *(const PG8_LAS bf16x8*)(lds + PG8_SB(b, h) + boff + n * 2048 + k * 1024); } while (0)
; #define PG8_MMA(ai, bj, At, Bt) do { __builtin_amdgcn_s_setprio(1); _Pragma("unroll") for (int m = 0; m < 4; ++m) _Pragma("unroll") for (int n = 0; n < 2; ++n) _Pragma("unroll") for (int k = 0; k < 2; ++k) \
;         acc[ai][bj][m][n] = __builtin_amdgcn_mfma_f32_16x16x32_bf16(Bt[n][k], At[m][k], acc[ai][bj][m][n], 0, 0, 0); __builtin_amdgcn_s_setprio(0); } while (0)
; #define PG8_WAIT_V(n) asm volatile("s_waitcnt vmcnt(" #n ")" ::: "memory")
; #define PG8_WAIT_L(n) asm volatile("s_waitcnt lgkmcnt(" #n ")" ::: "memory")
; template <class Epi, class Sched, bool ALIGN_EPI = false, bool SP2 = false>
; __device__ __forceinline__ void gemm_phase(PG8_LAS unsigned char* lds, const Gemm g, const Sched& S, const Epi& E) {
;     ...
;             const bool last = (t == nt - 2);
;             const char* a1 = cA + (size_t)(t + 1) * kstep;
;             const char* a2 = last ? nA : cA + (size_t)(t + 2) * kstep; const char* b2 = last ? nB : cB + (size_t)(t + 2) * kstep;
;             const char* a3 = a2 + kstep; const char* b3 = b2 + kstep;
;             if (last && has_next) S.a_ready(nxt);
;             if constexpr (SP2) {
;             PG8_LDB(B0, 0, 0); PG8_LDB(B1, 0, 1); PG8_SCHED; PG8_LDA(At, 0, 0); PG8_STAGE(PG8_SA(1, 1), a1 + hstep, voffA);
;             PG8_WAIT_V(8); PG8_WAIT_L(0); PG8_BAR; PG8_MMA(0, 0, At, B0); PG8_MMA(0, 1, At, B1); PG8_BAR; PG8_SCHED;
;             PG8_LDA(At, 0, 1); PG8_STAGE(PG8_SB(0, 0), b2, voffB); PG8_STAGE(PG8_SB(0, 1), b2 + hstep, voffB); PG8_STAGE(PG8_SA(0, 0), a2, voffA);
;             PG8_WAIT_V(8); PG8_WAIT_L(0); PG8_BAR; PG8_MMA(1, 0, At, B0); PG8_MMA(1, 1, At, B1); PG8_BAR; PG8_SCHED;
.LBB0_355:
	s_add_i32 s64, s50, 2
	s_add_u32 s28, s42, 0x80
	s_addc_u32 s29, s43, 0
	s_add_i32 s65, s33, 0x100
	s_cmp_eq_u32 s69, s50
	s_cselect_b32 s51, s61, s29
	s_cselect_b32 s50, s60, s28
	v_add_u32_e32 v2, s65, v142
	s_cselect_b32 s89, s63, s53
	s_cselect_b32 s88, s62, s20
	s_cselect_b64 s[98:99], s[40:41], 0
	s_cmp_lg_u64 s[98:99], 0
	s_cselect_b32 s98, 0, -1
	v_and_b32_e32 v246, s98, v132
	v_and_b32_e32 v247, s98, v133
	v_and_b32_e32 v248, s98, v136
	v_and_b32_e32 v249, s98, v137
	v_and_b32_e32 v250, s98, v0
	v_and_b32_e32 v251, s98, v1
	v_and_b32_e32 v252, s98, v134
	v_and_b32_e32 v253, s98, v135
	s_add_i32 s28, s21, 0x100
	ds_read_b128 v[144:147], v2
	ds_read_b128 v[148:151], v2 offset:1024
	ds_read_b128 v[152:155], v2 offset:2048
	ds_read_b128 v[156:159], v2 offset:3072
	v_add_u32_e32 v2, s28, v142
	ds_read_b128 v[160:163], v2
	ds_read_b128 v[164:167], v2 offset:1024
	ds_read_b128 v[168:171], v2 offset:2048
	ds_read_b128 v[172:175], v2 offset:3072
	v_lshl_add_u64 v[210:211], s[42:43], 0, v[140:141]
	s_add_i32 m0, s15, 0xc000
	ds_read_b128 v[176:179], v143
	ds_read_b128 v[180:183], v143 offset:1024
	ds_read_b128 v[194:197], v143 offset:2048
	ds_read_b128 v[198:201], v143 offset:3072
	ds_read_b128 v[202:205], v143 offset:4096
	ds_read_b128 v[206:209], v143 offset:5120
	ds_read_b128 v[220:223], v143 offset:6144
	ds_read_b128 v[224:227], v143 offset:7168
	global_load_lds_dwordx4 v[210:211], off
	v_lshl_add_u64 v[210:211], s[42:43], 0, v[138:139]
	s_add_i32 m0, s15, 0xe000
	s_nop 0
	global_load_lds_dwordx4 v[210:211], off
	s_waitcnt vmcnt(8)
	s_waitcnt lgkmcnt(0)
	s_barrier
	s_setprio 1
	s_waitcnt lgkmcnt(0)
	v_mfma_f32_16x16x32_bf16 v[124:127], v[144:147], v[176:179], v[124:127]
	v_mfma_f32_16x16x32_bf16 v[128:131], v[152:155], v[176:179], v[128:131]
	v_mfma_f32_16x16x32_bf16 v[112:115], v[144:147], v[194:197], v[112:115]
	v_mfma_f32_16x16x32_bf16 v[108:111], v[152:155], v[194:197], v[108:111]
	v_mfma_f32_16x16x32_bf16 v[96:99], v[144:147], v[202:205], v[96:99]
	v_mfma_f32_16x16x32_bf16 v[92:95], v[152:155], v[202:205], v[92:95]
	v_mfma_f32_16x16x32_bf16 v[80:83], v[144:147], v[220:223], v[80:83]
	v_mfma_f32_16x16x32_bf16 v[76:79], v[152:155], v[220:223], v[76:79]
	v_mfma_f32_16x16x32_bf16 v[124:127], v[148:151], v[180:183], v[124:127]
	v_mfma_f32_16x16x32_bf16 v[128:131], v[156:159], v[180:183], v[128:131]
	v_mfma_f32_16x16x32_bf16 v[112:115], v[148:151], v[198:201], v[112:115]
	v_mfma_f32_16x16x32_bf16 v[108:111], v[156:159], v[198:201], v[108:111]
	v_mfma_f32_16x16x32_bf16 v[96:99], v[148:151], v[206:209], v[96:99]
	v_mfma_f32_16x16x32_bf16 v[92:95], v[156:159], v[206:209], v[92:95]
	v_mfma_f32_16x16x32_bf16 v[80:83], v[148:151], v[224:227], v[80:83]
	v_mfma_f32_16x16x32_bf16 v[76:79], v[156:159], v[224:227], v[76:79]
	s_setprio 0
	s_setprio 1
	v_mfma_f32_16x16x32_bf16 v[120:123], v[160:163], v[176:179], v[120:123]
	v_mfma_f32_16x16x32_bf16 v[116:119], v[168:171], v[176:179], v[116:119]
	v_mfma_f32_16x16x32_bf16 v[104:107], v[160:163], v[194:197], v[104:107]
	v_mfma_f32_16x16x32_bf16 v[100:103], v[168:171], v[194:197], v[100:103]
	v_mfma_f32_16x16x32_bf16 v[88:91], v[160:163], v[202:205], v[88:91]
	v_mfma_f32_16x16x32_bf16 v[84:87], v[168:171], v[202:205], v[84:87]
	v_mfma_f32_16x16x32_bf16 v[72:75], v[160:163], v[220:223], v[72:75]
	v_mfma_f32_16x16x32_bf16 v[68:71], v[168:171], v[220:223], v[68:71]
	v_mfma_f32_16x16x32_bf16 v[120:123], v[164:167], v[180:183], v[120:123]
	v_mfma_f32_16x16x32_bf16 v[116:119], v[172:175], v[180:183], v[116:119]
	v_mfma_f32_16x16x32_bf16 v[104:107], v[164:167], v[198:201], v[104:107]
	v_mfma_f32_16x16x32_bf16 v[100:103], v[172:175], v[198:201], v[100:103]
	v_mfma_f32_16x16x32_bf16 v[88:91], v[164:167], v[206:209], v[88:91]
	v_mfma_f32_16x16x32_bf16 v[84:87], v[172:175], v[206:209], v[84:87]
	v_mfma_f32_16x16x32_bf16 v[72:75], v[164:167], v[224:227], v[72:75]
	v_mfma_f32_16x16x32_bf16 v[68:71], v[172:175], v[224:227], v[68:71]
	s_setprio 0
	s_barrier
	s_add_i32 s29, s65, s12
	v_lshl_add_u64 v[210:211], s[88:89], 0, v[246:247]
	s_mov_b32 m0, s29
	ds_read_b128 v[176:179], v143 offset:16384
	ds_read_b128 v[180:183], v143 offset:17408
	ds_read_b128 v[194:197], v143 offset:18432
	ds_read_b128 v[198:201], v143 offset:19456
	ds_read_b128 v[202:205], v143 offset:20480
	ds_read_b128 v[206:209], v143 offset:21504
	ds_read_b128 v[220:223], v143 offset:22528
	ds_read_b128 v[224:227], v143 offset:23552
	global_load_lds_dwordx4 v[210:211], off
	s_add_i32 m0, s29, 0x2000
	v_lshl_add_u64 v[228:229], s[88:89], 0, v[248:249]
	s_add_u32 s88, s88, s36
	s_addc_u32 s89, s89, s37
	s_add_i32 s28, s28, s12
	global_load_lds_dwordx4 v[228:229], off
	v_lshl_add_u64 v[230:231], s[88:89], 0, v[246:247]
	s_mov_b32 m0, s28
	v_lshl_add_u64 v[232:233], s[88:89], 0, v[248:249]
	global_load_lds_dwordx4 v[230:231], off
	s_add_i32 m0, s28, 0x2000
	v_lshl_add_u64 v[234:235], s[50:51], 0, v[250:251]
	global_load_lds_dwordx4 v[232:233], off
	s_mov_b32 m0, s15
	v_lshl_add_u64 v[236:237], s[50:51], 0, v[252:253]
	global_load_lds_dwordx4 v[234:235], off
	s_mov_b32 m0, s19
	s_nop 0
	global_load_lds_dwordx4 v[236:237], off
	s_waitcnt vmcnt(8)
	s_waitcnt lgkmcnt(0)
	s_barrier
; #define PG8_STAGE(bufoff, gbase, voff) do { _Pragma("unroll") for (int _i = 0; _i < 2; ++_i) \
;         __builtin_amdgcn_global_load_lds((const unsigned*)((const char*)(gbase) + (voff)[_i]), (PG8_LAS unsigned*)(lds + (bufoff) + ldsw + _i * 8192), 16, 0, 0); } while (0)
; #define PG8_LDA(dst, b, h) do { _Pragma("unroll") for (int m = 0; m < 4; ++m) _Pragma("unroll") for (int k = 0; k < 2; ++k) dst[m][k] = *(const PG8_LAS bf16x8*)(lds + PG8_SA(b, h) + aoff + m * 2048 + k * 1024); } while (0)
; #define PG8_LDB(dst, b, h) do { _Pragma("unroll") for (int n = 0; n < 2; ++n) _Pragma("unroll") for (int k = 0; k < 2; ++k) dst[n][k] = *(const PG8_LAS bf16x8*)(lds + PG8_SB(b, h) + boff + n * 2048 + k * 1024); } while (0)
; #define PG8_MMA(ai, bj, At, Bt) do { __builtin_amdgcn_s_setprio(1); _Pragma("unroll") for (int m = 0; m < 4; ++m) _Pragma("unroll") for (int n = 0; n < 2; ++n) _Pragma("unroll") for (int k = 0; k < 2; ++k) \
;         acc[ai][bj][m][n] = __builtin_amdgcn_mfma_f32_16x16x32_bf16(Bt[n][k], At[m][k], acc[ai][bj][m][n], 0, 0, 0); __builtin_amdgcn_s_setprio(0); } while (0)
; #define PG8_WAIT_V(n) asm volatile("s_waitcnt vmcnt(" #n ")" ::: "memory")
; #define PG8_WAIT_L(n) asm volatile("s_waitcnt lgkmcnt(" #n ")" ::: "memory")
; #define PG8_BAR __builtin_amdgcn_s_barrier()
; #define PG8_SCHED __builtin_amdgcn_sched_barrier(0)
; template <class Epi, class Sched, bool ALIGN_EPI = false, bool SP2 = false>
; __device__ __forceinline__ void gemm_phase(PG8_LAS unsigned char* lds, const Gemm g, const Sched& S, const Epi& E) {
;     ...
;             PG8_WAIT_V(8); PG8_WAIT_L(0); PG8_BAR; PG8_MMA(1, 0, At, B0); PG8_MMA(1, 1, At, B1); PG8_BAR; PG8_SCHED;
;             PG8_LDB(B0, 1, 0); PG8_LDB(B1, 1, 1); PG8_SCHED; PG8_LDA(At, 1, 0); PG8_STAGE(PG8_SA(0, 1), a2 + hstep, voffA);
;             PG8_WAIT_V(8); PG8_WAIT_L(0); PG8_BAR; PG8_MMA(0, 0, At, B0); PG8_MMA(0, 1, At, B1); PG8_BAR; PG8_SCHED;
	s_setprio 1
	s_waitcnt lgkmcnt(0)
	v_mfma_f32_16x16x32_bf16 v[64:67], v[144:147], v[176:179], v[64:67]
	v_mfma_f32_16x16x32_bf16 v[60:63], v[152:155], v[176:179], v[60:63]
	v_mfma_f32_16x16x32_bf16 v[48:51], v[144:147], v[194:197], v[48:51]
	v_mfma_f32_16x16x32_bf16 v[44:47], v[152:155], v[194:197], v[44:47]
	v_mfma_f32_16x16x32_bf16 v[32:35], v[144:147], v[202:205], v[32:35]
	v_mfma_f32_16x16x32_bf16 v[28:31], v[152:155], v[202:205], v[28:31]
	v_mfma_f32_16x16x32_bf16 v[16:19], v[144:147], v[220:223], v[16:19]
	v_mfma_f32_16x16x32_bf16 v[12:15], v[152:155], v[220:223], v[12:15]
	v_mfma_f32_16x16x32_bf16 v[64:67], v[148:151], v[180:183], v[64:67]
	v_mfma_f32_16x16x32_bf16 v[60:63], v[156:159], v[180:183], v[60:63]
	v_mfma_f32_16x16x32_bf16 v[48:51], v[148:151], v[198:201], v[48:51]
	v_mfma_f32_16x16x32_bf16 v[44:47], v[156:159], v[198:201], v[44:47]
	v_mfma_f32_16x16x32_bf16 v[32:35], v[148:151], v[206:209], v[32:35]
	v_mfma_f32_16x16x32_bf16 v[28:31], v[156:159], v[206:209], v[28:31]
	v_mfma_f32_16x16x32_bf16 v[16:19], v[148:151], v[224:227], v[16:19]
	v_mfma_f32_16x16x32_bf16 v[12:15], v[156:159], v[224:227], v[12:15]
	s_setprio 0
	s_setprio 1
	v_mfma_f32_16x16x32_bf16 v[56:59], v[160:163], v[176:179], v[56:59]
	v_mfma_f32_16x16x32_bf16 v[52:55], v[168:171], v[176:179], v[52:55]
	v_mfma_f32_16x16x32_bf16 v[40:43], v[160:163], v[194:197], v[40:43]
	v_mfma_f32_16x16x32_bf16 v[36:39], v[168:171], v[194:197], v[36:39]
	v_mfma_f32_16x16x32_bf16 v[24:27], v[160:163], v[202:205], v[24:27]
	v_mfma_f32_16x16x32_bf16 v[20:23], v[168:171], v[202:205], v[20:23]
	v_mfma_f32_16x16x32_bf16 v[8:11], v[160:163], v[220:223], v[8:11]
	v_mfma_f32_16x16x32_bf16 v[4:7], v[168:171], v[220:223], v[4:7]
	v_mfma_f32_16x16x32_bf16 v[56:59], v[164:167], v[180:183], v[56:59]
	v_mfma_f32_16x16x32_bf16 v[52:55], v[172:175], v[180:183], v[52:55]
	v_mfma_f32_16x16x32_bf16 v[40:43], v[164:167], v[198:201], v[40:43]
	v_mfma_f32_16x16x32_bf16 v[36:39], v[172:175], v[198:201], v[36:39]
	v_mfma_f32_16x16x32_bf16 v[24:27], v[164:167], v[206:209], v[24:27]
	v_mfma_f32_16x16x32_bf16 v[20:23], v[172:175], v[206:209], v[20:23]
	v_mfma_f32_16x16x32_bf16 v[8:11], v[164:167], v[224:227], v[8:11]
	v_mfma_f32_16x16x32_bf16 v[4:7], v[172:175], v[224:227], v[4:7]
	s_setprio 0
	s_barrier
	s_add_i32 s28, s82, 0x100
	v_add_u32_e32 v2, s28, v142
	s_add_i32 s29, s78, 0x100
	ds_read_b128 v[144:147], v2
	ds_read_b128 v[148:151], v2 offset:1024
	ds_read_b128 v[152:155], v2 offset:2048
	ds_read_b128 v[156:159], v2 offset:3072
	v_add_u32_e32 v2, s29, v142
	ds_read_b128 v[160:163], v2
	ds_read_b128 v[164:167], v2 offset:1024
	ds_read_b128 v[168:171], v2 offset:2048
	ds_read_b128 v[172:175], v2 offset:3072
	s_add_u32 s50, s50, s36
	s_addc_u32 s51, s51, s37
	s_mov_b32 m0, s23
	v_lshl_add_u64 v[238:239], s[50:51], 0, v[250:251]
	ds_read_b128 v[176:179], v143 offset:32768
	ds_read_b128 v[180:183], v143 offset:33792
	ds_read_b128 v[194:197], v143 offset:34816
	ds_read_b128 v[198:201], v143 offset:35840
	ds_read_b128 v[202:205], v143 offset:36864
	ds_read_b128 v[206:209], v143 offset:37888
	ds_read_b128 v[220:223], v143 offset:38912
	ds_read_b128 v[224:227], v143 offset:39936
	global_load_lds_dwordx4 v[238:239], off
	v_lshl_add_u64 v[238:239], s[50:51], 0, v[252:253]
	s_mov_b32 m0, s25
	s_nop 0
	global_load_lds_dwordx4 v[238:239], off
	s_waitcnt vmcnt(8)
	s_waitcnt lgkmcnt(0)
	s_barrier
	s_setprio 1
	s_waitcnt lgkmcnt(0)
	v_mfma_f32_16x16x32_bf16 v[124:127], v[144:147], v[176:179], v[124:127]
	v_mfma_f32_16x16x32_bf16 v[128:131], v[152:155], v[176:179], v[128:131]
	v_mfma_f32_16x16x32_bf16 v[112:115], v[144:147], v[194:197], v[112:115]
	v_mfma_f32_16x16x32_bf16 v[108:111], v[152:155], v[194:197], v[108:111]
	v_mfma_f32_16x16x32_bf16 v[96:99], v[144:147], v[202:205], v[96:99]
	v_mfma_f32_16x16x32_bf16 v[92:95], v[152:155], v[202:205], v[92:95]
	v_mfma_f32_16x16x32_bf16 v[80:83], v[144:147], v[220:223], v[80:83]
	v_mfma_f32_16x16x32_bf16 v[76:79], v[152:155], v[220:223], v[76:79]
	v_mfma_f32_16x16x32_bf16 v[124:127], v[148:151], v[180:183], v[124:127]
	v_mfma_f32_16x16x32_bf16 v[128:131], v[156:159], v[180:183], v[128:131]
	v_mfma_f32_16x16x32_bf16 v[112:115], v[148:151], v[198:201], v[112:115]
	v_mfma_f32_16x16x32_bf16 v[108:111], v[156:159], v[198:201], v[108:111]
	v_mfma_f32_16x16x32_bf16 v[96:99], v[148:151], v[206:209], v[96:99]
	v_mfma_f32_16x16x32_bf16 v[92:95], v[156:159], v[206:209], v[92:95]
	v_mfma_f32_16x16x32_bf16 v[80:83], v[148:151], v[224:227], v[80:83]
	v_mfma_f32_16x16x32_bf16 v[76:79], v[156:159], v[224:227], v[76:79]
	s_setprio 0
	s_setprio 1
	v_mfma_f32_16x16x32_bf16 v[120:123], v[160:163], v[176:179], v[120:123]
	v_mfma_f32_16x16x32_bf16 v[116:119], v[168:171], v[176:179], v[116:119]
	v_mfma_f32_16x16x32_bf16 v[104:107], v[160:163], v[194:197], v[104:107]
	v_mfma_f32_16x16x32_bf16 v[100:103], v[168:171], v[194:197], v[100:103]
	v_mfma_f32_16x16x32_bf16 v[88:91], v[160:163], v[202:205], v[88:91]
	v_mfma_f32_16x16x32_bf16 v[84:87], v[168:171], v[202:205], v[84:87]
	v_mfma_f32_16x16x32_bf16 v[72:75], v[160:163], v[220:223], v[72:75]
	v_mfma_f32_16x16x32_bf16 v[68:71], v[168:171], v[220:223], v[68:71]
	v_mfma_f32_16x16x32_bf16 v[120:123], v[164:167], v[180:183], v[120:123]
	v_mfma_f32_16x16x32_bf16 v[116:119], v[172:175], v[180:183], v[116:119]
	v_mfma_f32_16x16x32_bf16 v[104:107], v[164:167], v[198:201], v[104:107]
	v_mfma_f32_16x16x32_bf16 v[100:103], v[172:175], v[198:201], v[100:103]
	v_mfma_f32_16x16x32_bf16 v[88:91], v[164:167], v[206:209], v[88:91]
	v_mfma_f32_16x16x32_bf16 v[84:87], v[172:175], v[206:209], v[84:87]
	v_mfma_f32_16x16x32_bf16 v[72:75], v[164:167], v[224:227], v[72:75]
	v_mfma_f32_16x16x32_bf16 v[68:71], v[172:175], v[224:227], v[68:71]
	s_setprio 0
	s_barrier
; #define PG8_STAGE(bufoff, gbase, voff) do { _Pragma("unroll") for (int _i = 0; _i < 2; ++_i) \
;         __builtin_amdgcn_global_load_lds((const unsigned*)((const char*)(gbase) + (voff)[_i]), (PG8_LAS unsigned*)(lds + (bufoff) + ldsw + _i * 8192), 16, 0, 0); } while (0)
; #define PG8_LDA(dst, b, h) do { _Pragma("unroll") for (int m = 0; m < 4; ++m) _Pragma("unroll") for (int k = 0; k < 2; ++k) dst[m][k] = *(const PG8_LAS bf16x8*)(lds + PG8_SA(b, h) + aoff + m * 2048 + k * 1024); } while (0)
; #define PG8_MMA(ai, bj, At, Bt) do { __builtin_amdgcn_s_setprio(1); _Pragma("unroll") for (int m = 0; m < 4; ++m) _Pragma("unroll") for (int n = 0; n < 2; ++n) _Pragma("unroll") for (int k = 0; k < 2; ++k) \
;         acc[ai][bj][m][n] = __builtin_amdgcn_mfma_f32_16x16x32_bf16(Bt[n][k], At[m][k], acc[ai][bj][m][n], 0, 0, 0); __builtin_amdgcn_s_setprio(0); } while (0)
; #define PG8_WAIT_V(n) asm volatile("s_waitcnt vmcnt(" #n ")" ::: "memory")
; #define PG8_WAIT_L(n) asm volatile("s_waitcnt lgkmcnt(" #n ")" ::: "memory")
; #define PG8_BAR __builtin_amdgcn_s_barrier()
; #define PG8_SCHED __builtin_amdgcn_sched_barrier(0)
; template <class Epi, class Sched, bool ALIGN_EPI = false, bool SP2 = false>
; __device__ __forceinline__ void gemm_phase(PG8_LAS unsigned char* lds, const Gemm g, const Sched& S, const Epi& E) {
;     ...
;             PG8_LDA(At, 1, 1); PG8_STAGE(PG8_SB(1, 0), b3, voffB); PG8_STAGE(PG8_SB(1, 1), b3 + hstep, voffB); PG8_STAGE(PG8_SA(1, 0), a3, voffA);
;             PG8_WAIT_V(8); PG8_WAIT_L(0); PG8_BAR; PG8_MMA(1, 0, At, B0); PG8_MMA(1, 1, At, B1); PG8_BAR; PG8_SCHED;
	s_add_i32 s28, s28, s12
	v_lshl_add_u64 v[210:211], v[210:211], 0, s[8:9]
	s_mov_b32 m0, s28
	ds_read_b128 v[176:179], v143 offset:49152
	ds_read_b128 v[180:183], v143 offset:50176
	ds_read_b128 v[194:197], v143 offset:51200
	ds_read_b128 v[198:201], v143 offset:52224
	ds_read_b128 v[202:205], v143 offset:53248
	ds_read_b128 v[206:209], v143 offset:54272
	ds_read_b128 v[220:223], v143 offset:55296
	ds_read_b128 v[224:227], v143 offset:56320
	global_load_lds_dwordx4 v[210:211], off
	v_lshl_add_u64 v[210:211], v[228:229], 0, s[8:9]
	s_add_i32 m0, s28, 0x2000
	s_add_i32 s28, s29, s12
	global_load_lds_dwordx4 v[210:211], off
	v_lshl_add_u64 v[210:211], v[230:231], 0, s[8:9]
	s_mov_b32 m0, s28
	s_nop 0
	global_load_lds_dwordx4 v[210:211], off
	v_lshl_add_u64 v[210:211], v[232:233], 0, s[8:9]
	s_add_i32 m0, s28, 0x2000
	s_nop 0
	global_load_lds_dwordx4 v[210:211], off
	v_lshl_add_u64 v[210:211], v[234:235], 0, s[8:9]
	s_mov_b32 m0, s26
	s_nop 0
	global_load_lds_dwordx4 v[210:211], off
	v_lshl_add_u64 v[210:211], v[236:237], 0, s[8:9]
	s_mov_b32 m0, s27
	s_nop 0
	global_load_lds_dwordx4 v[210:211], off
	s_waitcnt vmcnt(8)
	s_waitcnt lgkmcnt(0)
	s_barrier
	s_setprio 1
	s_waitcnt lgkmcnt(0)
	v_mfma_f32_16x16x32_bf16 v[64:67], v[144:147], v[176:179], v[64:67]
	v_mfma_f32_16x16x32_bf16 v[60:63], v[152:155], v[176:179], v[60:63]
	v_mfma_f32_16x16x32_bf16 v[48:51], v[144:147], v[194:197], v[48:51]
	v_mfma_f32_16x16x32_bf16 v[44:47], v[152:155], v[194:197], v[44:47]
	v_mfma_f32_16x16x32_bf16 v[32:35], v[144:147], v[202:205], v[32:35]
	v_mfma_f32_16x16x32_bf16 v[28:31], v[152:155], v[202:205], v[28:31]
	v_mfma_f32_16x16x32_bf16 v[16:19], v[144:147], v[220:223], v[16:19]
	v_mfma_f32_16x16x32_bf16 v[12:15], v[152:155], v[220:223], v[12:15]
	v_mfma_f32_16x16x32_bf16 v[64:67], v[148:151], v[180:183], v[64:67]
	v_mfma_f32_16x16x32_bf16 v[60:63], v[156:159], v[180:183], v[60:63]
	v_mfma_f32_16x16x32_bf16 v[48:51], v[148:151], v[198:201], v[48:51]
	v_mfma_f32_16x16x32_bf16 v[44:47], v[156:159], v[198:201], v[44:47]
	v_mfma_f32_16x16x32_bf16 v[32:35], v[148:151], v[206:209], v[32:35]
	v_mfma_f32_16x16x32_bf16 v[28:31], v[156:159], v[206:209], v[28:31]
	v_mfma_f32_16x16x32_bf16 v[16:19], v[148:151], v[224:227], v[16:19]
	v_mfma_f32_16x16x32_bf16 v[12:15], v[156:159], v[224:227], v[12:15]
	s_setprio 0
	s_setprio 1
	v_mfma_f32_16x16x32_bf16 v[56:59], v[160:163], v[176:179], v[56:59]
	v_mfma_f32_16x16x32_bf16 v[52:55], v[168:171], v[176:179], v[52:55]
	v_mfma_f32_16x16x32_bf16 v[40:43], v[160:163], v[194:197], v[40:43]
	v_mfma_f32_16x16x32_bf16 v[36:39], v[168:171], v[194:197], v[36:39]
	v_mfma_f32_16x16x32_bf16 v[24:27], v[160:163], v[202:205], v[24:27]
	v_mfma_f32_16x16x32_bf16 v[20:23], v[168:171], v[202:205], v[20:23]
	v_mfma_f32_16x16x32_bf16 v[8:11], v[160:163], v[220:223], v[8:11]
	v_mfma_f32_16x16x32_bf16 v[4:7], v[168:171], v[220:223], v[4:7]
	v_mfma_f32_16x16x32_bf16 v[56:59], v[164:167], v[180:183], v[56:59]
	v_mfma_f32_16x16x32_bf16 v[52:55], v[172:175], v[180:183], v[52:55]
	v_mfma_f32_16x16x32_bf16 v[40:43], v[164:167], v[198:201], v[40:43]
	v_mfma_f32_16x16x32_bf16 v[36:39], v[172:175], v[198:201], v[36:39]
	v_mfma_f32_16x16x32_bf16 v[24:27], v[164:167], v[206:209], v[24:27]
	v_mfma_f32_16x16x32_bf16 v[20:23], v[172:175], v[206:209], v[20:23]
	v_mfma_f32_16x16x32_bf16 v[8:11], v[164:167], v[224:227], v[8:11]
	v_mfma_f32_16x16x32_bf16 v[4:7], v[172:175], v[224:227], v[4:7]
	s_setprio 0
	s_barrier
	s_add_u32 s20, s20, 0x100
	s_addc_u32 s53, s53, 0
	s_add_u32 s42, s42, 0x100
	s_addc_u32 s43, s43, 0
	s_cmp_ge_i32 s64, s30
	s_mov_b32 s50, s64
	s_cbranch_scc0 .LBB0_355

; #define PG8_STAGE(bufoff, gbase, voff) do { _Pragma("unroll") for (int _i = 0; _i < 2; ++_i) \
;         __builtin_amdgcn_global_load_lds((const unsigned*)((const char*)(gbase) + (voff)[_i]), (PG8_LAS unsigned*)(lds + (bufoff) + ldsw + _i * 8192), 16, 0, 0); } while (0)
; #define PG8_LDA(dst, b, h) do { _Pragma("unroll") for (int m = 0; m < 4; ++m) _Pragma("unroll") for (int k = 0; k < 2; ++k) dst[m][k] = *(const PG8_LAS bf16x8*)(lds + PG8_SA(b, h) + aoff + m * 2048 + k * 1024); } while (0)
; #define PG8_LDB(dst, b, h) do { _Pragma("unroll") for (int n = 0; n < 2; ++n) _Pragma("unroll") for (int k = 0; k < 2; ++k) dst[n][k] = *(const PG8_LAS bf16x8*)(lds + PG8_SB(b, h) + boff + n * 2048 + k * 1024); } while (0)
; #define PG8_MMA(ai, bj, At, Bt) do { __builtin_amdgcn_s_setprio(1); _Pragma("unroll") for (int m = 0; m < 4; ++m) _Pragma("unroll") for (int n = 0; n < 2; ++n) _Pragma("unroll") for (int k = 0; k < 2; ++k) \
;         acc[ai][bj][m][n] = __builtin_amdgcn_mfma_f32_16x16x32_bf16(Bt[n][k], At[m][k], acc[ai][bj][m][n], 0, 0, 0); __builtin_amdgcn_s_setprio(0); } while (0)
; #define PG8_WAIT_V(n) asm volatile("s_waitcnt vmcnt(" #n ")" ::: "memory")
; #define PG8_WAIT_L(n) asm volatile("s_waitcnt lgkmcnt(" #n ")" ::: "memory")
; template <class Epi, class Sched, bool ALIGN_EPI = false, bool SP2 = false>
; __device__ __forceinline__ void gemm_phase(PG8_LAS unsigned char* lds, const Gemm g, const Sched& S, const Epi& E) {
;     ...
;             const bool last = (t == nt - 2);
;             const char* a1 = cA + (size_t)(t + 1) * kstep;
;             const char* a2 = last ? nA : cA + (size_t)(t + 2) * kstep; const char* b2 = last ? nB : cB + (size_t)(t + 2) * kstep;
;             const char* a3 = a2 + kstep; const char* b3 = b2 + kstep;
;             if (last && has_next) S.a_ready(nxt);
;             if constexpr (SP2) {
;             PG8_LDB(B0, 0, 0); PG8_LDB(B1, 0, 1); PG8_SCHED; PG8_LDA(At, 0, 0); PG8_STAGE(PG8_SA(1, 1), a1 + hstep, voffA);
;             PG8_WAIT_V(8); PG8_WAIT_L(0); PG8_BAR; PG8_MMA(0, 0, At, B0); PG8_MMA(0, 1, At, B1); PG8_BAR; PG8_SCHED;
;             PG8_LDA(At, 0, 1); PG8_STAGE(PG8_SB(0, 0), b2, voffB); PG8_STAGE(PG8_SB(0, 1), b2 + hstep, voffB); PG8_STAGE(PG8_SA(0, 0), a2, voffA);
;             PG8_WAIT_V(8); PG8_WAIT_L(0); PG8_BAR; PG8_MMA(1, 0, At, B0); PG8_MMA(1, 1, At, B1); PG8_BAR; PG8_SCHED;
.LBB0_448:
	s_add_i32 s62, s52, 2
	s_add_u32 s28, s60, 0x80
	s_addc_u32 s29, s61, 0
	s_add_i32 s63, s33, 0x100
	s_cmp_eq_u32 s66, s52
	s_cselect_b32 s53, s43, s29
	s_cselect_b32 s52, s42, s28
	v_add_u32_e32 v2, s63, v174
	s_cselect_b32 s89, s51, s80
	s_cselect_b32 s88, s50, s77
	s_cselect_b64 s[98:99], s[40:41], 0
	s_cmp_lg_u64 s[98:99], 0
	s_cselect_b32 s98, 0, -1
	v_and_b32_e32 v246, s98, v164
	v_and_b32_e32 v247, s98, v165
	v_and_b32_e32 v248, s98, v168
	v_and_b32_e32 v249, s98, v169
	v_and_b32_e32 v250, s98, v0
	v_and_b32_e32 v251, s98, v1
	v_and_b32_e32 v252, s98, v166
	v_and_b32_e32 v253, s98, v167
	s_add_i32 s28, s21, 0x100
	ds_read_b128 v[132:135], v2
	ds_read_b128 v[136:139], v2 offset:1024
	ds_read_b128 v[140:143], v2 offset:2048
	ds_read_b128 v[144:147], v2 offset:3072
	v_add_u32_e32 v2, s28, v174
	ds_read_b128 v[148:151], v2
	ds_read_b128 v[152:155], v2 offset:1024
	ds_read_b128 v[156:159], v2 offset:2048
	ds_read_b128 v[160:163], v2 offset:3072
	v_lshl_add_u64 v[210:211], s[60:61], 0, v[172:173]
	s_add_i32 m0, s19, 0xc000
	ds_read_b128 v[176:179], v175
	ds_read_b128 v[180:183], v175 offset:1024
	ds_read_b128 v[194:197], v175 offset:2048
	ds_read_b128 v[198:201], v175 offset:3072
	ds_read_b128 v[202:205], v175 offset:4096
	ds_read_b128 v[206:209], v175 offset:5120
	ds_read_b128 v[220:223], v175 offset:6144
	ds_read_b128 v[224:227], v175 offset:7168
	global_load_lds_dwordx4 v[210:211], off
	v_lshl_add_u64 v[210:211], s[60:61], 0, v[170:171]
	s_add_i32 m0, s19, 0xe000
	s_nop 0
	global_load_lds_dwordx4 v[210:211], off
	s_waitcnt vmcnt(8)
	s_waitcnt lgkmcnt(0)
	s_barrier
	s_setprio 1
	s_waitcnt lgkmcnt(0)
	v_mfma_f32_16x16x32_bf16 v[128:131], v[132:135], v[176:179], v[128:131]
	v_mfma_f32_16x16x32_bf16 v[124:127], v[140:143], v[176:179], v[124:127]
	v_mfma_f32_16x16x32_bf16 v[112:115], v[132:135], v[194:197], v[112:115]
	v_mfma_f32_16x16x32_bf16 v[108:111], v[140:143], v[194:197], v[108:111]
	v_mfma_f32_16x16x32_bf16 v[96:99], v[132:135], v[202:205], v[96:99]
	v_mfma_f32_16x16x32_bf16 v[92:95], v[140:143], v[202:205], v[92:95]
	v_mfma_f32_16x16x32_bf16 v[80:83], v[132:135], v[220:223], v[80:83]
	v_mfma_f32_16x16x32_bf16 v[76:79], v[140:143], v[220:223], v[76:79]
	v_mfma_f32_16x16x32_bf16 v[128:131], v[136:139], v[180:183], v[128:131]
	v_mfma_f32_16x16x32_bf16 v[124:127], v[144:147], v[180:183], v[124:127]
	v_mfma_f32_16x16x32_bf16 v[112:115], v[136:139], v[198:201], v[112:115]
	v_mfma_f32_16x16x32_bf16 v[108:111], v[144:147], v[198:201], v[108:111]
	v_mfma_f32_16x16x32_bf16 v[96:99], v[136:139], v[206:209], v[96:99]
	v_mfma_f32_16x16x32_bf16 v[92:95], v[144:147], v[206:209], v[92:95]
	v_mfma_f32_16x16x32_bf16 v[80:83], v[136:139], v[224:227], v[80:83]
	v_mfma_f32_16x16x32_bf16 v[76:79], v[144:147], v[224:227], v[76:79]
	s_setprio 0
	s_setprio 1
	v_mfma_f32_16x16x32_bf16 v[120:123], v[148:151], v[176:179], v[120:123]
	v_mfma_f32_16x16x32_bf16 v[116:119], v[156:159], v[176:179], v[116:119]
	v_mfma_f32_16x16x32_bf16 v[104:107], v[148:151], v[194:197], v[104:107]
	v_mfma_f32_16x16x32_bf16 v[100:103], v[156:159], v[194:197], v[100:103]
	v_mfma_f32_16x16x32_bf16 v[88:91], v[148:151], v[202:205], v[88:91]
	v_mfma_f32_16x16x32_bf16 v[84:87], v[156:159], v[202:205], v[84:87]
	v_mfma_f32_16x16x32_bf16 v[72:75], v[148:151], v[220:223], v[72:75]
	v_mfma_f32_16x16x32_bf16 v[68:71], v[156:159], v[220:223], v[68:71]
	v_mfma_f32_16x16x32_bf16 v[120:123], v[152:155], v[180:183], v[120:123]
	v_mfma_f32_16x16x32_bf16 v[116:119], v[160:163], v[180:183], v[116:119]
	v_mfma_f32_16x16x32_bf16 v[104:107], v[152:155], v[198:201], v[104:107]
	v_mfma_f32_16x16x32_bf16 v[100:103], v[160:163], v[198:201], v[100:103]
	v_mfma_f32_16x16x32_bf16 v[88:91], v[152:155], v[206:209], v[88:91]
	v_mfma_f32_16x16x32_bf16 v[84:87], v[160:163], v[206:209], v[84:87]
	v_mfma_f32_16x16x32_bf16 v[72:75], v[152:155], v[224:227], v[72:75]
	v_mfma_f32_16x16x32_bf16 v[68:71], v[160:163], v[224:227], v[68:71]
	s_setprio 0
	s_barrier
	s_add_i32 s29, s63, s18
	v_lshl_add_u64 v[210:211], s[88:89], 0, v[246:247]
	s_mov_b32 m0, s29
	ds_read_b128 v[176:179], v175 offset:16384
	ds_read_b128 v[180:183], v175 offset:17408
	ds_read_b128 v[194:197], v175 offset:18432
	ds_read_b128 v[198:201], v175 offset:19456
	ds_read_b128 v[202:205], v175 offset:20480
	ds_read_b128 v[206:209], v175 offset:21504
	ds_read_b128 v[220:223], v175 offset:22528
	ds_read_b128 v[224:227], v175 offset:23552
	global_load_lds_dwordx4 v[210:211], off
	s_add_i32 m0, s29, 0x2000
	v_lshl_add_u64 v[228:229], s[88:89], 0, v[248:249]
	s_add_u32 s88, s88, s36
	s_addc_u32 s89, s89, s37
	s_add_i32 s28, s28, s18
	global_load_lds_dwordx4 v[228:229], off
	v_lshl_add_u64 v[230:231], s[88:89], 0, v[246:247]
	s_mov_b32 m0, s28
	v_lshl_add_u64 v[232:233], s[88:89], 0, v[248:249]
	global_load_lds_dwordx4 v[230:231], off
	s_add_i32 m0, s28, 0x2000
	v_lshl_add_u64 v[234:235], s[52:53], 0, v[250:251]
	global_load_lds_dwordx4 v[232:233], off
	s_mov_b32 m0, s19
	v_lshl_add_u64 v[236:237], s[52:53], 0, v[252:253]
	global_load_lds_dwordx4 v[234:235], off
	s_mov_b32 m0, s23
	s_nop 0
	global_load_lds_dwordx4 v[236:237], off
	s_waitcnt vmcnt(8)
	s_waitcnt lgkmcnt(0)
	s_barrier
; #define PG8_STAGE(bufoff, gbase, voff) do { _Pragma("unroll") for (int _i = 0; _i < 2; ++_i) \
;         __builtin_amdgcn_global_load_lds((const unsigned*)((const char*)(gbase) + (voff)[_i]), (PG8_LAS unsigned*)(lds + (bufoff) + ldsw + _i * 8192), 16, 0, 0); } while (0)
; #define PG8_LDA(dst, b, h) do { _Pragma("unroll") for (int m = 0; m < 4; ++m) _Pragma("unroll") for (int k = 0; k < 2; ++k) dst[m][k] = *(const PG8_LAS bf16x8*)(lds + PG8_SA(b, h) + aoff + m * 2048 + k * 1024); } while (0)
; #define PG8_LDB(dst, b, h) do { _Pragma("unroll") for (int n = 0; n < 2; ++n) _Pragma("unroll") for (int k = 0; k < 2; ++k) dst[n][k] = *(const PG8_LAS bf16x8*)(lds + PG8_SB(b, h) + boff + n * 2048 + k * 1024); } while (0)
; #define PG8_MMA(ai, bj, At, Bt) do { __builtin_amdgcn_s_setprio(1); _Pragma("unroll") for (int m = 0; m < 4; ++m) _Pragma("unroll") for (int n = 0; n < 2; ++n) _Pragma("unroll") for (int k = 0; k < 2; ++k) \
;         acc[ai][bj][m][n] = __builtin_amdgcn_mfma_f32_16x16x32_bf16(Bt[n][k], At[m][k], acc[ai][bj][m][n], 0, 0, 0); __builtin_amdgcn_s_setprio(0); } while (0)
; #define PG8_WAIT_V(n) asm volatile("s_waitcnt vmcnt(" #n ")" ::: "memory")
; #define PG8_WAIT_L(n) asm volatile("s_waitcnt lgkmcnt(" #n ")" ::: "memory")
; #define PG8_BAR __builtin_amdgcn_s_barrier()
; #define PG8_SCHED __builtin_amdgcn_sched_barrier(0)
; template <class Epi, class Sched, bool ALIGN_EPI = false, bool SP2 = false>
; __device__ __forceinline__ void gemm_phase(PG8_LAS unsigned char* lds, const Gemm g, const Sched& S, const Epi& E) {
;     ...
;             PG8_WAIT_V(8); PG8_WAIT_L(0); PG8_BAR; PG8_MMA(1, 0, At, B0); PG8_MMA(1, 1, At, B1); PG8_BAR; PG8_SCHED;
;             PG8_LDB(B0, 1, 0); PG8_LDB(B1, 1, 1); PG8_SCHED; PG8_LDA(At, 1, 0); PG8_STAGE(PG8_SA(0, 1), a2 + hstep, voffA);
;             PG8_WAIT_V(8); PG8_WAIT_L(0); PG8_BAR; PG8_MMA(0, 0, At, B0); PG8_MMA(0, 1, At, B1); PG8_BAR; PG8_SCHED;
	s_setprio 1
	s_waitcnt lgkmcnt(0)
	v_mfma_f32_16x16x32_bf16 v[64:67], v[132:135], v[176:179], v[64:67]
	v_mfma_f32_16x16x32_bf16 v[60:63], v[140:143], v[176:179], v[60:63]
	v_mfma_f32_16x16x32_bf16 v[48:51], v[132:135], v[194:197], v[48:51]
	v_mfma_f32_16x16x32_bf16 v[44:47], v[140:143], v[194:197], v[44:47]
	v_mfma_f32_16x16x32_bf16 v[32:35], v[132:135], v[202:205], v[32:35]
	v_mfma_f32_16x16x32_bf16 v[28:31], v[140:143], v[202:205], v[28:31]
	v_mfma_f32_16x16x32_bf16 v[16:19], v[132:135], v[220:223], v[16:19]
	v_mfma_f32_16x16x32_bf16 v[12:15], v[140:143], v[220:223], v[12:15]
	v_mfma_f32_16x16x32_bf16 v[64:67], v[136:139], v[180:183], v[64:67]
	v_mfma_f32_16x16x32_bf16 v[60:63], v[144:147], v[180:183], v[60:63]
	v_mfma_f32_16x16x32_bf16 v[48:51], v[136:139], v[198:201], v[48:51]
	v_mfma_f32_16x16x32_bf16 v[44:47], v[144:147], v[198:201], v[44:47]
	v_mfma_f32_16x16x32_bf16 v[32:35], v[136:139], v[206:209], v[32:35]
	v_mfma_f32_16x16x32_bf16 v[28:31], v[144:147], v[206:209], v[28:31]
	v_mfma_f32_16x16x32_bf16 v[16:19], v[136:139], v[224:227], v[16:19]
	v_mfma_f32_16x16x32_bf16 v[12:15], v[144:147], v[224:227], v[12:15]
	s_setprio 0
	s_setprio 1
	v_mfma_f32_16x16x32_bf16 v[56:59], v[148:151], v[176:179], v[56:59]
	v_mfma_f32_16x16x32_bf16 v[52:55], v[156:159], v[176:179], v[52:55]
	v_mfma_f32_16x16x32_bf16 v[40:43], v[148:151], v[194:197], v[40:43]
	v_mfma_f32_16x16x32_bf16 v[36:39], v[156:159], v[194:197], v[36:39]
	v_mfma_f32_16x16x32_bf16 v[24:27], v[148:151], v[202:205], v[24:27]
	v_mfma_f32_16x16x32_bf16 v[20:23], v[156:159], v[202:205], v[20:23]
	v_mfma_f32_16x16x32_bf16 v[8:11], v[148:151], v[220:223], v[8:11]
	v_mfma_f32_16x16x32_bf16 v[4:7], v[156:159], v[220:223], v[4:7]
	v_mfma_f32_16x16x32_bf16 v[56:59], v[152:155], v[180:183], v[56:59]
	v_mfma_f32_16x16x32_bf16 v[52:55], v[160:163], v[180:183], v[52:55]
	v_mfma_f32_16x16x32_bf16 v[40:43], v[152:155], v[198:201], v[40:43]
	v_mfma_f32_16x16x32_bf16 v[36:39], v[160:163], v[198:201], v[36:39]
	v_mfma_f32_16x16x32_bf16 v[24:27], v[152:155], v[206:209], v[24:27]
	v_mfma_f32_16x16x32_bf16 v[20:23], v[160:163], v[206:209], v[20:23]
	v_mfma_f32_16x16x32_bf16 v[8:11], v[152:155], v[224:227], v[8:11]
	v_mfma_f32_16x16x32_bf16 v[4:7], v[160:163], v[224:227], v[4:7]
	s_setprio 0
	s_barrier
	s_add_i32 s28, s82, 0x100
	v_add_u32_e32 v2, s28, v174
	s_add_i32 s29, s78, 0x100
	ds_read_b128 v[132:135], v2
	ds_read_b128 v[136:139], v2 offset:1024
	ds_read_b128 v[140:143], v2 offset:2048
	ds_read_b128 v[144:147], v2 offset:3072
	v_add_u32_e32 v2, s29, v174
	ds_read_b128 v[148:151], v2
	ds_read_b128 v[152:155], v2 offset:1024
	ds_read_b128 v[156:159], v2 offset:2048
	ds_read_b128 v[160:163], v2 offset:3072
	s_add_u32 s52, s52, s36
	s_addc_u32 s53, s53, s37
	s_mov_b32 m0, s25
	v_lshl_add_u64 v[238:239], s[52:53], 0, v[250:251]
	ds_read_b128 v[176:179], v175 offset:32768
	ds_read_b128 v[180:183], v175 offset:33792
	ds_read_b128 v[194:197], v175 offset:34816
	ds_read_b128 v[198:201], v175 offset:35840
	ds_read_b128 v[202:205], v175 offset:36864
	ds_read_b128 v[206:209], v175 offset:37888
	ds_read_b128 v[220:223], v175 offset:38912
	ds_read_b128 v[224:227], v175 offset:39936
	global_load_lds_dwordx4 v[238:239], off
	v_lshl_add_u64 v[238:239], s[52:53], 0, v[252:253]
	s_mov_b32 m0, s26
	s_nop 0
	global_load_lds_dwordx4 v[238:239], off
	s_waitcnt vmcnt(8)
	s_waitcnt lgkmcnt(0)
	s_barrier
	s_setprio 1
	s_waitcnt lgkmcnt(0)
	v_mfma_f32_16x16x32_bf16 v[128:131], v[132:135], v[176:179], v[128:131]
	v_mfma_f32_16x16x32_bf16 v[124:127], v[140:143], v[176:179], v[124:127]
	v_mfma_f32_16x16x32_bf16 v[112:115], v[132:135], v[194:197], v[112:115]
	v_mfma_f32_16x16x32_bf16 v[108:111], v[140:143], v[194:197], v[108:111]
	v_mfma_f32_16x16x32_bf16 v[96:99], v[132:135], v[202:205], v[96:99]
	v_mfma_f32_16x16x32_bf16 v[92:95], v[140:143], v[202:205], v[92:95]
	v_mfma_f32_16x16x32_bf16 v[80:83], v[132:135], v[220:223], v[80:83]
	v_mfma_f32_16x16x32_bf16 v[76:79], v[140:143], v[220:223], v[76:79]
	v_mfma_f32_16x16x32_bf16 v[128:131], v[136:139], v[180:183], v[128:131]
	v_mfma_f32_16x16x32_bf16 v[124:127], v[144:147], v[180:183], v[124:127]
	v_mfma_f32_16x16x32_bf16 v[112:115], v[136:139], v[198:201], v[112:115]
	v_mfma_f32_16x16x32_bf16 v[108:111], v[144:147], v[198:201], v[108:111]
	v_mfma_f32_16x16x32_bf16 v[96:99], v[136:139], v[206:209], v[96:99]
	v_mfma_f32_16x16x32_bf16 v[92:95], v[144:147], v[206:209], v[92:95]
	v_mfma_f32_16x16x32_bf16 v[80:83], v[136:139], v[224:227], v[80:83]
	v_mfma_f32_16x16x32_bf16 v[76:79], v[144:147], v[224:227], v[76:79]
	s_setprio 0
	s_setprio 1
	v_mfma_f32_16x16x32_bf16 v[120:123], v[148:151], v[176:179], v[120:123]
	v_mfma_f32_16x16x32_bf16 v[116:119], v[156:159], v[176:179], v[116:119]
	v_mfma_f32_16x16x32_bf16 v[104:107], v[148:151], v[194:197], v[104:107]
	v_mfma_f32_16x16x32_bf16 v[100:103], v[156:159], v[194:197], v[100:103]
	v_mfma_f32_16x16x32_bf16 v[88:91], v[148:151], v[202:205], v[88:91]
	v_mfma_f32_16x16x32_bf16 v[84:87], v[156:159], v[202:205], v[84:87]
	v_mfma_f32_16x16x32_bf16 v[72:75], v[148:151], v[220:223], v[72:75]
	v_mfma_f32_16x16x32_bf16 v[68:71], v[156:159], v[220:223], v[68:71]
	v_mfma_f32_16x16x32_bf16 v[120:123], v[152:155], v[180:183], v[120:123]
	v_mfma_f32_16x16x32_bf16 v[116:119], v[160:163], v[180:183], v[116:119]
	v_mfma_f32_16x16x32_bf16 v[104:107], v[152:155], v[198:201], v[104:107]
	v_mfma_f32_16x16x32_bf16 v[100:103], v[160:163], v[198:201], v[100:103]
	v_mfma_f32_16x16x32_bf16 v[88:91], v[152:155], v[206:209], v[88:91]
	v_mfma_f32_16x16x32_bf16 v[84:87], v[160:163], v[206:209], v[84:87]
	v_mfma_f32_16x16x32_bf16 v[72:75], v[152:155], v[224:227], v[72:75]
	v_mfma_f32_16x16x32_bf16 v[68:71], v[160:163], v[224:227], v[68:71]
	s_setprio 0
	s_barrier
; #define PG8_STAGE(bufoff, gbase, voff) do { _Pragma("unroll") for (int _i = 0; _i < 2; ++_i) \
;         __builtin_amdgcn_global_load_lds((const unsigned*)((const char*)(gbase) + (voff)[_i]), (PG8_LAS unsigned*)(lds + (bufoff) + ldsw + _i * 8192), 16, 0, 0); } while (0)
; #define PG8_LDA(dst, b, h) do { _Pragma("unroll") for (int m = 0; m < 4; ++m) _Pragma("unroll") for (int k = 0; k < 2; ++k) dst[m][k] = *(const PG8_LAS bf16x8*)(lds + PG8_SA(b, h) + aoff + m * 2048 + k * 1024); } while (0)
; #define PG8_MMA(ai, bj, At, Bt) do { __builtin_amdgcn_s_setprio(1); _Pragma("unroll") for (int m = 0; m < 4; ++m) _Pragma("unroll") for (int n = 0; n < 2; ++n) _Pragma("unroll") for (int k = 0; k < 2; ++k) \
;         acc[ai][bj][m][n] = __builtin_amdgcn_mfma_f32_16x16x32_bf16(Bt[n][k], At[m][k], acc[ai][bj][m][n], 0, 0, 0); __builtin_amdgcn_s_setprio(0); } while (0)
; #define PG8_WAIT_V(n) asm volatile("s_waitcnt vmcnt(" #n ")" ::: "memory")
; #define PG8_WAIT_L(n) asm volatile("s_waitcnt lgkmcnt(" #n ")" ::: "memory")
; #define PG8_BAR __builtin_amdgcn_s_barrier()
; #define PG8_SCHED __builtin_amdgcn_sched_barrier(0)
; template <class Epi, class Sched, bool ALIGN_EPI = false, bool SP2 = false>
; __device__ __forceinline__ void gemm_phase(PG8_LAS unsigned char* lds, const Gemm g, const Sched& S, const Epi& E) {
;     ...
;             PG8_LDA(At, 1, 1); PG8_STAGE(PG8_SB(1, 0), b3, voffB); PG8_STAGE(PG8_SB(1, 1), b3 + hstep, voffB); PG8_STAGE(PG8_SA(1, 0), a3, voffA);
;             PG8_WAIT_V(8); PG8_WAIT_L(0); PG8_BAR; PG8_MMA(1, 0, At, B0); PG8_MMA(1, 1, At, B1); PG8_BAR; PG8_SCHED;
	s_add_i32 s28, s28, s18
	v_lshl_add_u64 v[210:211], v[210:211], 0, s[8:9]
	s_mov_b32 m0, s28
	ds_read_b128 v[176:179], v175 offset:49152
	ds_read_b128 v[180:183], v175 offset:50176
	ds_read_b128 v[194:197], v175 offset:51200
	ds_read_b128 v[198:201], v175 offset:52224
	ds_read_b128 v[202:205], v175 offset:53248
	ds_read_b128 v[206:209], v175 offset:54272
	ds_read_b128 v[220:223], v175 offset:55296
	ds_read_b128 v[224:227], v175 offset:56320
	global_load_lds_dwordx4 v[210:211], off
	v_lshl_add_u64 v[210:211], v[228:229], 0, s[8:9]
	s_add_i32 m0, s28, 0x2000
	s_add_i32 s28, s29, s18
	global_load_lds_dwordx4 v[210:211], off
	v_lshl_add_u64 v[210:211], v[230:231], 0, s[8:9]
	s_mov_b32 m0, s28
	s_nop 0
	global_load_lds_dwordx4 v[210:211], off
	v_lshl_add_u64 v[210:211], v[232:233], 0, s[8:9]
	s_add_i32 m0, s28, 0x2000
	s_nop 0
	global_load_lds_dwordx4 v[210:211], off
	v_lshl_add_u64 v[210:211], v[234:235], 0, s[8:9]
	s_mov_b32 m0, s64
	s_nop 0
	global_load_lds_dwordx4 v[210:211], off
	v_lshl_add_u64 v[210:211], v[236:237], 0, s[8:9]
	s_mov_b32 m0, s65
	s_nop 0
	global_load_lds_dwordx4 v[210:211], off
	s_waitcnt vmcnt(8)
	s_waitcnt lgkmcnt(0)
	s_barrier
	s_setprio 1
	s_waitcnt lgkmcnt(0)
	v_mfma_f32_16x16x32_bf16 v[64:67], v[132:135], v[176:179], v[64:67]
	v_mfma_f32_16x16x32_bf16 v[60:63], v[140:143], v[176:179], v[60:63]
	v_mfma_f32_16x16x32_bf16 v[48:51], v[132:135], v[194:197], v[48:51]
	v_mfma_f32_16x16x32_bf16 v[44:47], v[140:143], v[194:197], v[44:47]
	v_mfma_f32_16x16x32_bf16 v[32:35], v[132:135], v[202:205], v[32:35]
	v_mfma_f32_16x16x32_bf16 v[28:31], v[140:143], v[202:205], v[28:31]
	v_mfma_f32_16x16x32_bf16 v[16:19], v[132:135], v[220:223], v[16:19]
	v_mfma_f32_16x16x32_bf16 v[12:15], v[140:143], v[220:223], v[12:15]
	v_mfma_f32_16x16x32_bf16 v[64:67], v[136:139], v[180:183], v[64:67]
	v_mfma_f32_16x16x32_bf16 v[60:63], v[144:147], v[180:183], v[60:63]
	v_mfma_f32_16x16x32_bf16 v[48:51], v[136:139], v[198:201], v[48:51]
	v_mfma_f32_16x16x32_bf16 v[44:47], v[144:147], v[198:201], v[44:47]
	v_mfma_f32_16x16x32_bf16 v[32:35], v[136:139], v[206:209], v[32:35]
	v_mfma_f32_16x16x32_bf16 v[28:31], v[144:147], v[206:209], v[28:31]
	v_mfma_f32_16x16x32_bf16 v[16:19], v[136:139], v[224:227], v[16:19]
	v_mfma_f32_16x16x32_bf16 v[12:15], v[144:147], v[224:227], v[12:15]
	s_setprio 0
	s_setprio 1
	v_mfma_f32_16x16x32_bf16 v[56:59], v[148:151], v[176:179], v[56:59]
	v_mfma_f32_16x16x32_bf16 v[52:55], v[156:159], v[176:179], v[52:55]
	v_mfma_f32_16x16x32_bf16 v[40:43], v[148:151], v[194:197], v[40:43]
	v_mfma_f32_16x16x32_bf16 v[36:39], v[156:159], v[194:197], v[36:39]
	v_mfma_f32_16x16x32_bf16 v[24:27], v[148:151], v[202:205], v[24:27]
	v_mfma_f32_16x16x32_bf16 v[20:23], v[156:159], v[202:205], v[20:23]
	v_mfma_f32_16x16x32_bf16 v[8:11], v[148:151], v[220:223], v[8:11]
	v_mfma_f32_16x16x32_bf16 v[4:7], v[156:159], v[220:223], v[4:7]
	v_mfma_f32_16x16x32_bf16 v[56:59], v[152:155], v[180:183], v[56:59]
	v_mfma_f32_16x16x32_bf16 v[52:55], v[160:163], v[180:183], v[52:55]
	v_mfma_f32_16x16x32_bf16 v[40:43], v[152:155], v[198:201], v[40:43]
	v_mfma_f32_16x16x32_bf16 v[36:39], v[160:163], v[198:201], v[36:39]
	v_mfma_f32_16x16x32_bf16 v[24:27], v[152:155], v[206:209], v[24:27]
	v_mfma_f32_16x16x32_bf16 v[20:23], v[160:163], v[206:209], v[20:23]
	v_mfma_f32_16x16x32_bf16 v[8:11], v[152:155], v[224:227], v[8:11]
	v_mfma_f32_16x16x32_bf16 v[4:7], v[160:163], v[224:227], v[4:7]
	s_setprio 0
	s_barrier
	s_add_u32 s77, s77, 0x100
	s_addc_u32 s80, s80, 0
	s_add_u32 s60, s60, 0x100
	s_addc_u32 s61, s61, 0
	s_cmp_ge_i32 s62, s6
	s_mov_b32 s52, s62
	s_cbranch_scc0 .LBB0_448

; #define PG8_STAGE(bufoff, gbase, voff) do { _Pragma("unroll") for (int _i = 0; _i < 2; ++_i) \
;         __builtin_amdgcn_global_load_lds((const unsigned*)((const char*)(gbase) + (voff)[_i]), (PG8_LAS unsigned*)(lds + (bufoff) + ldsw + _i * 8192), 16, 0, 0); } while (0)
; #define PG8_LDA(dst, b, h) do { _Pragma("unroll") for (int m = 0; m < 4; ++m) _Pragma("unroll") for (int k = 0; k < 2; ++k) dst[m][k] = *(const PG8_LAS bf16x8*)(lds + PG8_SA(b, h) + aoff + m * 2048 + k * 1024); } while (0)
; #define PG8_LDB(dst, b, h) do { _Pragma("unroll") for (int n = 0; n < 2; ++n) _Pragma("unroll") for (int k = 0; k < 2; ++k) dst[n][k] = *(const PG8_LAS bf16x8*)(lds + PG8_SB(b, h) + boff + n * 2048 + k * 1024); } while (0)
; #define PG8_MMA(ai, bj, At, Bt) do { __builtin_amdgcn_s_setprio(1); _Pragma("unroll") for (int m = 0; m < 4; ++m) _Pragma("unroll") for (int n = 0; n < 2; ++n) _Pragma("unroll") for (int k = 0; k < 2; ++k) \
;         acc[ai][bj][m][n] = __builtin_amdgcn_mfma_f32_16x16x32_bf16(Bt[n][k], At[m][k], acc[ai][bj][m][n], 0, 0, 0); __builtin_amdgcn_s_setprio(0); } while (0)
; #define PG8_WAIT_V(n) asm volatile("s_waitcnt vmcnt(" #n ")" ::: "memory")
; #define PG8_WAIT_L(n) asm volatile("s_waitcnt lgkmcnt(" #n ")" ::: "memory")
; template <class Epi, class Sched, bool ALIGN_EPI = false, bool SP2 = false>
; __device__ __forceinline__ void gemm_phase(PG8_LAS unsigned char* lds, const Gemm g, const Sched& S, const Epi& E) {
;     ...
;             const bool last = (t == nt - 2);
;             const char* a1 = cA + (size_t)(t + 1) * kstep;
;             const char* a2 = last ? nA : cA + (size_t)(t + 2) * kstep; const char* b2 = last ? nB : cB + (size_t)(t + 2) * kstep;
;             const char* a3 = a2 + kstep; const char* b3 = b2 + kstep;
;             if (last && has_next) S.a_ready(nxt);
;             if constexpr (SP2) {
;             PG8_LDB(B0, 0, 0); PG8_LDB(B1, 0, 1); PG8_SCHED; PG8_LDA(At, 0, 0); PG8_STAGE(PG8_SA(1, 1), a1 + hstep, voffA);
;             PG8_WAIT_V(8); PG8_WAIT_L(0); PG8_BAR; PG8_MMA(0, 0, At, B0); PG8_MMA(0, 1, At, B1); PG8_BAR; PG8_SCHED;
;             PG8_LDA(At, 0, 1); PG8_STAGE(PG8_SB(0, 0), b2, voffB); PG8_STAGE(PG8_SB(0, 1), b2 + hstep, voffB); PG8_STAGE(PG8_SA(0, 0), a2, voffA);
;             PG8_WAIT_V(8); PG8_WAIT_L(0); PG8_BAR; PG8_MMA(1, 0, At, B0); PG8_MMA(1, 1, At, B1); PG8_BAR; PG8_SCHED;
.LBB0_489:
	s_add_i32 s27, s26, 2
	s_add_u32 s28, s38, 0x80
	s_addc_u32 s29, s39, 0
	s_add_i32 s66, s33, 0x100
	s_cmp_eq_u32 s95, s26
	s_cselect_b32 s51, s43, s29
	s_cselect_b32 s50, s42, s28
	v_add_u32_e32 v2, s66, v149
	s_cselect_b32 s53, s65, s20
	s_cselect_b32 s52, s64, s4
	s_cselect_b64 s[98:99], s[40:41], 0
	s_cmp_lg_u64 s[98:99], 0
	s_cselect_b32 s98, 0, -1
	v_and_b32_e32 v246, s98, v134
	v_and_b32_e32 v247, s98, v135
	v_and_b32_e32 v248, s98, v0
	v_and_b32_e32 v249, s98, v1
	v_and_b32_e32 v250, s98, v136
	v_and_b32_e32 v251, s98, v137
	v_and_b32_e32 v252, s98, v132
	v_and_b32_e32 v253, s98, v133
	s_add_i32 s26, s21, 0x100
	ds_read_b128 v[142:145], v2
	ds_read_b128 v[154:157], v2 offset:1024
	ds_read_b128 v[158:161], v2 offset:2048
	ds_read_b128 v[162:165], v2 offset:3072
	v_add_u32_e32 v2, s26, v149
	ds_read_b128 v[166:169], v2
	ds_read_b128 v[170:173], v2 offset:1024
	ds_read_b128 v[174:177], v2 offset:2048
	ds_read_b128 v[178:181], v2 offset:3072
	v_lshl_add_u64 v[146:147], s[38:39], 0, v[140:141]
	s_add_i32 m0, s87, 0xc000
	ds_read_b128 v[194:197], v152
	ds_read_b128 v[198:201], v152 offset:1024
	ds_read_b128 v[202:205], v152 offset:2048
	ds_read_b128 v[206:209], v152 offset:3072
	ds_read_b128 v[220:223], v152 offset:4096
	ds_read_b128 v[224:227], v152 offset:5120
	ds_read_b128 v[228:231], v152 offset:6144
	ds_read_b128 v[232:235], v152 offset:7168
	global_load_lds_dwordx4 v[146:147], off
	v_lshl_add_u64 v[146:147], s[38:39], 0, v[138:139]
	s_add_i32 m0, s87, 0xe000
	s_nop 0
	global_load_lds_dwordx4 v[146:147], off
	s_waitcnt vmcnt(8)
	s_waitcnt lgkmcnt(0)
	s_barrier
	s_setprio 1
	s_waitcnt lgkmcnt(0)
	v_mfma_f32_16x16x32_bf16 v[128:131], v[142:145], v[194:197], v[128:131]
	v_mfma_f32_16x16x32_bf16 v[124:127], v[158:161], v[194:197], v[124:127]
	v_mfma_f32_16x16x32_bf16 v[112:115], v[142:145], v[202:205], v[112:115]
	v_mfma_f32_16x16x32_bf16 v[108:111], v[158:161], v[202:205], v[108:111]
	v_mfma_f32_16x16x32_bf16 v[96:99], v[142:145], v[220:223], v[96:99]
	v_mfma_f32_16x16x32_bf16 v[92:95], v[158:161], v[220:223], v[92:95]
	v_mfma_f32_16x16x32_bf16 v[80:83], v[142:145], v[228:231], v[80:83]
	v_mfma_f32_16x16x32_bf16 v[76:79], v[158:161], v[228:231], v[76:79]
	v_mfma_f32_16x16x32_bf16 v[128:131], v[154:157], v[198:201], v[128:131]
	v_mfma_f32_16x16x32_bf16 v[124:127], v[162:165], v[198:201], v[124:127]
	v_mfma_f32_16x16x32_bf16 v[112:115], v[154:157], v[206:209], v[112:115]
	v_mfma_f32_16x16x32_bf16 v[108:111], v[162:165], v[206:209], v[108:111]
	v_mfma_f32_16x16x32_bf16 v[96:99], v[154:157], v[224:227], v[96:99]
	v_mfma_f32_16x16x32_bf16 v[92:95], v[162:165], v[224:227], v[92:95]
	v_mfma_f32_16x16x32_bf16 v[80:83], v[154:157], v[232:235], v[80:83]
	v_mfma_f32_16x16x32_bf16 v[76:79], v[162:165], v[232:235], v[76:79]
	s_setprio 0
	s_setprio 1
	v_mfma_f32_16x16x32_bf16 v[120:123], v[166:169], v[194:197], v[120:123]
	v_mfma_f32_16x16x32_bf16 v[116:119], v[174:177], v[194:197], v[116:119]
	v_mfma_f32_16x16x32_bf16 v[104:107], v[166:169], v[202:205], v[104:107]
	v_mfma_f32_16x16x32_bf16 v[100:103], v[174:177], v[202:205], v[100:103]
	v_mfma_f32_16x16x32_bf16 v[88:91], v[166:169], v[220:223], v[88:91]
	v_mfma_f32_16x16x32_bf16 v[84:87], v[174:177], v[220:223], v[84:87]
	v_mfma_f32_16x16x32_bf16 v[72:75], v[166:169], v[228:231], v[72:75]
	v_mfma_f32_16x16x32_bf16 v[68:71], v[174:177], v[228:231], v[68:71]
	v_mfma_f32_16x16x32_bf16 v[120:123], v[170:173], v[198:201], v[120:123]
	v_mfma_f32_16x16x32_bf16 v[116:119], v[178:181], v[198:201], v[116:119]
	v_mfma_f32_16x16x32_bf16 v[104:107], v[170:173], v[206:209], v[104:107]
	v_mfma_f32_16x16x32_bf16 v[100:103], v[178:181], v[206:209], v[100:103]
	v_mfma_f32_16x16x32_bf16 v[88:91], v[170:173], v[224:227], v[88:91]
	v_mfma_f32_16x16x32_bf16 v[84:87], v[178:181], v[224:227], v[84:87]
	v_mfma_f32_16x16x32_bf16 v[72:75], v[170:173], v[232:235], v[72:75]
	v_mfma_f32_16x16x32_bf16 v[68:71], v[178:181], v[232:235], v[68:71]
	s_setprio 0
	s_barrier
	s_add_i32 s28, s66, s25
	v_lshl_add_u64 v[146:147], s[52:53], 0, v[246:247]
	s_mov_b32 m0, s28
	ds_read_b128 v[194:197], v152 offset:16384
	ds_read_b128 v[198:201], v152 offset:17408
	ds_read_b128 v[202:205], v152 offset:18432
	ds_read_b128 v[206:209], v152 offset:19456
	ds_read_b128 v[220:223], v152 offset:20480
	ds_read_b128 v[224:227], v152 offset:21504
	ds_read_b128 v[228:231], v152 offset:22528
	ds_read_b128 v[232:235], v152 offset:23552
	global_load_lds_dwordx4 v[146:147], off
	s_add_i32 m0, s28, 0x2000
	v_lshl_add_u64 v[150:151], s[52:53], 0, v[248:249]
	s_add_u32 s52, s52, s36
	s_addc_u32 s53, s53, s37
	s_add_i32 s26, s26, s25
	global_load_lds_dwordx4 v[150:151], off
	v_lshl_add_u64 v[182:183], s[52:53], 0, v[246:247]
	s_mov_b32 m0, s26
	v_lshl_add_u64 v[210:211], s[52:53], 0, v[248:249]
	global_load_lds_dwordx4 v[182:183], off
	s_add_i32 m0, s26, 0x2000
	v_lshl_add_u64 v[236:237], s[50:51], 0, v[250:251]
	global_load_lds_dwordx4 v[210:211], off
	s_mov_b32 m0, s87
	v_lshl_add_u64 v[238:239], s[50:51], 0, v[252:253]
	global_load_lds_dwordx4 v[236:237], off
	s_mov_b32 m0, s88
	s_nop 0
	global_load_lds_dwordx4 v[238:239], off
	s_waitcnt vmcnt(8)
	s_waitcnt lgkmcnt(0)
	s_barrier
; #define PG8_STAGE(bufoff, gbase, voff) do { _Pragma("unroll") for (int _i = 0; _i < 2; ++_i) \
;         __builtin_amdgcn_global_load_lds((const unsigned*)((const char*)(gbase) + (voff)[_i]), (PG8_LAS unsigned*)(lds + (bufoff) + ldsw + _i * 8192), 16, 0, 0); } while (0)
; #define PG8_LDA(dst, b, h) do { _Pragma("unroll") for (int m = 0; m < 4; ++m) _Pragma("unroll") for (int k = 0; k < 2; ++k) dst[m][k] = *(const PG8_LAS bf16x8*)(lds + PG8_SA(b, h) + aoff + m * 2048 + k * 1024); } while (0)
; #define PG8_LDB(dst, b, h) do { _Pragma("unroll") for (int n = 0; n < 2; ++n) _Pragma("unroll") for (int k = 0; k < 2; ++k) dst[n][k] = *(const PG8_LAS bf16x8*)(lds + PG8_SB(b, h) + boff + n * 2048 + k * 1024); } while (0)
; #define PG8_MMA(ai, bj, At, Bt) do { __builtin_amdgcn_s_setprio(1); _Pragma("unroll") for (int m = 0; m < 4; ++m) _Pragma("unroll") for (int n = 0; n < 2; ++n) _Pragma("unroll") for (int k = 0; k < 2; ++k) \
;         acc[ai][bj][m][n] = __builtin_amdgcn_mfma_f32_16x16x32_bf16(Bt[n][k], At[m][k], acc[ai][bj][m][n], 0, 0, 0); __builtin_amdgcn_s_setprio(0); } while (0)
; #define PG8_WAIT_V(n) asm volatile("s_waitcnt vmcnt(" #n ")" ::: "memory")
; #define PG8_WAIT_L(n) asm volatile("s_waitcnt lgkmcnt(" #n ")" ::: "memory")
; #define PG8_BAR __builtin_amdgcn_s_barrier()
; #define PG8_SCHED __builtin_amdgcn_sched_barrier(0)
; template <class Epi, class Sched, bool ALIGN_EPI = false, bool SP2 = false>
; __device__ __forceinline__ void gemm_phase(PG8_LAS unsigned char* lds, const Gemm g, const Sched& S, const Epi& E) {
;     ...
;             PG8_WAIT_V(8); PG8_WAIT_L(0); PG8_BAR; PG8_MMA(1, 0, At, B0); PG8_MMA(1, 1, At, B1); PG8_BAR; PG8_SCHED;
;             PG8_LDB(B0, 1, 0); PG8_LDB(B1, 1, 1); PG8_SCHED; PG8_LDA(At, 1, 0); PG8_STAGE(PG8_SA(0, 1), a2 + hstep, voffA);
;             PG8_WAIT_V(8); PG8_WAIT_L(0); PG8_BAR; PG8_MMA(0, 0, At, B0); PG8_MMA(0, 1, At, B1); PG8_BAR; PG8_SCHED;
	s_setprio 1
	s_waitcnt lgkmcnt(0)
	v_mfma_f32_16x16x32_bf16 v[64:67], v[142:145], v[194:197], v[64:67]
	v_mfma_f32_16x16x32_bf16 v[60:63], v[158:161], v[194:197], v[60:63]
	v_mfma_f32_16x16x32_bf16 v[48:51], v[142:145], v[202:205], v[48:51]
	v_mfma_f32_16x16x32_bf16 v[44:47], v[158:161], v[202:205], v[44:47]
	v_mfma_f32_16x16x32_bf16 v[32:35], v[142:145], v[220:223], v[32:35]
	v_mfma_f32_16x16x32_bf16 v[28:31], v[158:161], v[220:223], v[28:31]
	v_mfma_f32_16x16x32_bf16 v[16:19], v[142:145], v[228:231], v[16:19]
	v_mfma_f32_16x16x32_bf16 v[12:15], v[158:161], v[228:231], v[12:15]
	v_mfma_f32_16x16x32_bf16 v[64:67], v[154:157], v[198:201], v[64:67]
	v_mfma_f32_16x16x32_bf16 v[60:63], v[162:165], v[198:201], v[60:63]
	v_mfma_f32_16x16x32_bf16 v[48:51], v[154:157], v[206:209], v[48:51]
	v_mfma_f32_16x16x32_bf16 v[44:47], v[162:165], v[206:209], v[44:47]
	v_mfma_f32_16x16x32_bf16 v[32:35], v[154:157], v[224:227], v[32:35]
	v_mfma_f32_16x16x32_bf16 v[28:31], v[162:165], v[224:227], v[28:31]
	v_mfma_f32_16x16x32_bf16 v[16:19], v[154:157], v[232:235], v[16:19]
	v_mfma_f32_16x16x32_bf16 v[12:15], v[162:165], v[232:235], v[12:15]
	s_setprio 0
	s_setprio 1
	v_mfma_f32_16x16x32_bf16 v[56:59], v[166:169], v[194:197], v[56:59]
	v_mfma_f32_16x16x32_bf16 v[52:55], v[174:177], v[194:197], v[52:55]
	v_mfma_f32_16x16x32_bf16 v[40:43], v[166:169], v[202:205], v[40:43]
	v_mfma_f32_16x16x32_bf16 v[36:39], v[174:177], v[202:205], v[36:39]
	v_mfma_f32_16x16x32_bf16 v[24:27], v[166:169], v[220:223], v[24:27]
	v_mfma_f32_16x16x32_bf16 v[20:23], v[174:177], v[220:223], v[20:23]
	v_mfma_f32_16x16x32_bf16 v[8:11], v[166:169], v[228:231], v[8:11]
	v_mfma_f32_16x16x32_bf16 v[4:7], v[174:177], v[228:231], v[4:7]
	v_mfma_f32_16x16x32_bf16 v[56:59], v[170:173], v[198:201], v[56:59]
	v_mfma_f32_16x16x32_bf16 v[52:55], v[178:181], v[198:201], v[52:55]
	v_mfma_f32_16x16x32_bf16 v[40:43], v[170:173], v[206:209], v[40:43]
	v_mfma_f32_16x16x32_bf16 v[36:39], v[178:181], v[206:209], v[36:39]
	v_mfma_f32_16x16x32_bf16 v[24:27], v[170:173], v[224:227], v[24:27]
	v_mfma_f32_16x16x32_bf16 v[20:23], v[178:181], v[224:227], v[20:23]
	v_mfma_f32_16x16x32_bf16 v[8:11], v[170:173], v[232:235], v[8:11]
	v_mfma_f32_16x16x32_bf16 v[4:7], v[178:181], v[232:235], v[4:7]
	s_setprio 0
	s_barrier
	s_add_i32 s26, s82, 0x100
	v_add_u32_e32 v2, s26, v149
	s_add_i32 s28, s78, 0x100
	ds_read_b128 v[142:145], v2
	ds_read_b128 v[154:157], v2 offset:1024
	ds_read_b128 v[158:161], v2 offset:2048
	ds_read_b128 v[162:165], v2 offset:3072
	v_add_u32_e32 v2, s28, v149
	ds_read_b128 v[166:169], v2
	ds_read_b128 v[170:173], v2 offset:1024
	ds_read_b128 v[174:177], v2 offset:2048
	ds_read_b128 v[178:181], v2 offset:3072
	s_add_u32 s50, s50, s36
	s_addc_u32 s51, s51, s37
	s_mov_b32 m0, s89
	v_lshl_add_u64 v[244:245], s[50:51], 0, v[250:251]
	ds_read_b128 v[194:197], v152 offset:32768
	ds_read_b128 v[198:201], v152 offset:33792
	ds_read_b128 v[202:205], v152 offset:34816
	ds_read_b128 v[206:209], v152 offset:35840
	ds_read_b128 v[220:223], v152 offset:36864
	ds_read_b128 v[224:227], v152 offset:37888
	ds_read_b128 v[228:231], v152 offset:38912
	ds_read_b128 v[232:235], v152 offset:39936
	global_load_lds_dwordx4 v[244:245], off
	v_lshl_add_u64 v[244:245], s[50:51], 0, v[252:253]
	s_mov_b32 m0, s90
	s_nop 0
	global_load_lds_dwordx4 v[244:245], off
	s_waitcnt vmcnt(8)
	s_waitcnt lgkmcnt(0)
	s_barrier
	s_setprio 1
	s_waitcnt lgkmcnt(0)
	v_mfma_f32_16x16x32_bf16 v[128:131], v[142:145], v[194:197], v[128:131]
	v_mfma_f32_16x16x32_bf16 v[124:127], v[158:161], v[194:197], v[124:127]
	v_mfma_f32_16x16x32_bf16 v[112:115], v[142:145], v[202:205], v[112:115]
	v_mfma_f32_16x16x32_bf16 v[108:111], v[158:161], v[202:205], v[108:111]
	v_mfma_f32_16x16x32_bf16 v[96:99], v[142:145], v[220:223], v[96:99]
	v_mfma_f32_16x16x32_bf16 v[92:95], v[158:161], v[220:223], v[92:95]
	v_mfma_f32_16x16x32_bf16 v[80:83], v[142:145], v[228:231], v[80:83]
	v_mfma_f32_16x16x32_bf16 v[76:79], v[158:161], v[228:231], v[76:79]
	v_mfma_f32_16x16x32_bf16 v[128:131], v[154:157], v[198:201], v[128:131]
	v_mfma_f32_16x16x32_bf16 v[124:127], v[162:165], v[198:201], v[124:127]
	v_mfma_f32_16x16x32_bf16 v[112:115], v[154:157], v[206:209], v[112:115]
	v_mfma_f32_16x16x32_bf16 v[108:111], v[162:165], v[206:209], v[108:111]
	v_mfma_f32_16x16x32_bf16 v[96:99], v[154:157], v[224:227], v[96:99]
	v_mfma_f32_16x16x32_bf16 v[92:95], v[162:165], v[224:227], v[92:95]
	v_mfma_f32_16x16x32_bf16 v[80:83], v[154:157], v[232:235], v[80:83]
	v_mfma_f32_16x16x32_bf16 v[76:79], v[162:165], v[232:235], v[76:79]
	s_setprio 0
	s_setprio 1
	v_mfma_f32_16x16x32_bf16 v[120:123], v[166:169], v[194:197], v[120:123]
	v_mfma_f32_16x16x32_bf16 v[116:119], v[174:177], v[194:197], v[116:119]
	v_mfma_f32_16x16x32_bf16 v[104:107], v[166:169], v[202:205], v[104:107]
	v_mfma_f32_16x16x32_bf16 v[100:103], v[174:177], v[202:205], v[100:103]
	v_mfma_f32_16x16x32_bf16 v[88:91], v[166:169], v[220:223], v[88:91]
	v_mfma_f32_16x16x32_bf16 v[84:87], v[174:177], v[220:223], v[84:87]
	v_mfma_f32_16x16x32_bf16 v[72:75], v[166:169], v[228:231], v[72:75]
	v_mfma_f32_16x16x32_bf16 v[68:71], v[174:177], v[228:231], v[68:71]
	v_mfma_f32_16x16x32_bf16 v[120:123], v[170:173], v[198:201], v[120:123]
	v_mfma_f32_16x16x32_bf16 v[116:119], v[178:181], v[198:201], v[116:119]
	v_mfma_f32_16x16x32_bf16 v[104:107], v[170:173], v[206:209], v[104:107]
	v_mfma_f32_16x16x32_bf16 v[100:103], v[178:181], v[206:209], v[100:103]
	v_mfma_f32_16x16x32_bf16 v[88:91], v[170:173], v[224:227], v[88:91]
	v_mfma_f32_16x16x32_bf16 v[84:87], v[178:181], v[224:227], v[84:87]
	v_mfma_f32_16x16x32_bf16 v[72:75], v[170:173], v[232:235], v[72:75]
	v_mfma_f32_16x16x32_bf16 v[68:71], v[178:181], v[232:235], v[68:71]
	s_setprio 0
	s_barrier
; #define PG8_STAGE(bufoff, gbase, voff) do { _Pragma("unroll") for (int _i = 0; _i < 2; ++_i) \
;         __builtin_amdgcn_global_load_lds((const unsigned*)((const char*)(gbase) + (voff)[_i]), (PG8_LAS unsigned*)(lds + (bufoff) + ldsw + _i * 8192), 16, 0, 0); } while (0)
; #define PG8_LDA(dst, b, h) do { _Pragma("unroll") for (int m = 0; m < 4; ++m) _Pragma("unroll") for (int k = 0; k < 2; ++k) dst[m][k] = *(const PG8_LAS bf16x8*)(lds + PG8_SA(b, h) + aoff + m * 2048 + k * 1024); } while (0)
; #define PG8_MMA(ai, bj, At, Bt) do { __builtin_amdgcn_s_setprio(1); _Pragma("unroll") for (int m = 0; m < 4; ++m) _Pragma("unroll") for (int n = 0; n < 2; ++n) _Pragma("unroll") for (int k = 0; k < 2; ++k) \
;         acc[ai][bj][m][n] = __builtin_amdgcn_mfma_f32_16x16x32_bf16(Bt[n][k], At[m][k], acc[ai][bj][m][n], 0, 0, 0); __builtin_amdgcn_s_setprio(0); } while (0)
; #define PG8_WAIT_V(n) asm volatile("s_waitcnt vmcnt(" #n ")" ::: "memory")
; #define PG8_WAIT_L(n) asm volatile("s_waitcnt lgkmcnt(" #n ")" ::: "memory")
; #define PG8_BAR __builtin_amdgcn_s_barrier()
; #define PG8_SCHED __builtin_amdgcn_sched_barrier(0)
; template <class Epi, class Sched, bool ALIGN_EPI = false, bool SP2 = false>
; __device__ __forceinline__ void gemm_phase(PG8_LAS unsigned char* lds, const Gemm g, const Sched& S, const Epi& E) {
;     ...
;             PG8_LDA(At, 1, 1); PG8_STAGE(PG8_SB(1, 0), b3, voffB); PG8_STAGE(PG8_SB(1, 1), b3 + hstep, voffB); PG8_STAGE(PG8_SA(1, 0), a3, voffA);
;             PG8_WAIT_V(8); PG8_WAIT_L(0); PG8_BAR; PG8_MMA(1, 0, At, B0); PG8_MMA(1, 1, At, B1); PG8_BAR; PG8_SCHED;
	s_add_i32 s26, s26, s25
	v_lshl_add_u64 v[146:147], v[146:147], 0, s[8:9]
	s_mov_b32 m0, s26
	ds_read_b128 v[194:197], v152 offset:49152
	ds_read_b128 v[198:201], v152 offset:50176
	ds_read_b128 v[202:205], v152 offset:51200
	ds_read_b128 v[206:209], v152 offset:52224
	ds_read_b128 v[220:223], v152 offset:53248
	ds_read_b128 v[224:227], v152 offset:54272
	ds_read_b128 v[228:231], v152 offset:55296
	ds_read_b128 v[232:235], v152 offset:56320
	global_load_lds_dwordx4 v[146:147], off
	v_lshl_add_u64 v[146:147], v[150:151], 0, s[8:9]
	s_add_i32 m0, s26, 0x2000
	s_add_i32 s26, s28, s25
	global_load_lds_dwordx4 v[146:147], off
	v_lshl_add_u64 v[146:147], v[182:183], 0, s[8:9]
	s_mov_b32 m0, s26
	s_nop 0
	global_load_lds_dwordx4 v[146:147], off
	v_lshl_add_u64 v[146:147], v[210:211], 0, s[8:9]
	s_add_i32 m0, s26, 0x2000
	s_nop 0
	global_load_lds_dwordx4 v[146:147], off
	v_lshl_add_u64 v[146:147], v[236:237], 0, s[8:9]
	s_mov_b32 m0, s93
	s_nop 0
	global_load_lds_dwordx4 v[146:147], off
	v_lshl_add_u64 v[146:147], v[238:239], 0, s[8:9]
	s_mov_b32 m0, s94
	s_nop 0
	global_load_lds_dwordx4 v[146:147], off
	s_waitcnt vmcnt(8)
	s_waitcnt lgkmcnt(0)
	s_barrier
	s_setprio 1
	s_waitcnt lgkmcnt(0)
	v_mfma_f32_16x16x32_bf16 v[64:67], v[142:145], v[194:197], v[64:67]
	v_mfma_f32_16x16x32_bf16 v[60:63], v[158:161], v[194:197], v[60:63]
	v_mfma_f32_16x16x32_bf16 v[48:51], v[142:145], v[202:205], v[48:51]
	v_mfma_f32_16x16x32_bf16 v[44:47], v[158:161], v[202:205], v[44:47]
	v_mfma_f32_16x16x32_bf16 v[32:35], v[142:145], v[220:223], v[32:35]
	v_mfma_f32_16x16x32_bf16 v[28:31], v[158:161], v[220:223], v[28:31]
	v_mfma_f32_16x16x32_bf16 v[16:19], v[142:145], v[228:231], v[16:19]
	v_mfma_f32_16x16x32_bf16 v[12:15], v[158:161], v[228:231], v[12:15]
	v_mfma_f32_16x16x32_bf16 v[64:67], v[154:157], v[198:201], v[64:67]
	v_mfma_f32_16x16x32_bf16 v[60:63], v[162:165], v[198:201], v[60:63]
	v_mfma_f32_16x16x32_bf16 v[48:51], v[154:157], v[206:209], v[48:51]
	v_mfma_f32_16x16x32_bf16 v[44:47], v[162:165], v[206:209], v[44:47]
	v_mfma_f32_16x16x32_bf16 v[32:35], v[154:157], v[224:227], v[32:35]
	v_mfma_f32_16x16x32_bf16 v[28:31], v[162:165], v[224:227], v[28:31]
	v_mfma_f32_16x16x32_bf16 v[16:19], v[154:157], v[232:235], v[16:19]
	v_mfma_f32_16x16x32_bf16 v[12:15], v[162:165], v[232:235], v[12:15]
	s_setprio 0
	s_setprio 1
	v_mfma_f32_16x16x32_bf16 v[56:59], v[166:169], v[194:197], v[56:59]
	v_mfma_f32_16x16x32_bf16 v[52:55], v[174:177], v[194:197], v[52:55]
	v_mfma_f32_16x16x32_bf16 v[40:43], v[166:169], v[202:205], v[40:43]
	v_mfma_f32_16x16x32_bf16 v[36:39], v[174:177], v[202:205], v[36:39]
	v_mfma_f32_16x16x32_bf16 v[24:27], v[166:169], v[220:223], v[24:27]
	v_mfma_f32_16x16x32_bf16 v[20:23], v[174:177], v[220:223], v[20:23]
	v_mfma_f32_16x16x32_bf16 v[8:11], v[166:169], v[228:231], v[8:11]
	v_mfma_f32_16x16x32_bf16 v[4:7], v[174:177], v[228:231], v[4:7]
	v_mfma_f32_16x16x32_bf16 v[56:59], v[170:173], v[198:201], v[56:59]
	v_mfma_f32_16x16x32_bf16 v[52:55], v[178:181], v[198:201], v[52:55]
	v_mfma_f32_16x16x32_bf16 v[40:43], v[170:173], v[206:209], v[40:43]
	v_mfma_f32_16x16x32_bf16 v[36:39], v[178:181], v[206:209], v[36:39]
	v_mfma_f32_16x16x32_bf16 v[24:27], v[170:173], v[224:227], v[24:27]
	v_mfma_f32_16x16x32_bf16 v[20:23], v[178:181], v[224:227], v[20:23]
	v_mfma_f32_16x16x32_bf16 v[8:11], v[170:173], v[232:235], v[8:11]
	v_mfma_f32_16x16x32_bf16 v[4:7], v[178:181], v[232:235], v[4:7]
	s_setprio 0
	s_barrier
	s_add_u32 s4, s4, 0x100
	s_addc_u32 s20, s20, 0
	s_add_u32 s38, s38, 0x100
	s_addc_u32 s39, s39, 0
	s_cmp_ge_i32 s27, s6
	s_mov_b32 s26, s27
	s_cbranch_scc0 .LBB0_489

; #define PG8_STAGE(bufoff, gbase, voff) do { _Pragma("unroll") for (int _i = 0; _i < 2; ++_i) \
;         __builtin_amdgcn_global_load_lds((const unsigned*)((const char*)(gbase) + (voff)[_i]), (PG8_LAS unsigned*)(lds + (bufoff) + ldsw + _i * 8192), 16, 0, 0); } while (0)
; #define PG8_LDA(dst, b, h) do { _Pragma("unroll") for (int m = 0; m < 4; ++m) _Pragma("unroll") for (int k = 0; k < 2; ++k) dst[m][k] = *(const PG8_LAS bf16x8*)(lds + PG8_SA(b, h) + aoff + m * 2048 + k * 1024); } while (0)
; #define PG8_LDB(dst, b, h) do { _Pragma("unroll") for (int n = 0; n < 2; ++n) _Pragma("unroll") for (int k = 0; k < 2; ++k) dst[n][k] = *(const PG8_LAS bf16x8*)(lds + PG8_SB(b, h) + boff + n * 2048 + k * 1024); } while (0)
; #define PG8_MMA(ai, bj, At, Bt) do { __builtin_amdgcn_s_setprio(1); _Pragma("unroll") for (int m = 0; m < 4; ++m) _Pragma("unroll") for (int n = 0; n < 2; ++n) _Pragma("unroll") for (int k = 0; k < 2; ++k) \
;         acc[ai][bj][m][n] = __builtin_amdgcn_mfma_f32_16x16x32_bf16(Bt[n][k], At[m][k], acc[ai][bj][m][n], 0, 0, 0); __builtin_amdgcn_s_setprio(0); } while (0)
; #define PG8_WAIT_V(n) asm volatile("s_waitcnt vmcnt(" #n ")" ::: "memory")
; #define PG8_WAIT_L(n) asm volatile("s_waitcnt lgkmcnt(" #n ")" ::: "memory")
; template <class Epi, class Sched, bool ALIGN_EPI = false, bool SP2 = false>
; __device__ __forceinline__ void gemm_phase(PG8_LAS unsigned char* lds, const Gemm g, const Sched& S, const Epi& E) {
;     ...
;             const bool last = (t == nt - 2);
;             const char* a1 = cA + (size_t)(t + 1) * kstep;
;             const char* a2 = last ? nA : cA + (size_t)(t + 2) * kstep; const char* b2 = last ? nB : cB + (size_t)(t + 2) * kstep;
;             const char* a3 = a2 + kstep; const char* b3 = b2 + kstep;
;             if (last && has_next) S.a_ready(nxt);
;             if constexpr (SP2) {
;             PG8_LDB(B0, 0, 0); PG8_LDB(B1, 0, 1); PG8_SCHED; PG8_LDA(At, 0, 0); PG8_STAGE(PG8_SA(1, 1), a1 + hstep, voffA);
;             PG8_WAIT_V(8); PG8_WAIT_L(0); PG8_BAR; PG8_MMA(0, 0, At, B0); PG8_MMA(0, 1, At, B1); PG8_BAR; PG8_SCHED;
;             PG8_LDA(At, 0, 1); PG8_STAGE(PG8_SB(0, 0), b2, voffB); PG8_STAGE(PG8_SB(0, 1), b2 + hstep, voffB); PG8_STAGE(PG8_SA(0, 0), a2, voffA);
;             PG8_WAIT_V(8); PG8_WAIT_L(0); PG8_BAR; PG8_MMA(1, 0, At, B0); PG8_MMA(1, 1, At, B1); PG8_BAR; PG8_SCHED;
.LBB0_530:
	s_add_i32 s58, s27, 2
	s_add_u32 s28, s38, 0x80
	s_addc_u32 s29, s39, 0
	s_add_i32 s59, s33, 0x100
	s_cmp_eq_u32 s80, s27
	s_cselect_b32 s51, s43, s29
	s_cselect_b32 s50, s42, s28
	v_add_u32_e32 v2, s59, v144
	s_cselect_b32 s61, s57, s26
	s_cselect_b32 s60, s56, s20
	s_cselect_b64 s[98:99], s[40:41], 0
	s_cmp_lg_u64 s[98:99], 0
	s_cselect_b32 s98, 0, -1
	v_and_b32_e32 v246, s98, v132
	v_and_b32_e32 v247, s98, v133
	v_and_b32_e32 v248, s98, v136
	v_and_b32_e32 v249, s98, v137
	v_and_b32_e32 v250, s98, v0
	v_and_b32_e32 v251, s98, v1
	v_and_b32_e32 v252, s98, v134
	v_and_b32_e32 v253, s98, v135
	s_add_i32 s27, s21, 0x100
	ds_read_b128 v[146:149], v2
	ds_read_b128 v[150:153], v2 offset:1024
	ds_read_b128 v[154:157], v2 offset:2048
	ds_read_b128 v[158:161], v2 offset:3072
	v_add_u32_e32 v2, s27, v144
	ds_read_b128 v[162:165], v2
	ds_read_b128 v[166:169], v2 offset:1024
	ds_read_b128 v[170:173], v2 offset:2048
	ds_read_b128 v[174:177], v2 offset:3072
	v_lshl_add_u64 v[142:143], s[38:39], 0, v[140:141]
	s_add_i32 m0, s23, 0xc000
	ds_read_b128 v[178:181], v145
	ds_read_b128 v[194:197], v145 offset:1024
	ds_read_b128 v[198:201], v145 offset:2048
	ds_read_b128 v[202:205], v145 offset:3072
	ds_read_b128 v[206:209], v145 offset:4096
	ds_read_b128 v[220:223], v145 offset:5120
	ds_read_b128 v[224:227], v145 offset:6144
	ds_read_b128 v[228:231], v145 offset:7168
	global_load_lds_dwordx4 v[142:143], off
	v_lshl_add_u64 v[142:143], s[38:39], 0, v[138:139]
	s_add_i32 m0, s23, 0xe000
	s_nop 0
	global_load_lds_dwordx4 v[142:143], off
	s_waitcnt vmcnt(8)
	s_waitcnt lgkmcnt(0)
	s_barrier
	s_setprio 1
	s_waitcnt lgkmcnt(0)
	v_mfma_f32_16x16x32_bf16 v[124:127], v[146:149], v[178:181], v[124:127]
	v_mfma_f32_16x16x32_bf16 v[128:131], v[154:157], v[178:181], v[128:131]
	v_mfma_f32_16x16x32_bf16 v[112:115], v[146:149], v[198:201], v[112:115]
	v_mfma_f32_16x16x32_bf16 v[108:111], v[154:157], v[198:201], v[108:111]
	v_mfma_f32_16x16x32_bf16 v[96:99], v[146:149], v[206:209], v[96:99]
	v_mfma_f32_16x16x32_bf16 v[92:95], v[154:157], v[206:209], v[92:95]
	v_mfma_f32_16x16x32_bf16 v[80:83], v[146:149], v[224:227], v[80:83]
	v_mfma_f32_16x16x32_bf16 v[76:79], v[154:157], v[224:227], v[76:79]
	v_mfma_f32_16x16x32_bf16 v[124:127], v[150:153], v[194:197], v[124:127]
	v_mfma_f32_16x16x32_bf16 v[128:131], v[158:161], v[194:197], v[128:131]
	v_mfma_f32_16x16x32_bf16 v[112:115], v[150:153], v[202:205], v[112:115]
	v_mfma_f32_16x16x32_bf16 v[108:111], v[158:161], v[202:205], v[108:111]
	v_mfma_f32_16x16x32_bf16 v[96:99], v[150:153], v[220:223], v[96:99]
	v_mfma_f32_16x16x32_bf16 v[92:95], v[158:161], v[220:223], v[92:95]
	v_mfma_f32_16x16x32_bf16 v[80:83], v[150:153], v[228:231], v[80:83]
	v_mfma_f32_16x16x32_bf16 v[76:79], v[158:161], v[228:231], v[76:79]
	s_setprio 0
	s_setprio 1
	v_mfma_f32_16x16x32_bf16 v[120:123], v[162:165], v[178:181], v[120:123]
	v_mfma_f32_16x16x32_bf16 v[116:119], v[170:173], v[178:181], v[116:119]
	v_mfma_f32_16x16x32_bf16 v[104:107], v[162:165], v[198:201], v[104:107]
	v_mfma_f32_16x16x32_bf16 v[100:103], v[170:173], v[198:201], v[100:103]
	v_mfma_f32_16x16x32_bf16 v[88:91], v[162:165], v[206:209], v[88:91]
	v_mfma_f32_16x16x32_bf16 v[84:87], v[170:173], v[206:209], v[84:87]
	v_mfma_f32_16x16x32_bf16 v[72:75], v[162:165], v[224:227], v[72:75]
	v_mfma_f32_16x16x32_bf16 v[68:71], v[170:173], v[224:227], v[68:71]
	v_mfma_f32_16x16x32_bf16 v[120:123], v[166:169], v[194:197], v[120:123]
	v_mfma_f32_16x16x32_bf16 v[116:119], v[174:177], v[194:197], v[116:119]
	v_mfma_f32_16x16x32_bf16 v[104:107], v[166:169], v[202:205], v[104:107]
	v_mfma_f32_16x16x32_bf16 v[100:103], v[174:177], v[202:205], v[100:103]
	v_mfma_f32_16x16x32_bf16 v[88:91], v[166:169], v[220:223], v[88:91]
	v_mfma_f32_16x16x32_bf16 v[84:87], v[174:177], v[220:223], v[84:87]
	v_mfma_f32_16x16x32_bf16 v[72:75], v[166:169], v[228:231], v[72:75]
	v_mfma_f32_16x16x32_bf16 v[68:71], v[174:177], v[228:231], v[68:71]
	s_setprio 0
	s_barrier
	s_add_i32 s28, s59, s11
	v_lshl_add_u64 v[142:143], s[60:61], 0, v[246:247]
	s_mov_b32 m0, s28
	ds_read_b128 v[178:181], v145 offset:16384
	ds_read_b128 v[194:197], v145 offset:17408
	ds_read_b128 v[198:201], v145 offset:18432
	ds_read_b128 v[202:205], v145 offset:19456
	ds_read_b128 v[206:209], v145 offset:20480
	ds_read_b128 v[220:223], v145 offset:21504
	ds_read_b128 v[224:227], v145 offset:22528
	ds_read_b128 v[228:231], v145 offset:23552
	global_load_lds_dwordx4 v[142:143], off
	s_add_i32 m0, s28, 0x2000
	v_lshl_add_u64 v[182:183], s[60:61], 0, v[248:249]
	s_add_u32 s60, s60, s36
	s_addc_u32 s61, s61, s37
	s_add_i32 s27, s27, s11
	global_load_lds_dwordx4 v[182:183], off
	v_lshl_add_u64 v[210:211], s[60:61], 0, v[246:247]
	s_mov_b32 m0, s27
	v_lshl_add_u64 v[232:233], s[60:61], 0, v[248:249]
	global_load_lds_dwordx4 v[210:211], off
	s_add_i32 m0, s27, 0x2000
	v_lshl_add_u64 v[234:235], s[50:51], 0, v[250:251]
	global_load_lds_dwordx4 v[232:233], off
	s_mov_b32 m0, s23
	v_lshl_add_u64 v[236:237], s[50:51], 0, v[252:253]
	global_load_lds_dwordx4 v[234:235], off
	s_mov_b32 m0, s25
	s_nop 0
	global_load_lds_dwordx4 v[236:237], off
	s_waitcnt vmcnt(8)
	s_waitcnt lgkmcnt(0)
	s_barrier
; #define PG8_STAGE(bufoff, gbase, voff) do { _Pragma("unroll") for (int _i = 0; _i < 2; ++_i) \
;         __builtin_amdgcn_global_load_lds((const unsigned*)((const char*)(gbase) + (voff)[_i]), (PG8_LAS unsigned*)(lds + (bufoff) + ldsw + _i * 8192), 16, 0, 0); } while (0)
; #define PG8_LDA(dst, b, h) do { _Pragma("unroll") for (int m = 0; m < 4; ++m) _Pragma("unroll") for (int k = 0; k < 2; ++k) dst[m][k] = *(const PG8_LAS bf16x8*)(lds + PG8_SA(b, h) + aoff + m * 2048 + k * 1024); } while (0)
; #define PG8_LDB(dst, b, h) do { _Pragma("unroll") for (int n = 0; n < 2; ++n) _Pragma("unroll") for (int k = 0; k < 2; ++k) dst[n][k] = *(const PG8_LAS bf16x8*)(lds + PG8_SB(b, h) + boff + n * 2048 + k * 1024); } while (0)
; #define PG8_MMA(ai, bj, At, Bt) do { __builtin_amdgcn_s_setprio(1); _Pragma("unroll") for (int m = 0; m < 4; ++m) _Pragma("unroll") for (int n = 0; n < 2; ++n) _Pragma("unroll") for (int k = 0; k < 2; ++k) \
;         acc[ai][bj][m][n] = __builtin_amdgcn_mfma_f32_16x16x32_bf16(Bt[n][k], At[m][k], acc[ai][bj][m][n], 0, 0, 0); __builtin_amdgcn_s_setprio(0); } while (0)
; #define PG8_WAIT_V(n) asm volatile("s_waitcnt vmcnt(" #n ")" ::: "memory")
; #define PG8_WAIT_L(n) asm volatile("s_waitcnt lgkmcnt(" #n ")" ::: "memory")
; #define PG8_BAR __builtin_amdgcn_s_barrier()
; #define PG8_SCHED __builtin_amdgcn_sched_barrier(0)
; template <class Epi, class Sched, bool ALIGN_EPI = false, bool SP2 = false>
; __device__ __forceinline__ void gemm_phase(PG8_LAS unsigned char* lds, const Gemm g, const Sched& S, const Epi& E) {
;     ...
;             PG8_WAIT_V(8); PG8_WAIT_L(0); PG8_BAR; PG8_MMA(1, 0, At, B0); PG8_MMA(1, 1, At, B1); PG8_BAR; PG8_SCHED;
;             PG8_LDB(B0, 1, 0); PG8_LDB(B1, 1, 1); PG8_SCHED; PG8_LDA(At, 1, 0); PG8_STAGE(PG8_SA(0, 1), a2 + hstep, voffA);
;             PG8_WAIT_V(8); PG8_WAIT_L(0); PG8_BAR; PG8_MMA(0, 0, At, B0); PG8_MMA(0, 1, At, B1); PG8_BAR; PG8_SCHED;
	s_setprio 1
	s_waitcnt lgkmcnt(0)
	v_mfma_f32_16x16x32_bf16 v[64:67], v[146:149], v[178:181], v[64:67]
	v_mfma_f32_16x16x32_bf16 v[60:63], v[154:157], v[178:181], v[60:63]
	v_mfma_f32_16x16x32_bf16 v[48:51], v[146:149], v[198:201], v[48:51]
	v_mfma_f32_16x16x32_bf16 v[44:47], v[154:157], v[198:201], v[44:47]
	v_mfma_f32_16x16x32_bf16 v[32:35], v[146:149], v[206:209], v[32:35]
	v_mfma_f32_16x16x32_bf16 v[28:31], v[154:157], v[206:209], v[28:31]
	v_mfma_f32_16x16x32_bf16 v[16:19], v[146:149], v[224:227], v[16:19]
	v_mfma_f32_16x16x32_bf16 v[12:15], v[154:157], v[224:227], v[12:15]
	v_mfma_f32_16x16x32_bf16 v[64:67], v[150:153], v[194:197], v[64:67]
	v_mfma_f32_16x16x32_bf16 v[60:63], v[158:161], v[194:197], v[60:63]
	v_mfma_f32_16x16x32_bf16 v[48:51], v[150:153], v[202:205], v[48:51]
	v_mfma_f32_16x16x32_bf16 v[44:47], v[158:161], v[202:205], v[44:47]
	v_mfma_f32_16x16x32_bf16 v[32:35], v[150:153], v[220:223], v[32:35]
	v_mfma_f32_16x16x32_bf16 v[28:31], v[158:161], v[220:223], v[28:31]
	v_mfma_f32_16x16x32_bf16 v[16:19], v[150:153], v[228:231], v[16:19]
	v_mfma_f32_16x16x32_bf16 v[12:15], v[158:161], v[228:231], v[12:15]
	s_setprio 0
	s_setprio 1
	v_mfma_f32_16x16x32_bf16 v[56:59], v[162:165], v[178:181], v[56:59]
	v_mfma_f32_16x16x32_bf16 v[52:55], v[170:173], v[178:181], v[52:55]
	v_mfma_f32_16x16x32_bf16 v[40:43], v[162:165], v[198:201], v[40:43]
	v_mfma_f32_16x16x32_bf16 v[36:39], v[170:173], v[198:201], v[36:39]
	v_mfma_f32_16x16x32_bf16 v[24:27], v[162:165], v[206:209], v[24:27]
	v_mfma_f32_16x16x32_bf16 v[20:23], v[170:173], v[206:209], v[20:23]
	v_mfma_f32_16x16x32_bf16 v[8:11], v[162:165], v[224:227], v[8:11]
	v_mfma_f32_16x16x32_bf16 v[4:7], v[170:173], v[224:227], v[4:7]
	v_mfma_f32_16x16x32_bf16 v[56:59], v[166:169], v[194:197], v[56:59]
	v_mfma_f32_16x16x32_bf16 v[52:55], v[174:177], v[194:197], v[52:55]
	v_mfma_f32_16x16x32_bf16 v[40:43], v[166:169], v[202:205], v[40:43]
	v_mfma_f32_16x16x32_bf16 v[36:39], v[174:177], v[202:205], v[36:39]
	v_mfma_f32_16x16x32_bf16 v[24:27], v[166:169], v[220:223], v[24:27]
	v_mfma_f32_16x16x32_bf16 v[20:23], v[174:177], v[220:223], v[20:23]
	v_mfma_f32_16x16x32_bf16 v[8:11], v[166:169], v[228:231], v[8:11]
	v_mfma_f32_16x16x32_bf16 v[4:7], v[174:177], v[228:231], v[4:7]
	s_setprio 0
	s_barrier
	s_add_i32 s27, s82, 0x100
	v_add_u32_e32 v2, s27, v144
	s_add_i32 s28, s78, 0x100
	ds_read_b128 v[146:149], v2
	ds_read_b128 v[150:153], v2 offset:1024
	ds_read_b128 v[154:157], v2 offset:2048
	ds_read_b128 v[158:161], v2 offset:3072
	v_add_u32_e32 v2, s28, v144
	ds_read_b128 v[162:165], v2
	ds_read_b128 v[166:169], v2 offset:1024
	ds_read_b128 v[170:173], v2 offset:2048
	ds_read_b128 v[174:177], v2 offset:3072
	s_add_u32 s50, s50, s36
	s_addc_u32 s51, s51, s37
	s_mov_b32 m0, s30
	v_lshl_add_u64 v[238:239], s[50:51], 0, v[250:251]
	ds_read_b128 v[178:181], v145 offset:32768
	ds_read_b128 v[194:197], v145 offset:33792
	ds_read_b128 v[198:201], v145 offset:34816
	ds_read_b128 v[202:205], v145 offset:35840
	ds_read_b128 v[206:209], v145 offset:36864
	ds_read_b128 v[220:223], v145 offset:37888
	ds_read_b128 v[224:227], v145 offset:38912
	ds_read_b128 v[228:231], v145 offset:39936
	global_load_lds_dwordx4 v[238:239], off
	v_lshl_add_u64 v[238:239], s[50:51], 0, v[252:253]
	s_mov_b32 m0, s64
	s_nop 0
	global_load_lds_dwordx4 v[238:239], off
	s_waitcnt vmcnt(8)
	s_waitcnt lgkmcnt(0)
	s_barrier
	s_setprio 1
	s_waitcnt lgkmcnt(0)
	v_mfma_f32_16x16x32_bf16 v[124:127], v[146:149], v[178:181], v[124:127]
	v_mfma_f32_16x16x32_bf16 v[128:131], v[154:157], v[178:181], v[128:131]
	v_mfma_f32_16x16x32_bf16 v[112:115], v[146:149], v[198:201], v[112:115]
	v_mfma_f32_16x16x32_bf16 v[108:111], v[154:157], v[198:201], v[108:111]
	v_mfma_f32_16x16x32_bf16 v[96:99], v[146:149], v[206:209], v[96:99]
	v_mfma_f32_16x16x32_bf16 v[92:95], v[154:157], v[206:209], v[92:95]
	v_mfma_f32_16x16x32_bf16 v[80:83], v[146:149], v[224:227], v[80:83]
	v_mfma_f32_16x16x32_bf16 v[76:79], v[154:157], v[224:227], v[76:79]
	v_mfma_f32_16x16x32_bf16 v[124:127], v[150:153], v[194:197], v[124:127]
	v_mfma_f32_16x16x32_bf16 v[128:131], v[158:161], v[194:197], v[128:131]
	v_mfma_f32_16x16x32_bf16 v[112:115], v[150:153], v[202:205], v[112:115]
	v_mfma_f32_16x16x32_bf16 v[108:111], v[158:161], v[202:205], v[108:111]
	v_mfma_f32_16x16x32_bf16 v[96:99], v[150:153], v[220:223], v[96:99]
	v_mfma_f32_16x16x32_bf16 v[92:95], v[158:161], v[220:223], v[92:95]
	v_mfma_f32_16x16x32_bf16 v[80:83], v[150:153], v[228:231], v[80:83]
	v_mfma_f32_16x16x32_bf16 v[76:79], v[158:161], v[228:231], v[76:79]
	s_setprio 0
	s_setprio 1
	v_mfma_f32_16x16x32_bf16 v[120:123], v[162:165], v[178:181], v[120:123]
	v_mfma_f32_16x16x32_bf16 v[116:119], v[170:173], v[178:181], v[116:119]
	v_mfma_f32_16x16x32_bf16 v[104:107], v[162:165], v[198:201], v[104:107]
	v_mfma_f32_16x16x32_bf16 v[100:103], v[170:173], v[198:201], v[100:103]
	v_mfma_f32_16x16x32_bf16 v[88:91], v[162:165], v[206:209], v[88:91]
	v_mfma_f32_16x16x32_bf16 v[84:87], v[170:173], v[206:209], v[84:87]
	v_mfma_f32_16x16x32_bf16 v[72:75], v[162:165], v[224:227], v[72:75]
	v_mfma_f32_16x16x32_bf16 v[68:71], v[170:173], v[224:227], v[68:71]
	v_mfma_f32_16x16x32_bf16 v[120:123], v[166:169], v[194:197], v[120:123]
	v_mfma_f32_16x16x32_bf16 v[116:119], v[174:177], v[194:197], v[116:119]
	v_mfma_f32_16x16x32_bf16 v[104:107], v[166:169], v[202:205], v[104:107]
	v_mfma_f32_16x16x32_bf16 v[100:103], v[174:177], v[202:205], v[100:103]
	v_mfma_f32_16x16x32_bf16 v[88:91], v[166:169], v[220:223], v[88:91]
	v_mfma_f32_16x16x32_bf16 v[84:87], v[174:177], v[220:223], v[84:87]
	v_mfma_f32_16x16x32_bf16 v[72:75], v[166:169], v[228:231], v[72:75]
	v_mfma_f32_16x16x32_bf16 v[68:71], v[174:177], v[228:231], v[68:71]
	s_setprio 0
	s_barrier
; #define PG8_STAGE(bufoff, gbase, voff) do { _Pragma("unroll") for (int _i = 0; _i < 2; ++_i) \
;         __builtin_amdgcn_global_load_lds((const unsigned*)((const char*)(gbase) + (voff)[_i]), (PG8_LAS unsigned*)(lds + (bufoff) + ldsw + _i * 8192), 16, 0, 0); } while (0)
; #define PG8_LDA(dst, b, h) do { _Pragma("unroll") for (int m = 0; m < 4; ++m) _Pragma("unroll") for (int k = 0; k < 2; ++k) dst[m][k] = *(const PG8_LAS bf16x8*)(lds + PG8_SA(b, h) + aoff + m * 2048 + k * 1024); } while (0)
; #define PG8_MMA(ai, bj, At, Bt) do { __builtin_amdgcn_s_setprio(1); _Pragma("unroll") for (int m = 0; m < 4; ++m) _Pragma("unroll") for (int n = 0; n < 2; ++n) _Pragma("unroll") for (int k = 0; k < 2; ++k) \
;         acc[ai][bj][m][n] = __builtin_amdgcn_mfma_f32_16x16x32_bf16(Bt[n][k], At[m][k], acc[ai][bj][m][n], 0, 0, 0); __builtin_amdgcn_s_setprio(0); } while (0)
; #define PG8_WAIT_V(n) asm volatile("s_waitcnt vmcnt(" #n ")" ::: "memory")
; #define PG8_WAIT_L(n) asm volatile("s_waitcnt lgkmcnt(" #n ")" ::: "memory")
; #define PG8_BAR __builtin_amdgcn_s_barrier()
; #define PG8_SCHED __builtin_amdgcn_sched_barrier(0)
; template <class Epi, class Sched, bool ALIGN_EPI = false, bool SP2 = false>
; __device__ __forceinline__ void gemm_phase(PG8_LAS unsigned char* lds, const Gemm g, const Sched& S, const Epi& E) {
;     ...
;             PG8_LDA(At, 1, 1); PG8_STAGE(PG8_SB(1, 0), b3, voffB); PG8_STAGE(PG8_SB(1, 1), b3 + hstep, voffB); PG8_STAGE(PG8_SA(1, 0), a3, voffA);
;             PG8_WAIT_V(8); PG8_WAIT_L(0); PG8_BAR; PG8_MMA(1, 0, At, B0); PG8_MMA(1, 1, At, B1); PG8_BAR; PG8_SCHED;
	s_add_i32 s27, s27, s11
	v_lshl_add_u64 v[142:143], v[142:143], 0, s[8:9]
	s_mov_b32 m0, s27
	ds_read_b128 v[178:181], v145 offset:49152
	ds_read_b128 v[194:197], v145 offset:50176
	ds_read_b128 v[198:201], v145 offset:51200
	ds_read_b128 v[202:205], v145 offset:52224
	ds_read_b128 v[206:209], v145 offset:53248
	ds_read_b128 v[220:223], v145 offset:54272
	ds_read_b128 v[224:227], v145 offset:55296
	ds_read_b128 v[228:231], v145 offset:56320
	global_load_lds_dwordx4 v[142:143], off
	v_lshl_add_u64 v[142:143], v[182:183], 0, s[8:9]
	s_add_i32 m0, s27, 0x2000
	s_add_i32 s27, s28, s11
	global_load_lds_dwordx4 v[142:143], off
	v_lshl_add_u64 v[142:143], v[210:211], 0, s[8:9]
	s_mov_b32 m0, s27
	s_nop 0
	global_load_lds_dwordx4 v[142:143], off
	v_lshl_add_u64 v[142:143], v[232:233], 0, s[8:9]
	s_add_i32 m0, s27, 0x2000
	s_nop 0
	global_load_lds_dwordx4 v[142:143], off
	v_lshl_add_u64 v[142:143], v[234:235], 0, s[8:9]
	s_mov_b32 m0, s65
	s_nop 0
	global_load_lds_dwordx4 v[142:143], off
	v_lshl_add_u64 v[142:143], v[236:237], 0, s[8:9]
	s_mov_b32 m0, s66
	s_nop 0
	global_load_lds_dwordx4 v[142:143], off
	s_waitcnt vmcnt(8)
	s_waitcnt lgkmcnt(0)
	s_barrier
	s_setprio 1
	s_waitcnt lgkmcnt(0)
	v_mfma_f32_16x16x32_bf16 v[64:67], v[146:149], v[178:181], v[64:67]
	v_mfma_f32_16x16x32_bf16 v[60:63], v[154:157], v[178:181], v[60:63]
	v_mfma_f32_16x16x32_bf16 v[48:51], v[146:149], v[198:201], v[48:51]
	v_mfma_f32_16x16x32_bf16 v[44:47], v[154:157], v[198:201], v[44:47]
	v_mfma_f32_16x16x32_bf16 v[32:35], v[146:149], v[206:209], v[32:35]
	v_mfma_f32_16x16x32_bf16 v[28:31], v[154:157], v[206:209], v[28:31]
	v_mfma_f32_16x16x32_bf16 v[16:19], v[146:149], v[224:227], v[16:19]
	v_mfma_f32_16x16x32_bf16 v[12:15], v[154:157], v[224:227], v[12:15]
	v_mfma_f32_16x16x32_bf16 v[64:67], v[150:153], v[194:197], v[64:67]
	v_mfma_f32_16x16x32_bf16 v[60:63], v[158:161], v[194:197], v[60:63]
	v_mfma_f32_16x16x32_bf16 v[48:51], v[150:153], v[202:205], v[48:51]
	v_mfma_f32_16x16x32_bf16 v[44:47], v[158:161], v[202:205], v[44:47]
	v_mfma_f32_16x16x32_bf16 v[32:35], v[150:153], v[220:223], v[32:35]
	v_mfma_f32_16x16x32_bf16 v[28:31], v[158:161], v[220:223], v[28:31]
	v_mfma_f32_16x16x32_bf16 v[16:19], v[150:153], v[228:231], v[16:19]
	v_mfma_f32_16x16x32_bf16 v[12:15], v[158:161], v[228:231], v[12:15]
	s_setprio 0
	s_setprio 1
	v_mfma_f32_16x16x32_bf16 v[56:59], v[162:165], v[178:181], v[56:59]
	v_mfma_f32_16x16x32_bf16 v[52:55], v[170:173], v[178:181], v[52:55]
	v_mfma_f32_16x16x32_bf16 v[40:43], v[162:165], v[198:201], v[40:43]
	v_mfma_f32_16x16x32_bf16 v[36:39], v[170:173], v[198:201], v[36:39]
	v_mfma_f32_16x16x32_bf16 v[24:27], v[162:165], v[206:209], v[24:27]
	v_mfma_f32_16x16x32_bf16 v[20:23], v[170:173], v[206:209], v[20:23]
	v_mfma_f32_16x16x32_bf16 v[8:11], v[162:165], v[224:227], v[8:11]
	v_mfma_f32_16x16x32_bf16 v[4:7], v[170:173], v[224:227], v[4:7]
	v_mfma_f32_16x16x32_bf16 v[56:59], v[166:169], v[194:197], v[56:59]
	v_mfma_f32_16x16x32_bf16 v[52:55], v[174:177], v[194:197], v[52:55]
	v_mfma_f32_16x16x32_bf16 v[40:43], v[166:169], v[202:205], v[40:43]
	v_mfma_f32_16x16x32_bf16 v[36:39], v[174:177], v[202:205], v[36:39]
	v_mfma_f32_16x16x32_bf16 v[24:27], v[166:169], v[220:223], v[24:27]
	v_mfma_f32_16x16x32_bf16 v[20:23], v[174:177], v[220:223], v[20:23]
	v_mfma_f32_16x16x32_bf16 v[8:11], v[166:169], v[228:231], v[8:11]
	v_mfma_f32_16x16x32_bf16 v[4:7], v[174:177], v[228:231], v[4:7]
	s_setprio 0
	s_barrier
	s_add_u32 s20, s20, 0x100
	s_addc_u32 s26, s26, 0
	s_add_u32 s38, s38, 0x100
	s_addc_u32 s39, s39, 0
	s_cmp_ge_i32 s58, s69
	s_mov_b32 s27, s58
	s_cbranch_scc0 .LBB0_530
